# load segments P1/P4: scalar pointer bookkeeping moved behind the first block of ds_reads (on top of the saddr-form balanced loops)
# speedup vs baseline: 1.0009x; 1.0009x over previous
; #define PG8_STAGE(bufoff, gbase, voff) do { _Pragma("unroll") for (int _i = 0; _i < 2; ++_i) \
;         __builtin_amdgcn_global_load_lds((const unsigned*)((const char*)(gbase) + (voff)[_i]), (PG8_LAS unsigned*)(lds + (bufoff) + ldsw + _i * 8192), 16, 0, 0); } while (0)
; #define PG8_LDA(dst, b, h) do { _Pragma("unroll") for (int m = 0; m < 4; ++m) _Pragma("unroll") for (int k = 0; k < 2; ++k) dst[m][k] = *(const PG8_LAS bf16x8*)(lds + PG8_SA(b, h) + aoff + m * 2048 + k * 1024); } while (0)
; #define PG8_LDB(dst, b, h) do { _Pragma("unroll") for (int n = 0; n < 2; ++n) _Pragma("unroll") for (int k = 0; k < 2; ++k) dst[n][k] = *(const PG8_LAS bf16x8*)(lds + PG8_SB(b, h) + boff + n * 2048 + k * 1024); } while (0)
; #define PG8_WAIT_V(n) asm volatile("s_waitcnt vmcnt(" #n ")" ::: "memory")
; #define PG8_WAIT_L(n) asm volatile("s_waitcnt lgkmcnt(" #n ")" ::: "memory")
; #define PG8_BAR __builtin_amdgcn_s_barrier()
; #define PG8_SCHED __builtin_amdgcn_sched_barrier(0)
; template <class Epi, class Sched, bool ALIGN_EPI = false, bool SP2 = false, bool I8 = false>
; __device__ __forceinline__ void gemm_phase(PG8_LAS unsigned char* lds, const Gemm g, const Sched& S, const Epi& E) {
;     ...
;         const bool has_next = S.next(ui + 1, nxt);
;         const char* nA = has_next ? (const char*)g.A + (size_t)nxt.pm * tstep : cA; const char* nB = has_next ? (const char*)g.Bt + (size_t)nxt.pn * tstep : cB;
;         for (int t = 0; t < nt; t += 2) {
;             const bool last = (t == nt - 2);
;             const char* a1 = cA + (size_t)(t + 1) * kstep;
;             const char* a2 = last ? nA : cA + (size_t)(t + 2) * kstep; const char* b2 = last ? nB : cB + (size_t)(t + 2) * kstep;
;             const char* a3 = a2 + kstep; const char* b3 = b2 + kstep;
;             if (last && has_next) S.a_ready(nxt);
;             if constexpr (SP2) {
;             PG8_LDB(B0, 0, 0); PG8_LDB(B1, 0, 1); PG8_SCHED; PG8_LDA(At, 0, 0); PG8_STAGE(PG8_SA(1, 1), a1 + hstep, voffA);
;             PG8_WAIT_V(8); PG8_WAIT_L(0); PG8_BAR; PG8_MMA(0, 0, At, B0); PG8_MMA(0, 1, At, B1); PG8_BAR; PG8_SCHED;
;             PG8_LDA(At, 0, 1); PG8_STAGE(PG8_SB(0, 0), b2, voffB); PG8_STAGE(PG8_SB(0, 1), b2 + hstep, voffB); PG8_STAGE(PG8_SA(0, 0), a2, voffA);
;             PG8_WAIT_V(8); PG8_WAIT_L(0); PG8_BAR; PG8_MMA(1, 0, At, B0); PG8_MMA(1, 1, At, B1); PG8_BAR; PG8_SCHED;
.LBB0_207:
	s_ashr_i32 s19, s18, 31
	s_lshl_b64 s[22:23], s[18:19], 20
	s_add_u32 s22, s28, s22
	s_addc_u32 s23, s34, s23
	s_and_b64 s[24:25], s[6:7], exec
	s_cselect_b32 s19, s23, s27
	s_cselect_b32 s64, s22, s26
	s_ashr_i32 s17, s16, 31
	s_lshl_b64 s[24:25], s[16:17], 20
	s_add_u32 s24, s35, s24
	s_addc_u32 s25, s42, s25
	s_and_b64 s[40:41], s[6:7], exec
	s_cselect_b32 s17, s25, s37
	s_cselect_b32 s65, s24, s36
	s_add_u32 s26, s26, 0x80080
	s_addc_u32 s27, s27, 0
	s_add_u32 s72, s36, 0x100
	s_addc_u32 s73, s37, 0
	s_mov_b32 s76, -2
	s_add_i32 s50, 0, 0x10000
	s_add_i32 s56, 0, 0x14000
	v_add_u32_e32 v136, s50, v175
	v_add_u32_e32 v172, s56, v175
	ds_read_b128 v[116:119], v136
	ds_read_b128 v[124:127], v136 offset:1024
	ds_read_b128 v[132:135], v136 offset:2048
	ds_read_b128 v[136:139], v136 offset:3072
	ds_read_b128 v[160:163], v172
	ds_read_b128 v[164:167], v172 offset:1024
	ds_read_b128 v[168:171], v172 offset:2048
	ds_read_b128 v[178:181], v172 offset:3072
	s_add_u32 s36, s26, 0xfff80080
	s_addc_u32 s37, s27, -1
	s_cmp_eq_u32 s76, 28
	s_cselect_b32 s41, s19, s37
	s_cselect_b32 s40, s64, s36
	s_cselect_b32 s37, s17, s73
	s_cselect_b32 s36, s65, s72
	s_add_i32 m0, s44, 0xc000
	ds_read_b128 v[182:185], v177
	ds_read_b128 v[186:189], v177 offset:1024
	ds_read_b128 v[204:207], v177 offset:2048
	ds_read_b128 v[208:211], v177 offset:3072
	ds_read_b128 v[212:215], v177 offset:4096
	ds_read_b128 v[216:219], v177 offset:5120
	ds_read_b128 v[220:223], v177 offset:6144
	ds_read_b128 v[224:227], v177 offset:7168
	global_load_lds_dwordx4 v156, s[26:27]
	s_add_i32 m0, s44, 0xe000
	s_nop 0
	global_load_lds_dwordx4 v158, s[26:27]
	s_waitcnt vmcnt(8)
	s_waitcnt lgkmcnt(0)
	s_barrier
	s_setprio 1
	s_waitcnt lgkmcnt(0)
	v_mfma_i32_16x16x64_i8 v[144:147], v[116:119], v[182:185], 0
	v_mfma_i32_16x16x64_i8 v[144:147], v[124:127], v[186:189], v[144:147]
	v_mfma_i32_16x16x64_i8 v[112:115], v[124:127], v[208:211], 0
	v_mfma_i32_16x16x64_i8 v[112:115], v[116:119], v[204:207], v[112:115]
	v_mfma_i32_16x16x64_i8 v[96:99], v[116:119], v[212:215], 0
	v_mfma_i32_16x16x64_i8 v[96:99], v[124:127], v[216:219], v[96:99]
	v_mfma_i32_16x16x64_i8 v[80:83], v[124:127], v[224:227], 0
	v_mfma_i32_16x16x64_i8 v[80:83], v[116:119], v[220:223], v[80:83]
	v_mfma_i32_16x16x64_i8 v[76:79], v[132:135], v[220:223], 0
	v_mfma_i32_16x16x64_i8 v[76:79], v[136:139], v[224:227], v[76:79]
	v_mfma_i32_16x16x64_i8 v[92:95], v[136:139], v[216:219], 0
	v_mfma_i32_16x16x64_i8 v[92:95], v[132:135], v[212:215], v[92:95]
	v_mfma_i32_16x16x64_i8 v[108:111], v[132:135], v[204:207], 0
	v_mfma_i32_16x16x64_i8 v[108:111], v[136:139], v[208:211], v[108:111]
	v_mfma_i32_16x16x64_i8 v[140:143], v[136:139], v[186:189], 0
	v_mfma_i32_16x16x64_i8 v[140:143], v[132:135], v[182:185], v[140:143]
	v_mfma_i32_16x16x64_i8 v[128:131], v[160:163], v[182:185], 0
	v_mfma_i32_16x16x64_i8 v[128:131], v[164:167], v[186:189], v[128:131]
	v_mfma_i32_16x16x64_i8 v[104:107], v[164:167], v[208:211], 0
	v_mfma_i32_16x16x64_i8 v[104:107], v[160:163], v[204:207], v[104:107]
	v_mfma_i32_16x16x64_i8 v[88:91], v[160:163], v[212:215], 0
	v_mfma_i32_16x16x64_i8 v[88:91], v[164:167], v[216:219], v[88:91]
	v_mfma_i32_16x16x64_i8 v[72:75], v[164:167], v[224:227], 0
	v_mfma_i32_16x16x64_i8 v[72:75], v[160:163], v[220:223], v[72:75]
	v_mfma_i32_16x16x64_i8 v[68:71], v[168:171], v[220:223], 0
	v_mfma_i32_16x16x64_i8 v[68:71], v[178:181], v[224:227], v[68:71]
	v_mfma_i32_16x16x64_i8 v[84:87], v[178:181], v[216:219], 0
	v_mfma_i32_16x16x64_i8 v[84:87], v[168:171], v[212:215], v[84:87]
	v_mfma_i32_16x16x64_i8 v[100:103], v[168:171], v[204:207], 0
	v_mfma_i32_16x16x64_i8 v[100:103], v[178:181], v[208:211], v[100:103]
	v_mfma_i32_16x16x64_i8 v[120:123], v[178:181], v[186:189], 0
	v_mfma_i32_16x16x64_i8 v[120:123], v[168:171], v[182:185], v[120:123]
	s_setprio 0
	s_barrier
	s_add_i32 s50, s50, s43
	s_mov_b32 m0, s50
	ds_read_b128 v[182:185], v177 offset:16384
	ds_read_b128 v[186:189], v177 offset:17408
	ds_read_b128 v[204:207], v177 offset:18432
	ds_read_b128 v[208:211], v177 offset:19456
	ds_read_b128 v[212:215], v177 offset:20480
	ds_read_b128 v[216:219], v177 offset:21504
	ds_read_b128 v[220:223], v177 offset:22528
	ds_read_b128 v[224:227], v177 offset:23552
	global_load_lds_dwordx4 v2, s[36:37]
	s_add_i32 m0, s50, 0x2000
	s_add_u32 s50, s36, 0x80000
	s_addc_u32 s51, s37, 0
	s_add_i32 s56, s56, s43
	global_load_lds_dwordx4 v148, s[36:37]
	s_mov_b32 m0, s56
	v_lshl_add_u64 v[240:241], s[40:41], 0, v[150:151]
	global_load_lds_dwordx4 v2, s[50:51]
	s_add_i32 m0, s56, 0x2000
	s_nop 0
	global_load_lds_dwordx4 v148, s[50:51]
	v_lshl_add_u64 v[228:229], s[40:41], 0, v[152:153]
	s_waitcnt vmcnt(6)
	s_waitcnt lgkmcnt(0)
	s_barrier
; #define PG8_STAGE(bufoff, gbase, voff) do { _Pragma("unroll") for (int _i = 0; _i < 2; ++_i) \
;         __builtin_amdgcn_global_load_lds((const unsigned*)((const char*)(gbase) + (voff)[_i]), (PG8_LAS unsigned*)(lds + (bufoff) + ldsw + _i * 8192), 16, 0, 0); } while (0)
; #define PG8_LDA(dst, b, h) do { _Pragma("unroll") for (int m = 0; m < 4; ++m) _Pragma("unroll") for (int k = 0; k < 2; ++k) dst[m][k] = *(const PG8_LAS bf16x8*)(lds + PG8_SA(b, h) + aoff + m * 2048 + k * 1024); } while (0)
; #define PG8_LDB(dst, b, h) do { _Pragma("unroll") for (int n = 0; n < 2; ++n) _Pragma("unroll") for (int k = 0; k < 2; ++k) dst[n][k] = *(const PG8_LAS bf16x8*)(lds + PG8_SB(b, h) + boff + n * 2048 + k * 1024); } while (0)
; #define PG8_WAIT_V(n) asm volatile("s_waitcnt vmcnt(" #n ")" ::: "memory")
; #define PG8_WAIT_L(n) asm volatile("s_waitcnt lgkmcnt(" #n ")" ::: "memory")
; #define PG8_BAR __builtin_amdgcn_s_barrier()
; #define PG8_SCHED __builtin_amdgcn_sched_barrier(0)
; template <class Epi, class Sched, bool ALIGN_EPI = false, bool SP2 = false, bool I8 = false>
; __device__ __forceinline__ void gemm_phase(PG8_LAS unsigned char* lds, const Gemm g, const Sched& S, const Epi& E) {
;     ...
;             PG8_WAIT_V(8); PG8_WAIT_L(0); PG8_BAR; PG8_MMA(1, 0, At, B0); PG8_MMA(1, 1, At, B1); PG8_BAR; PG8_SCHED;
;             PG8_LDB(B0, 1, 0); PG8_LDB(B1, 1, 1); PG8_SCHED; PG8_LDA(At, 1, 0); PG8_STAGE(PG8_SA(0, 1), a2 + hstep, voffA);
;             PG8_WAIT_V(8); PG8_WAIT_L(0); PG8_BAR; PG8_MMA(0, 0, At, B0); PG8_MMA(0, 1, At, B1); PG8_BAR; PG8_SCHED;
;             PG8_LDA(At, 1, 1); PG8_STAGE(PG8_SB(1, 0), b3, voffB); PG8_STAGE(PG8_SB(1, 1), b3 + hstep, voffB); PG8_STAGE(PG8_SA(1, 0), a3, voffA);
;             PG8_WAIT_V(8); PG8_WAIT_L(0); PG8_BAR; PG8_MMA(1, 0, At, B0); PG8_MMA(1, 1, At, B1); PG8_BAR; PG8_SCHED;
	s_setprio 1
	s_waitcnt lgkmcnt(0)
	v_mfma_i32_16x16x64_i8 v[64:67], v[116:119], v[182:185], 0
	v_mfma_i32_16x16x64_i8 v[64:67], v[124:127], v[186:189], v[64:67]
	v_mfma_i32_16x16x64_i8 v[48:51], v[124:127], v[208:211], 0
	v_mfma_i32_16x16x64_i8 v[48:51], v[116:119], v[204:207], v[48:51]
	v_mfma_i32_16x16x64_i8 v[32:35], v[116:119], v[212:215], 0
	v_mfma_i32_16x16x64_i8 v[32:35], v[124:127], v[216:219], v[32:35]
	v_mfma_i32_16x16x64_i8 v[16:19], v[124:127], v[224:227], 0
	v_mfma_i32_16x16x64_i8 v[16:19], v[116:119], v[220:223], v[16:19]
	v_mfma_i32_16x16x64_i8 v[12:15], v[132:135], v[220:223], 0
	v_mfma_i32_16x16x64_i8 v[12:15], v[136:139], v[224:227], v[12:15]
	v_mfma_i32_16x16x64_i8 v[28:31], v[136:139], v[216:219], 0
	v_mfma_i32_16x16x64_i8 v[28:31], v[132:135], v[212:215], v[28:31]
	v_mfma_i32_16x16x64_i8 v[44:47], v[132:135], v[204:207], 0
	v_mfma_i32_16x16x64_i8 v[44:47], v[136:139], v[208:211], v[44:47]
	v_mfma_i32_16x16x64_i8 v[60:63], v[136:139], v[186:189], 0
	v_mfma_i32_16x16x64_i8 v[60:63], v[132:135], v[182:185], v[60:63]
	v_mfma_i32_16x16x64_i8 v[56:59], v[160:163], v[182:185], 0
	v_mfma_i32_16x16x64_i8 v[56:59], v[164:167], v[186:189], v[56:59]
	v_mfma_i32_16x16x64_i8 v[40:43], v[164:167], v[208:211], 0
	v_mfma_i32_16x16x64_i8 v[40:43], v[160:163], v[204:207], v[40:43]
	v_mfma_i32_16x16x64_i8 v[24:27], v[160:163], v[212:215], 0
	v_mfma_i32_16x16x64_i8 v[24:27], v[164:167], v[216:219], v[24:27]
	v_mfma_i32_16x16x64_i8 v[8:11], v[164:167], v[224:227], 0
	v_mfma_i32_16x16x64_i8 v[8:11], v[160:163], v[220:223], v[8:11]
	v_mfma_i32_16x16x64_i8 v[4:7], v[168:171], v[220:223], 0
	v_mfma_i32_16x16x64_i8 v[4:7], v[178:181], v[224:227], v[4:7]
	v_mfma_i32_16x16x64_i8 v[20:23], v[178:181], v[216:219], 0
	v_mfma_i32_16x16x64_i8 v[20:23], v[168:171], v[212:215], v[20:23]
	v_mfma_i32_16x16x64_i8 v[36:39], v[168:171], v[204:207], 0
	v_mfma_i32_16x16x64_i8 v[36:39], v[178:181], v[208:211], v[36:39]
	v_mfma_i32_16x16x64_i8 v[52:55], v[178:181], v[186:189], 0
	v_mfma_i32_16x16x64_i8 v[52:55], v[168:171], v[182:185], v[52:55]
	s_setprio 0
	s_barrier
	s_mov_b32 m0, s44
	s_nop 0
	global_load_lds_dwordx4 v[228:229], off
	s_mov_b32 m0, s45
	s_nop 0
	global_load_lds_dwordx4 v[240:241], off
	s_add_i32 s50, 0, 0x18000
	s_add_i32 s51, 0, 0x1c000
	v_add_u32_e32 v136, s50, v175
	v_add_u32_e32 v178, s51, v175
	ds_read_b128 v[116:119], v136
	ds_read_b128 v[124:127], v136 offset:1024
	ds_read_b128 v[132:135], v136 offset:2048
	ds_read_b128 v[136:139], v136 offset:3072
	ds_read_b128 v[160:163], v178
	ds_read_b128 v[164:167], v178 offset:1024
	ds_read_b128 v[168:171], v178 offset:2048
	ds_read_b128 v[178:181], v178 offset:3072
	s_add_u32 s40, s40, 0x80000
	s_addc_u32 s41, s41, 0
	s_mov_b32 m0, s46
	ds_read_b128 v[182:185], v177 offset:32768
	ds_read_b128 v[186:189], v177 offset:33792
	ds_read_b128 v[204:207], v177 offset:34816
	ds_read_b128 v[208:211], v177 offset:35840
	ds_read_b128 v[212:215], v177 offset:36864
	ds_read_b128 v[216:219], v177 offset:37888
	ds_read_b128 v[220:223], v177 offset:38912
	ds_read_b128 v[224:227], v177 offset:39936
	global_load_lds_dwordx4 v152, s[40:41]
	s_mov_b32 m0, s47
	s_nop 0
	global_load_lds_dwordx4 v150, s[40:41]
	s_waitcnt vmcnt(8)
	s_waitcnt lgkmcnt(0)
	s_barrier
	s_setprio 1
	s_waitcnt lgkmcnt(0)
	v_mfma_i32_16x16x64_i8 v[144:147], v[116:119], v[182:185], v[144:147]
	v_mfma_i32_16x16x64_i8 v[144:147], v[124:127], v[186:189], v[144:147]
	v_mfma_i32_16x16x64_i8 v[112:115], v[124:127], v[208:211], v[112:115]
	v_mfma_i32_16x16x64_i8 v[112:115], v[116:119], v[204:207], v[112:115]
	v_mfma_i32_16x16x64_i8 v[96:99], v[116:119], v[212:215], v[96:99]
	v_mfma_i32_16x16x64_i8 v[96:99], v[124:127], v[216:219], v[96:99]
	v_mfma_i32_16x16x64_i8 v[80:83], v[124:127], v[224:227], v[80:83]
	v_mfma_i32_16x16x64_i8 v[80:83], v[116:119], v[220:223], v[80:83]
	v_mfma_i32_16x16x64_i8 v[76:79], v[132:135], v[220:223], v[76:79]
	v_mfma_i32_16x16x64_i8 v[76:79], v[136:139], v[224:227], v[76:79]
	v_mfma_i32_16x16x64_i8 v[92:95], v[136:139], v[216:219], v[92:95]
	v_mfma_i32_16x16x64_i8 v[92:95], v[132:135], v[212:215], v[92:95]
	v_mfma_i32_16x16x64_i8 v[108:111], v[132:135], v[204:207], v[108:111]
	v_mfma_i32_16x16x64_i8 v[108:111], v[136:139], v[208:211], v[108:111]
	v_mfma_i32_16x16x64_i8 v[140:143], v[136:139], v[186:189], v[140:143]
	v_mfma_i32_16x16x64_i8 v[140:143], v[132:135], v[182:185], v[140:143]
	v_mfma_i32_16x16x64_i8 v[128:131], v[160:163], v[182:185], v[128:131]
	v_mfma_i32_16x16x64_i8 v[128:131], v[164:167], v[186:189], v[128:131]
	v_mfma_i32_16x16x64_i8 v[104:107], v[164:167], v[208:211], v[104:107]
	v_mfma_i32_16x16x64_i8 v[104:107], v[160:163], v[204:207], v[104:107]
	v_mfma_i32_16x16x64_i8 v[88:91], v[160:163], v[212:215], v[88:91]
	v_mfma_i32_16x16x64_i8 v[88:91], v[164:167], v[216:219], v[88:91]
	v_mfma_i32_16x16x64_i8 v[72:75], v[164:167], v[224:227], v[72:75]
	v_mfma_i32_16x16x64_i8 v[72:75], v[160:163], v[220:223], v[72:75]
	v_mfma_i32_16x16x64_i8 v[68:71], v[168:171], v[220:223], v[68:71]
	v_mfma_i32_16x16x64_i8 v[68:71], v[178:181], v[224:227], v[68:71]
	v_mfma_i32_16x16x64_i8 v[84:87], v[178:181], v[216:219], v[84:87]
	v_mfma_i32_16x16x64_i8 v[84:87], v[168:171], v[212:215], v[84:87]
	v_mfma_i32_16x16x64_i8 v[100:103], v[168:171], v[204:207], v[100:103]
	v_mfma_i32_16x16x64_i8 v[100:103], v[178:181], v[208:211], v[100:103]
	v_mfma_i32_16x16x64_i8 v[120:123], v[178:181], v[186:189], v[120:123]
	v_mfma_i32_16x16x64_i8 v[120:123], v[168:171], v[182:185], v[120:123]
	s_setprio 0
	s_barrier
	s_add_i32 s40, s50, s43
	s_mov_b32 m0, s40
	ds_read_b128 v[182:185], v177 offset:49152
	ds_read_b128 v[186:189], v177 offset:50176
	ds_read_b128 v[204:207], v177 offset:51200
	ds_read_b128 v[208:211], v177 offset:52224
	ds_read_b128 v[212:215], v177 offset:53248
	ds_read_b128 v[216:219], v177 offset:54272
	ds_read_b128 v[220:223], v177 offset:55296
	ds_read_b128 v[224:227], v177 offset:56320
	s_add_u32 s98, s36, 0x80
	s_addc_u32 s99, s37, 0
	global_load_lds_dwordx4 v2, s[98:99]
	s_add_i32 m0, s40, 0x2000
	s_add_u32 s36, s36, 0x80080
	s_addc_u32 s37, s37, 0
	s_add_i32 s40, s51, s43
	global_load_lds_dwordx4 v148, s[98:99]
	s_mov_b32 m0, s40
	s_nop 0
	global_load_lds_dwordx4 v2, s[36:37]
	s_add_i32 m0, s40, 0x2000
	s_nop 0
	global_load_lds_dwordx4 v148, s[36:37]
	s_cmp_eq_u32 s76, 28
	s_cbranch_scc0 .Ldefer_208_peel
	v_lshl_add_u64 v[172:173], v[228:229], 0, s[84:85]
	s_mov_b32 m0, s52
	s_nop 0
	global_load_lds_dwordx4 v[172:173], off
	v_lshl_add_u64 v[172:173], v[240:241], 0, s[84:85]
	s_mov_b32 m0, s53
	s_nop 0
	global_load_lds_dwordx4 v[172:173], off

; #define PG8_STAGE(bufoff, gbase, voff) do { _Pragma("unroll") for (int _i = 0; _i < 2; ++_i) \
;         __builtin_amdgcn_global_load_lds((const unsigned*)((const char*)(gbase) + (voff)[_i]), (PG8_LAS unsigned*)(lds + (bufoff) + ldsw + _i * 8192), 16, 0, 0); } while (0)
; #define PG8_LDA(dst, b, h) do { _Pragma("unroll") for (int m = 0; m < 4; ++m) _Pragma("unroll") for (int k = 0; k < 2; ++k) dst[m][k] = *(const PG8_LAS bf16x8*)(lds + PG8_SA(b, h) + aoff + m * 2048 + k * 1024); } while (0)
; #define PG8_LDB(dst, b, h) do { _Pragma("unroll") for (int n = 0; n < 2; ++n) _Pragma("unroll") for (int k = 0; k < 2; ++k) dst[n][k] = *(const PG8_LAS bf16x8*)(lds + PG8_SB(b, h) + boff + n * 2048 + k * 1024); } while (0)
; #define PG8_WAIT_V(n) asm volatile("s_waitcnt vmcnt(" #n ")" ::: "memory")
; #define PG8_WAIT_L(n) asm volatile("s_waitcnt lgkmcnt(" #n ")" ::: "memory")
; #define PG8_BAR __builtin_amdgcn_s_barrier()
; #define PG8_SCHED __builtin_amdgcn_sched_barrier(0)
; template <class Epi, class Sched, bool ALIGN_EPI = false, bool SP2 = false, bool I8 = false>
; __device__ __forceinline__ void gemm_phase(PG8_LAS unsigned char* lds, const Gemm g, const Sched& S, const Epi& E) {
;     ...
;             const bool last = (t == nt - 2);
;             const char* a1 = cA + (size_t)(t + 1) * kstep;
;             const char* a2 = last ? nA : cA + (size_t)(t + 2) * kstep; const char* b2 = last ? nB : cB + (size_t)(t + 2) * kstep;
;             const char* a3 = a2 + kstep; const char* b3 = b2 + kstep;
;             if (last && has_next) S.a_ready(nxt);
;             if constexpr (SP2) {
;             PG8_LDB(B0, 0, 0); PG8_LDB(B1, 0, 1); PG8_SCHED; PG8_LDA(At, 0, 0); PG8_STAGE(PG8_SA(1, 1), a1 + hstep, voffA);
;             PG8_WAIT_V(8); PG8_WAIT_L(0); PG8_BAR; PG8_MMA(0, 0, At, B0); PG8_MMA(0, 1, At, B1); PG8_BAR; PG8_SCHED;
;             PG8_LDA(At, 0, 1); PG8_STAGE(PG8_SB(0, 0), b2, voffB); PG8_STAGE(PG8_SB(0, 1), b2 + hstep, voffB); PG8_STAGE(PG8_SA(0, 0), a2, voffA);
;             PG8_WAIT_V(8); PG8_WAIT_L(0); PG8_BAR; PG8_MMA(1, 0, At, B0); PG8_MMA(1, 1, At, B1); PG8_BAR; PG8_SCHED;
.LBB0_208:
	s_add_i32 s50, 0, 0x10000
	s_add_i32 s56, 0, 0x14000
	v_add_u32_e32 v136, s50, v175
	v_add_u32_e32 v172, s56, v175
	ds_read_b128 v[116:119], v136
	ds_read_b128 v[124:127], v136 offset:1024
	ds_read_b128 v[132:135], v136 offset:2048
	ds_read_b128 v[136:139], v136 offset:3072
	ds_read_b128 v[160:163], v172
	ds_read_b128 v[164:167], v172 offset:1024
	ds_read_b128 v[168:171], v172 offset:2048
	ds_read_b128 v[178:181], v172 offset:3072
	s_add_u32 s36, s26, 0xfff80080
	s_addc_u32 s37, s27, -1
	s_cmp_eq_u32 s76, 28
	s_cselect_b32 s41, s19, s37
	s_cselect_b32 s40, s64, s36
	s_cselect_b32 s37, s17, s73
	s_cselect_b32 s36, s65, s72
	v_lshl_add_u64 v[172:173], v[228:229], 0, s[84:85]
	s_mov_b32 m0, s52
	s_nop 0
	global_load_lds_dwordx4 v[172:173], off
	v_lshl_add_u64 v[172:173], v[240:241], 0, s[84:85]
	s_mov_b32 m0, s53
	s_nop 0
	global_load_lds_dwordx4 v[172:173], off
	s_add_i32 m0, s44, 0xc000
	ds_read_b128 v[182:185], v177
	ds_read_b128 v[186:189], v177 offset:1024
	ds_read_b128 v[204:207], v177 offset:2048
	ds_read_b128 v[208:211], v177 offset:3072
	ds_read_b128 v[212:215], v177 offset:4096
	ds_read_b128 v[216:219], v177 offset:5120
	ds_read_b128 v[220:223], v177 offset:6144
	ds_read_b128 v[224:227], v177 offset:7168
	global_load_lds_dwordx4 v156, s[26:27]
	s_add_i32 m0, s44, 0xe000
	s_nop 0
	global_load_lds_dwordx4 v158, s[26:27]
	s_waitcnt vmcnt(8)
	s_waitcnt lgkmcnt(0)
	s_barrier
	s_setprio 1
	s_waitcnt lgkmcnt(0)
	v_mfma_i32_16x16x64_i8 v[144:147], v[116:119], v[182:185], v[144:147]
	v_mfma_i32_16x16x64_i8 v[144:147], v[124:127], v[186:189], v[144:147]
	v_mfma_i32_16x16x64_i8 v[112:115], v[124:127], v[208:211], v[112:115]
	v_mfma_i32_16x16x64_i8 v[112:115], v[116:119], v[204:207], v[112:115]
	v_mfma_i32_16x16x64_i8 v[96:99], v[116:119], v[212:215], v[96:99]
	v_mfma_i32_16x16x64_i8 v[96:99], v[124:127], v[216:219], v[96:99]
	v_mfma_i32_16x16x64_i8 v[80:83], v[124:127], v[224:227], v[80:83]
	v_mfma_i32_16x16x64_i8 v[80:83], v[116:119], v[220:223], v[80:83]
	v_mfma_i32_16x16x64_i8 v[76:79], v[132:135], v[220:223], v[76:79]
	v_mfma_i32_16x16x64_i8 v[76:79], v[136:139], v[224:227], v[76:79]
	v_mfma_i32_16x16x64_i8 v[92:95], v[136:139], v[216:219], v[92:95]
	v_mfma_i32_16x16x64_i8 v[92:95], v[132:135], v[212:215], v[92:95]
	v_mfma_i32_16x16x64_i8 v[108:111], v[132:135], v[204:207], v[108:111]
	v_mfma_i32_16x16x64_i8 v[108:111], v[136:139], v[208:211], v[108:111]
	v_mfma_i32_16x16x64_i8 v[140:143], v[136:139], v[186:189], v[140:143]
	v_mfma_i32_16x16x64_i8 v[140:143], v[132:135], v[182:185], v[140:143]
	v_mfma_i32_16x16x64_i8 v[128:131], v[160:163], v[182:185], v[128:131]
	v_mfma_i32_16x16x64_i8 v[128:131], v[164:167], v[186:189], v[128:131]
	v_mfma_i32_16x16x64_i8 v[104:107], v[164:167], v[208:211], v[104:107]
	v_mfma_i32_16x16x64_i8 v[104:107], v[160:163], v[204:207], v[104:107]
	v_mfma_i32_16x16x64_i8 v[88:91], v[160:163], v[212:215], v[88:91]
	v_mfma_i32_16x16x64_i8 v[88:91], v[164:167], v[216:219], v[88:91]
	v_mfma_i32_16x16x64_i8 v[72:75], v[164:167], v[224:227], v[72:75]
	v_mfma_i32_16x16x64_i8 v[72:75], v[160:163], v[220:223], v[72:75]
	v_mfma_i32_16x16x64_i8 v[68:71], v[168:171], v[220:223], v[68:71]
	v_mfma_i32_16x16x64_i8 v[68:71], v[178:181], v[224:227], v[68:71]
	v_mfma_i32_16x16x64_i8 v[84:87], v[178:181], v[216:219], v[84:87]
	v_mfma_i32_16x16x64_i8 v[84:87], v[168:171], v[212:215], v[84:87]
	v_mfma_i32_16x16x64_i8 v[100:103], v[168:171], v[204:207], v[100:103]
	v_mfma_i32_16x16x64_i8 v[100:103], v[178:181], v[208:211], v[100:103]
	v_mfma_i32_16x16x64_i8 v[120:123], v[178:181], v[186:189], v[120:123]
	v_mfma_i32_16x16x64_i8 v[120:123], v[168:171], v[182:185], v[120:123]
	s_setprio 0
	s_barrier
	s_add_i32 s50, s50, s43
	s_mov_b32 m0, s50
	ds_read_b128 v[182:185], v177 offset:16384
	ds_read_b128 v[186:189], v177 offset:17408
	ds_read_b128 v[204:207], v177 offset:18432
	ds_read_b128 v[208:211], v177 offset:19456
	ds_read_b128 v[212:215], v177 offset:20480
	ds_read_b128 v[216:219], v177 offset:21504
	ds_read_b128 v[220:223], v177 offset:22528
	ds_read_b128 v[224:227], v177 offset:23552
	global_load_lds_dwordx4 v2, s[36:37]
	s_add_i32 m0, s50, 0x2000
	s_add_u32 s50, s36, 0x80000
	s_addc_u32 s51, s37, 0
	s_add_i32 s56, s56, s43
	global_load_lds_dwordx4 v148, s[36:37]
	s_mov_b32 m0, s56
	v_lshl_add_u64 v[240:241], s[40:41], 0, v[150:151]
	global_load_lds_dwordx4 v2, s[50:51]
	s_add_i32 m0, s56, 0x2000
	s_nop 0
	global_load_lds_dwordx4 v148, s[50:51]
	v_lshl_add_u64 v[228:229], s[40:41], 0, v[152:153]
	s_waitcnt vmcnt(6)
	s_waitcnt lgkmcnt(0)
	s_barrier
; #define PG8_STAGE(bufoff, gbase, voff) do { _Pragma("unroll") for (int _i = 0; _i < 2; ++_i) \
;         __builtin_amdgcn_global_load_lds((const unsigned*)((const char*)(gbase) + (voff)[_i]), (PG8_LAS unsigned*)(lds + (bufoff) + ldsw + _i * 8192), 16, 0, 0); } while (0)
; #define PG8_LDA(dst, b, h) do { _Pragma("unroll") for (int m = 0; m < 4; ++m) _Pragma("unroll") for (int k = 0; k < 2; ++k) dst[m][k] = *(const PG8_LAS bf16x8*)(lds + PG8_SA(b, h) + aoff + m * 2048 + k * 1024); } while (0)
; #define PG8_LDB(dst, b, h) do { _Pragma("unroll") for (int n = 0; n < 2; ++n) _Pragma("unroll") for (int k = 0; k < 2; ++k) dst[n][k] = *(const PG8_LAS bf16x8*)(lds + PG8_SB(b, h) + boff + n * 2048 + k * 1024); } while (0)
; #define PG8_WAIT_V(n) asm volatile("s_waitcnt vmcnt(" #n ")" ::: "memory")
; #define PG8_WAIT_L(n) asm volatile("s_waitcnt lgkmcnt(" #n ")" ::: "memory")
; #define PG8_BAR __builtin_amdgcn_s_barrier()
; #define PG8_SCHED __builtin_amdgcn_sched_barrier(0)
; template <class Epi, class Sched, bool ALIGN_EPI = false, bool SP2 = false, bool I8 = false>
; __device__ __forceinline__ void gemm_phase(PG8_LAS unsigned char* lds, const Gemm g, const Sched& S, const Epi& E) {
;     ...
;             PG8_WAIT_V(8); PG8_WAIT_L(0); PG8_BAR; PG8_MMA(1, 0, At, B0); PG8_MMA(1, 1, At, B1); PG8_BAR; PG8_SCHED;
;             PG8_LDB(B0, 1, 0); PG8_LDB(B1, 1, 1); PG8_SCHED; PG8_LDA(At, 1, 0); PG8_STAGE(PG8_SA(0, 1), a2 + hstep, voffA);
;             PG8_WAIT_V(8); PG8_WAIT_L(0); PG8_BAR; PG8_MMA(0, 0, At, B0); PG8_MMA(0, 1, At, B1); PG8_BAR; PG8_SCHED;
;             PG8_LDA(At, 1, 1); PG8_STAGE(PG8_SB(1, 0), b3, voffB); PG8_STAGE(PG8_SB(1, 1), b3 + hstep, voffB); PG8_STAGE(PG8_SA(1, 0), a3, voffA);
;             PG8_WAIT_V(8); PG8_WAIT_L(0); PG8_BAR; PG8_MMA(1, 0, At, B0); PG8_MMA(1, 1, At, B1); PG8_BAR; PG8_SCHED;
	s_setprio 1
	s_waitcnt lgkmcnt(0)
	v_mfma_i32_16x16x64_i8 v[64:67], v[116:119], v[182:185], v[64:67]
	v_mfma_i32_16x16x64_i8 v[64:67], v[124:127], v[186:189], v[64:67]
	v_mfma_i32_16x16x64_i8 v[48:51], v[124:127], v[208:211], v[48:51]
	v_mfma_i32_16x16x64_i8 v[48:51], v[116:119], v[204:207], v[48:51]
	v_mfma_i32_16x16x64_i8 v[32:35], v[116:119], v[212:215], v[32:35]
	v_mfma_i32_16x16x64_i8 v[32:35], v[124:127], v[216:219], v[32:35]
	v_mfma_i32_16x16x64_i8 v[16:19], v[124:127], v[224:227], v[16:19]
	v_mfma_i32_16x16x64_i8 v[16:19], v[116:119], v[220:223], v[16:19]
	v_mfma_i32_16x16x64_i8 v[12:15], v[132:135], v[220:223], v[12:15]
	v_mfma_i32_16x16x64_i8 v[12:15], v[136:139], v[224:227], v[12:15]
	v_mfma_i32_16x16x64_i8 v[28:31], v[136:139], v[216:219], v[28:31]
	v_mfma_i32_16x16x64_i8 v[28:31], v[132:135], v[212:215], v[28:31]
	v_mfma_i32_16x16x64_i8 v[44:47], v[132:135], v[204:207], v[44:47]
	v_mfma_i32_16x16x64_i8 v[44:47], v[136:139], v[208:211], v[44:47]
	v_mfma_i32_16x16x64_i8 v[60:63], v[136:139], v[186:189], v[60:63]
	v_mfma_i32_16x16x64_i8 v[60:63], v[132:135], v[182:185], v[60:63]
	v_mfma_i32_16x16x64_i8 v[56:59], v[160:163], v[182:185], v[56:59]
	v_mfma_i32_16x16x64_i8 v[56:59], v[164:167], v[186:189], v[56:59]
	v_mfma_i32_16x16x64_i8 v[40:43], v[164:167], v[208:211], v[40:43]
	v_mfma_i32_16x16x64_i8 v[40:43], v[160:163], v[204:207], v[40:43]
	v_mfma_i32_16x16x64_i8 v[24:27], v[160:163], v[212:215], v[24:27]
	v_mfma_i32_16x16x64_i8 v[24:27], v[164:167], v[216:219], v[24:27]
	v_mfma_i32_16x16x64_i8 v[8:11], v[164:167], v[224:227], v[8:11]
	v_mfma_i32_16x16x64_i8 v[8:11], v[160:163], v[220:223], v[8:11]
	v_mfma_i32_16x16x64_i8 v[4:7], v[168:171], v[220:223], v[4:7]
	v_mfma_i32_16x16x64_i8 v[4:7], v[178:181], v[224:227], v[4:7]
	v_mfma_i32_16x16x64_i8 v[20:23], v[178:181], v[216:219], v[20:23]
	v_mfma_i32_16x16x64_i8 v[20:23], v[168:171], v[212:215], v[20:23]
	v_mfma_i32_16x16x64_i8 v[36:39], v[168:171], v[204:207], v[36:39]
	v_mfma_i32_16x16x64_i8 v[36:39], v[178:181], v[208:211], v[36:39]
	v_mfma_i32_16x16x64_i8 v[52:55], v[178:181], v[186:189], v[52:55]
	v_mfma_i32_16x16x64_i8 v[52:55], v[168:171], v[182:185], v[52:55]
	s_setprio 0
	s_barrier
	s_mov_b32 m0, s44
	s_nop 0
	global_load_lds_dwordx4 v[228:229], off
	s_mov_b32 m0, s45
	s_nop 0
	global_load_lds_dwordx4 v[240:241], off
	s_add_i32 s50, 0, 0x18000
	s_add_i32 s51, 0, 0x1c000
	v_add_u32_e32 v136, s50, v175
	v_add_u32_e32 v178, s51, v175
	ds_read_b128 v[116:119], v136
	ds_read_b128 v[124:127], v136 offset:1024
	ds_read_b128 v[132:135], v136 offset:2048
	ds_read_b128 v[136:139], v136 offset:3072
	ds_read_b128 v[160:163], v178
	ds_read_b128 v[164:167], v178 offset:1024
	ds_read_b128 v[168:171], v178 offset:2048
	ds_read_b128 v[178:181], v178 offset:3072
	s_add_u32 s40, s40, 0x80000
	s_addc_u32 s41, s41, 0
	s_mov_b32 m0, s46
	ds_read_b128 v[182:185], v177 offset:32768
	ds_read_b128 v[186:189], v177 offset:33792
	ds_read_b128 v[204:207], v177 offset:34816
	ds_read_b128 v[208:211], v177 offset:35840
	ds_read_b128 v[212:215], v177 offset:36864
	ds_read_b128 v[216:219], v177 offset:37888
	ds_read_b128 v[220:223], v177 offset:38912
	ds_read_b128 v[224:227], v177 offset:39936
	global_load_lds_dwordx4 v152, s[40:41]
	s_mov_b32 m0, s47
	s_nop 0
	global_load_lds_dwordx4 v150, s[40:41]
	s_waitcnt vmcnt(8)
	s_waitcnt lgkmcnt(0)
	s_barrier
	s_setprio 1
	s_waitcnt lgkmcnt(0)
	v_mfma_i32_16x16x64_i8 v[144:147], v[116:119], v[182:185], v[144:147]
	v_mfma_i32_16x16x64_i8 v[144:147], v[124:127], v[186:189], v[144:147]
	v_mfma_i32_16x16x64_i8 v[112:115], v[124:127], v[208:211], v[112:115]
	v_mfma_i32_16x16x64_i8 v[112:115], v[116:119], v[204:207], v[112:115]
	v_mfma_i32_16x16x64_i8 v[96:99], v[116:119], v[212:215], v[96:99]
	v_mfma_i32_16x16x64_i8 v[96:99], v[124:127], v[216:219], v[96:99]
	v_mfma_i32_16x16x64_i8 v[80:83], v[124:127], v[224:227], v[80:83]
	v_mfma_i32_16x16x64_i8 v[80:83], v[116:119], v[220:223], v[80:83]
	v_mfma_i32_16x16x64_i8 v[76:79], v[132:135], v[220:223], v[76:79]
	v_mfma_i32_16x16x64_i8 v[76:79], v[136:139], v[224:227], v[76:79]
	v_mfma_i32_16x16x64_i8 v[92:95], v[136:139], v[216:219], v[92:95]
	v_mfma_i32_16x16x64_i8 v[92:95], v[132:135], v[212:215], v[92:95]
	v_mfma_i32_16x16x64_i8 v[108:111], v[132:135], v[204:207], v[108:111]
	v_mfma_i32_16x16x64_i8 v[108:111], v[136:139], v[208:211], v[108:111]
	v_mfma_i32_16x16x64_i8 v[140:143], v[136:139], v[186:189], v[140:143]
	v_mfma_i32_16x16x64_i8 v[140:143], v[132:135], v[182:185], v[140:143]
	v_mfma_i32_16x16x64_i8 v[128:131], v[160:163], v[182:185], v[128:131]
	v_mfma_i32_16x16x64_i8 v[128:131], v[164:167], v[186:189], v[128:131]
	v_mfma_i32_16x16x64_i8 v[104:107], v[164:167], v[208:211], v[104:107]
	v_mfma_i32_16x16x64_i8 v[104:107], v[160:163], v[204:207], v[104:107]
	v_mfma_i32_16x16x64_i8 v[88:91], v[160:163], v[212:215], v[88:91]
	v_mfma_i32_16x16x64_i8 v[88:91], v[164:167], v[216:219], v[88:91]
	v_mfma_i32_16x16x64_i8 v[72:75], v[164:167], v[224:227], v[72:75]
	v_mfma_i32_16x16x64_i8 v[72:75], v[160:163], v[220:223], v[72:75]
	v_mfma_i32_16x16x64_i8 v[68:71], v[168:171], v[220:223], v[68:71]
	v_mfma_i32_16x16x64_i8 v[68:71], v[178:181], v[224:227], v[68:71]
	v_mfma_i32_16x16x64_i8 v[84:87], v[178:181], v[216:219], v[84:87]
	v_mfma_i32_16x16x64_i8 v[84:87], v[168:171], v[212:215], v[84:87]
	v_mfma_i32_16x16x64_i8 v[100:103], v[168:171], v[204:207], v[100:103]
	v_mfma_i32_16x16x64_i8 v[100:103], v[178:181], v[208:211], v[100:103]
	v_mfma_i32_16x16x64_i8 v[120:123], v[178:181], v[186:189], v[120:123]
	v_mfma_i32_16x16x64_i8 v[120:123], v[168:171], v[182:185], v[120:123]
	s_setprio 0
	s_barrier
	s_add_i32 s40, s50, s43
	s_mov_b32 m0, s40
	ds_read_b128 v[182:185], v177 offset:49152
	ds_read_b128 v[186:189], v177 offset:50176
	ds_read_b128 v[204:207], v177 offset:51200
	ds_read_b128 v[208:211], v177 offset:52224
	ds_read_b128 v[212:215], v177 offset:53248
	ds_read_b128 v[216:219], v177 offset:54272
	ds_read_b128 v[220:223], v177 offset:55296
	ds_read_b128 v[224:227], v177 offset:56320
	s_add_u32 s98, s36, 0x80
	s_addc_u32 s99, s37, 0
	global_load_lds_dwordx4 v2, s[98:99]
	s_add_i32 m0, s40, 0x2000
	s_add_u32 s36, s36, 0x80080
	s_addc_u32 s37, s37, 0
	s_add_i32 s40, s51, s43
	global_load_lds_dwordx4 v148, s[98:99]
	s_mov_b32 m0, s40
	s_nop 0
	global_load_lds_dwordx4 v2, s[36:37]
	s_add_i32 m0, s40, 0x2000
	s_nop 0
	global_load_lds_dwordx4 v148, s[36:37]
	s_cmp_eq_u32 s76, 28
	s_cbranch_scc0 .Ldefer_208_body
	v_lshl_add_u64 v[172:173], v[228:229], 0, s[84:85]
	s_mov_b32 m0, s52
	s_nop 0
	global_load_lds_dwordx4 v[172:173], off
	v_lshl_add_u64 v[172:173], v[240:241], 0, s[84:85]
	s_mov_b32 m0, s53
	s_nop 0
	global_load_lds_dwordx4 v[172:173], off

; #define PG8_STAGE(bufoff, gbase, voff) do { _Pragma("unroll") for (int _i = 0; _i < 2; ++_i) \
;         __builtin_amdgcn_global_load_lds((const unsigned*)((const char*)(gbase) + (voff)[_i]), (PG8_LAS unsigned*)(lds + (bufoff) + ldsw + _i * 8192), 16, 0, 0); } while (0)
; #define PG8_LDA(dst, b, h) do { _Pragma("unroll") for (int m = 0; m < 4; ++m) _Pragma("unroll") for (int k = 0; k < 2; ++k) dst[m][k] = *(const PG8_LAS bf16x8*)(lds + PG8_SA(b, h) + aoff + m * 2048 + k * 1024); } while (0)
; #define PG8_LDB(dst, b, h) do { _Pragma("unroll") for (int n = 0; n < 2; ++n) _Pragma("unroll") for (int k = 0; k < 2; ++k) dst[n][k] = *(const PG8_LAS bf16x8*)(lds + PG8_SB(b, h) + boff + n * 2048 + k * 1024); } while (0)
; #define PG8_WAIT_V(n) asm volatile("s_waitcnt vmcnt(" #n ")" ::: "memory")
; #define PG8_WAIT_L(n) asm volatile("s_waitcnt lgkmcnt(" #n ")" ::: "memory")
; #define PG8_BAR __builtin_amdgcn_s_barrier()
; #define PG8_SCHED __builtin_amdgcn_sched_barrier(0)
; template <class Epi, class Sched, bool ALIGN_EPI = false, bool SP2 = false, bool I8 = false>
; __device__ __forceinline__ void gemm_phase(PG8_LAS unsigned char* lds, const Gemm g, const Sched& S, const Epi& E) {
;     ...
;         const bool has_next = S.next(ui + 1, nxt);
;         const char* nA = has_next ? (const char*)g.A + (size_t)nxt.pm * tstep : cA; const char* nB = has_next ? (const char*)g.Bt + (size_t)nxt.pn * tstep : cB;
;         for (int t = 0; t < nt; t += 2) {
;             const bool last = (t == nt - 2);
;             const char* a1 = cA + (size_t)(t + 1) * kstep;
;             const char* a2 = last ? nA : cA + (size_t)(t + 2) * kstep; const char* b2 = last ? nB : cB + (size_t)(t + 2) * kstep;
;             const char* a3 = a2 + kstep; const char* b3 = b2 + kstep;
;             if (last && has_next) S.a_ready(nxt);
;             if constexpr (SP2) {
;             PG8_LDB(B0, 0, 0); PG8_LDB(B1, 0, 1); PG8_SCHED; PG8_LDA(At, 0, 0); PG8_STAGE(PG8_SA(1, 1), a1 + hstep, voffA);
;             PG8_WAIT_V(8); PG8_WAIT_L(0); PG8_BAR; PG8_MMA(0, 0, At, B0); PG8_MMA(0, 1, At, B1); PG8_BAR; PG8_SCHED;
;             PG8_LDA(At, 0, 1); PG8_STAGE(PG8_SB(0, 0), b2, voffB); PG8_STAGE(PG8_SB(0, 1), b2 + hstep, voffB); PG8_STAGE(PG8_SA(0, 0), a2, voffA);
;             PG8_WAIT_V(8); PG8_WAIT_L(0); PG8_BAR; PG8_MMA(1, 0, At, B0); PG8_MMA(1, 1, At, B1); PG8_BAR; PG8_SCHED;
.LBB0_229:
	s_ashr_i32 s37, s36, 31
	s_lshl_b64 s[34:35], s[36:37], 21
	s_add_u32 s40, s42, s34
	s_addc_u32 s41, s43, s35
	s_and_b64 s[34:35], s[8:9], exec
	s_cselect_b32 s11, s41, s13
	s_cselect_b32 s34, s40, s12
	s_ashr_i32 s27, s26, 31
	s_lshl_b64 s[50:51], s[26:27], 21
	s_add_u32 s54, s44, s50
	s_addc_u32 s55, s45, s51
	s_and_b64 s[50:51], s[8:9], exec
	s_cselect_b32 s27, s55, s73
	s_cselect_b32 s35, s54, s72
	s_add_u32 s12, s12, 0x100080
	s_addc_u32 s13, s13, 0
	s_add_u32 s37, s72, 0x100
	s_addc_u32 s61, s73, 0
	s_mov_b32 s97, -2
	s_add_i32 s56, 0, 0x10000
	s_add_i32 s57, 0, 0x14000
	v_add_u32_e32 v156, s56, v171
	v_add_u32_e32 v168, s57, v171
	s_waitcnt vmcnt(0)
	ds_read_b128 v[112:115], v156
	ds_read_b128 v[120:123], v156 offset:1024
	ds_read_b128 v[152:155], v156 offset:2048
	ds_read_b128 v[156:159], v156 offset:3072
	ds_read_b128 v[160:163], v168
	ds_read_b128 v[164:167], v168 offset:1024
	s_waitcnt lgkmcnt(0)
	ds_read_b128 v[176:179], v168 offset:2048
	ds_read_b128 v[180:183], v168 offset:3072
	s_add_u32 s50, s12, 0xfff00080
	s_addc_u32 s51, s13, -1
	s_cmp_eq_u32 s97, 60
	s_cselect_b32 s77, s11, s51
	s_cselect_b32 s76, s34, s50
	s_cselect_b32 s73, s27, s61
	s_cselect_b32 s72, s35, s37
	s_add_i32 m0, s47, 0xc000
	ds_read_b128 v[184:187], v173
	ds_read_b128 v[188:191], v173 offset:1024
	ds_read_b128 v[204:207], v173 offset:2048
	ds_read_b128 v[208:211], v173 offset:3072
	ds_read_b128 v[212:215], v173 offset:4096
	ds_read_b128 v[216:219], v173 offset:5120
	ds_read_b128 v[220:223], v173 offset:6144
	ds_read_b128 v[224:227], v173 offset:7168
	global_load_lds_dwordx4 v148, s[12:13]
	s_add_i32 m0, s47, 0xe000
	s_nop 0
	global_load_lds_dwordx4 v150, s[12:13]
	s_waitcnt vmcnt(8)
	s_waitcnt lgkmcnt(0)
	s_barrier
	s_setprio 1
	s_waitcnt lgkmcnt(0)
	v_mfma_f32_16x16x32_bf16 v[136:139], v[112:115], v[184:187], 0
	v_mfma_f32_16x16x32_bf16 v[136:139], v[120:123], v[188:191], v[136:139]
	v_mfma_f32_16x16x32_bf16 v[116:119], v[120:123], v[208:211], 0
	v_mfma_f32_16x16x32_bf16 v[116:119], v[112:115], v[204:207], v[116:119]
	v_mfma_f32_16x16x32_bf16 v[96:99], v[112:115], v[212:215], 0
	v_mfma_f32_16x16x32_bf16 v[96:99], v[120:123], v[216:219], v[96:99]
	v_mfma_f32_16x16x32_bf16 v[80:83], v[120:123], v[224:227], 0
	v_mfma_f32_16x16x32_bf16 v[80:83], v[112:115], v[220:223], v[80:83]
	v_mfma_f32_16x16x32_bf16 v[76:79], v[152:155], v[220:223], 0
	v_mfma_f32_16x16x32_bf16 v[76:79], v[156:159], v[224:227], v[76:79]
	v_mfma_f32_16x16x32_bf16 v[92:95], v[156:159], v[216:219], 0
	v_mfma_f32_16x16x32_bf16 v[92:95], v[152:155], v[212:215], v[92:95]
	v_mfma_f32_16x16x32_bf16 v[108:111], v[152:155], v[204:207], 0
	v_mfma_f32_16x16x32_bf16 v[108:111], v[156:159], v[208:211], v[108:111]
	v_mfma_f32_16x16x32_bf16 v[132:135], v[156:159], v[188:191], 0
	v_mfma_f32_16x16x32_bf16 v[132:135], v[152:155], v[184:187], v[132:135]
	v_mfma_f32_16x16x32_bf16 v[128:131], v[160:163], v[184:187], 0
	v_mfma_f32_16x16x32_bf16 v[128:131], v[164:167], v[188:191], v[128:131]
	v_mfma_f32_16x16x32_bf16 v[104:107], v[164:167], v[208:211], 0
	v_mfma_f32_16x16x32_bf16 v[104:107], v[160:163], v[204:207], v[104:107]
	v_mfma_f32_16x16x32_bf16 v[88:91], v[160:163], v[212:215], 0
	v_mfma_f32_16x16x32_bf16 v[88:91], v[164:167], v[216:219], v[88:91]
	v_mfma_f32_16x16x32_bf16 v[72:75], v[164:167], v[224:227], 0
	v_mfma_f32_16x16x32_bf16 v[72:75], v[160:163], v[220:223], v[72:75]
	v_mfma_f32_16x16x32_bf16 v[68:71], v[176:179], v[220:223], 0
	v_mfma_f32_16x16x32_bf16 v[68:71], v[180:183], v[224:227], v[68:71]
	v_mfma_f32_16x16x32_bf16 v[84:87], v[180:183], v[216:219], 0
	v_mfma_f32_16x16x32_bf16 v[84:87], v[176:179], v[212:215], v[84:87]
	v_mfma_f32_16x16x32_bf16 v[100:103], v[176:179], v[204:207], 0
	v_mfma_f32_16x16x32_bf16 v[100:103], v[180:183], v[208:211], v[100:103]
	v_mfma_f32_16x16x32_bf16 v[124:127], v[180:183], v[188:191], 0
	v_mfma_f32_16x16x32_bf16 v[124:127], v[176:179], v[184:187], v[124:127]
	s_setprio 0
	s_barrier
	s_add_i32 s50, s56, s46
	s_mov_b32 m0, s50
	ds_read_b128 v[184:187], v173 offset:16384
	ds_read_b128 v[188:191], v173 offset:17408
	ds_read_b128 v[204:207], v173 offset:18432
	ds_read_b128 v[208:211], v173 offset:19456
	ds_read_b128 v[212:215], v173 offset:20480
	ds_read_b128 v[216:219], v173 offset:21504
	ds_read_b128 v[220:223], v173 offset:22528
	ds_read_b128 v[224:227], v173 offset:23552
	global_load_lds_dwordx4 v2, s[72:73]
	s_add_i32 m0, s50, 0x2000
	s_add_u32 s50, s72, 0x100000
	s_addc_u32 s51, s73, 0
	s_add_i32 s56, s57, s46
	global_load_lds_dwordx4 v144, s[72:73]
	s_mov_b32 m0, s56
	v_lshl_add_u64 v[242:243], s[76:77], 0, v[142:143]
	global_load_lds_dwordx4 v2, s[50:51]
	s_add_i32 m0, s56, 0x2000
	s_nop 0
	global_load_lds_dwordx4 v144, s[50:51]
	v_lshl_add_u64 v[240:241], s[76:77], 0, v[140:141]
	s_waitcnt vmcnt(6)
	s_waitcnt lgkmcnt(0)
	s_barrier
; #define PG8_STAGE(bufoff, gbase, voff) do { _Pragma("unroll") for (int _i = 0; _i < 2; ++_i) \
;         __builtin_amdgcn_global_load_lds((const unsigned*)((const char*)(gbase) + (voff)[_i]), (PG8_LAS unsigned*)(lds + (bufoff) + ldsw + _i * 8192), 16, 0, 0); } while (0)
; #define PG8_LDA(dst, b, h) do { _Pragma("unroll") for (int m = 0; m < 4; ++m) _Pragma("unroll") for (int k = 0; k < 2; ++k) dst[m][k] = *(const PG8_LAS bf16x8*)(lds + PG8_SA(b, h) + aoff + m * 2048 + k * 1024); } while (0)
; #define PG8_LDB(dst, b, h) do { _Pragma("unroll") for (int n = 0; n < 2; ++n) _Pragma("unroll") for (int k = 0; k < 2; ++k) dst[n][k] = *(const PG8_LAS bf16x8*)(lds + PG8_SB(b, h) + boff + n * 2048 + k * 1024); } while (0)
; #define PG8_WAIT_V(n) asm volatile("s_waitcnt vmcnt(" #n ")" ::: "memory")
; #define PG8_WAIT_L(n) asm volatile("s_waitcnt lgkmcnt(" #n ")" ::: "memory")
; #define PG8_BAR __builtin_amdgcn_s_barrier()
; #define PG8_SCHED __builtin_amdgcn_sched_barrier(0)
; template <class Epi, class Sched, bool ALIGN_EPI = false, bool SP2 = false, bool I8 = false>
; __device__ __forceinline__ void gemm_phase(PG8_LAS unsigned char* lds, const Gemm g, const Sched& S, const Epi& E) {
;     ...
;             PG8_WAIT_V(8); PG8_WAIT_L(0); PG8_BAR; PG8_MMA(1, 0, At, B0); PG8_MMA(1, 1, At, B1); PG8_BAR; PG8_SCHED;
;             PG8_LDB(B0, 1, 0); PG8_LDB(B1, 1, 1); PG8_SCHED; PG8_LDA(At, 1, 0); PG8_STAGE(PG8_SA(0, 1), a2 + hstep, voffA);
;             PG8_WAIT_V(8); PG8_WAIT_L(0); PG8_BAR; PG8_MMA(0, 0, At, B0); PG8_MMA(0, 1, At, B1); PG8_BAR; PG8_SCHED;
;             PG8_LDA(At, 1, 1); PG8_STAGE(PG8_SB(1, 0), b3, voffB); PG8_STAGE(PG8_SB(1, 1), b3 + hstep, voffB); PG8_STAGE(PG8_SA(1, 0), a3, voffA);
;             PG8_WAIT_V(8); PG8_WAIT_L(0); PG8_BAR; PG8_MMA(1, 0, At, B0); PG8_MMA(1, 1, At, B1); PG8_BAR; PG8_SCHED;
	s_setprio 1
	s_waitcnt lgkmcnt(0)
	v_mfma_f32_16x16x32_bf16 v[64:67], v[112:115], v[184:187], 0
	v_mfma_f32_16x16x32_bf16 v[64:67], v[120:123], v[188:191], v[64:67]
	v_mfma_f32_16x16x32_bf16 v[48:51], v[120:123], v[208:211], 0
	v_mfma_f32_16x16x32_bf16 v[48:51], v[112:115], v[204:207], v[48:51]
	v_mfma_f32_16x16x32_bf16 v[32:35], v[112:115], v[212:215], 0
	v_mfma_f32_16x16x32_bf16 v[32:35], v[120:123], v[216:219], v[32:35]
	v_mfma_f32_16x16x32_bf16 v[16:19], v[120:123], v[224:227], 0
	v_mfma_f32_16x16x32_bf16 v[16:19], v[112:115], v[220:223], v[16:19]
	v_mfma_f32_16x16x32_bf16 v[12:15], v[152:155], v[220:223], 0
	v_mfma_f32_16x16x32_bf16 v[12:15], v[156:159], v[224:227], v[12:15]
	v_mfma_f32_16x16x32_bf16 v[28:31], v[156:159], v[216:219], 0
	v_mfma_f32_16x16x32_bf16 v[28:31], v[152:155], v[212:215], v[28:31]
	v_mfma_f32_16x16x32_bf16 v[44:47], v[152:155], v[204:207], 0
	v_mfma_f32_16x16x32_bf16 v[44:47], v[156:159], v[208:211], v[44:47]
	v_mfma_f32_16x16x32_bf16 v[60:63], v[156:159], v[188:191], 0
	v_mfma_f32_16x16x32_bf16 v[60:63], v[152:155], v[184:187], v[60:63]
	v_mfma_f32_16x16x32_bf16 v[56:59], v[160:163], v[184:187], 0
	v_mfma_f32_16x16x32_bf16 v[56:59], v[164:167], v[188:191], v[56:59]
	v_mfma_f32_16x16x32_bf16 v[40:43], v[164:167], v[208:211], 0
	v_mfma_f32_16x16x32_bf16 v[40:43], v[160:163], v[204:207], v[40:43]
	v_mfma_f32_16x16x32_bf16 v[24:27], v[160:163], v[212:215], 0
	v_mfma_f32_16x16x32_bf16 v[24:27], v[164:167], v[216:219], v[24:27]
	v_mfma_f32_16x16x32_bf16 v[8:11], v[164:167], v[224:227], 0
	v_mfma_f32_16x16x32_bf16 v[8:11], v[160:163], v[220:223], v[8:11]
	v_mfma_f32_16x16x32_bf16 v[4:7], v[176:179], v[220:223], 0
	v_mfma_f32_16x16x32_bf16 v[4:7], v[180:183], v[224:227], v[4:7]
	v_mfma_f32_16x16x32_bf16 v[20:23], v[180:183], v[216:219], 0
	v_mfma_f32_16x16x32_bf16 v[20:23], v[176:179], v[212:215], v[20:23]
	v_mfma_f32_16x16x32_bf16 v[36:39], v[176:179], v[204:207], 0
	v_mfma_f32_16x16x32_bf16 v[36:39], v[180:183], v[208:211], v[36:39]
	v_mfma_f32_16x16x32_bf16 v[52:55], v[180:183], v[188:191], 0
	v_mfma_f32_16x16x32_bf16 v[52:55], v[176:179], v[184:187], v[52:55]
	s_setprio 0
	s_barrier
	s_mov_b32 m0, s47
	s_nop 0
	global_load_lds_dwordx4 v[240:241], off
	s_mov_b32 m0, s52
	s_nop 0
	global_load_lds_dwordx4 v[242:243], off
	s_add_i32 s56, 0, 0x18000
	s_add_i32 s57, 0, 0x1c000
	v_add_u32_e32 v156, s56, v171
	v_add_u32_e32 v175, s57, v171
	ds_read_b128 v[112:115], v156
	ds_read_b128 v[120:123], v156 offset:1024
	ds_read_b128 v[152:155], v156 offset:2048
	ds_read_b128 v[156:159], v156 offset:3072
	ds_read_b128 v[160:163], v175
	ds_read_b128 v[164:167], v175 offset:1024
	ds_read_b128 v[176:179], v175 offset:2048
	ds_read_b128 v[180:183], v175 offset:3072
	s_add_u32 s50, s76, 0x100000
	s_addc_u32 s51, s77, 0
	s_mov_b32 m0, s53
	ds_read_b128 v[184:187], v173 offset:32768
	ds_read_b128 v[188:191], v173 offset:33792
	ds_read_b128 v[204:207], v173 offset:34816
	ds_read_b128 v[208:211], v173 offset:35840
	ds_read_b128 v[212:215], v173 offset:36864
	ds_read_b128 v[216:219], v173 offset:37888
	ds_read_b128 v[220:223], v173 offset:38912
	ds_read_b128 v[224:227], v173 offset:39936
	global_load_lds_dwordx4 v140, s[50:51]
	s_mov_b32 m0, s64
	s_nop 0
	global_load_lds_dwordx4 v142, s[50:51]
	s_waitcnt vmcnt(8)
	s_waitcnt lgkmcnt(0)
	s_barrier
	s_setprio 1
	s_waitcnt lgkmcnt(0)
	v_mfma_f32_16x16x32_bf16 v[136:139], v[112:115], v[184:187], v[136:139]
	v_mfma_f32_16x16x32_bf16 v[136:139], v[120:123], v[188:191], v[136:139]
	v_mfma_f32_16x16x32_bf16 v[116:119], v[120:123], v[208:211], v[116:119]
	v_mfma_f32_16x16x32_bf16 v[116:119], v[112:115], v[204:207], v[116:119]
	v_mfma_f32_16x16x32_bf16 v[96:99], v[112:115], v[212:215], v[96:99]
	v_mfma_f32_16x16x32_bf16 v[96:99], v[120:123], v[216:219], v[96:99]
	v_mfma_f32_16x16x32_bf16 v[80:83], v[120:123], v[224:227], v[80:83]
	v_mfma_f32_16x16x32_bf16 v[80:83], v[112:115], v[220:223], v[80:83]
	v_mfma_f32_16x16x32_bf16 v[76:79], v[152:155], v[220:223], v[76:79]
	v_mfma_f32_16x16x32_bf16 v[76:79], v[156:159], v[224:227], v[76:79]
	v_mfma_f32_16x16x32_bf16 v[92:95], v[156:159], v[216:219], v[92:95]
	v_mfma_f32_16x16x32_bf16 v[92:95], v[152:155], v[212:215], v[92:95]
	v_mfma_f32_16x16x32_bf16 v[108:111], v[152:155], v[204:207], v[108:111]
	v_mfma_f32_16x16x32_bf16 v[108:111], v[156:159], v[208:211], v[108:111]
	v_mfma_f32_16x16x32_bf16 v[132:135], v[156:159], v[188:191], v[132:135]
	v_mfma_f32_16x16x32_bf16 v[132:135], v[152:155], v[184:187], v[132:135]
	v_mfma_f32_16x16x32_bf16 v[128:131], v[160:163], v[184:187], v[128:131]
	v_mfma_f32_16x16x32_bf16 v[128:131], v[164:167], v[188:191], v[128:131]
	v_mfma_f32_16x16x32_bf16 v[104:107], v[164:167], v[208:211], v[104:107]
	v_mfma_f32_16x16x32_bf16 v[104:107], v[160:163], v[204:207], v[104:107]
	v_mfma_f32_16x16x32_bf16 v[88:91], v[160:163], v[212:215], v[88:91]
	v_mfma_f32_16x16x32_bf16 v[88:91], v[164:167], v[216:219], v[88:91]
	v_mfma_f32_16x16x32_bf16 v[72:75], v[164:167], v[224:227], v[72:75]
	v_mfma_f32_16x16x32_bf16 v[72:75], v[160:163], v[220:223], v[72:75]
	v_mfma_f32_16x16x32_bf16 v[68:71], v[176:179], v[220:223], v[68:71]
	v_mfma_f32_16x16x32_bf16 v[68:71], v[180:183], v[224:227], v[68:71]
	v_mfma_f32_16x16x32_bf16 v[84:87], v[180:183], v[216:219], v[84:87]
	v_mfma_f32_16x16x32_bf16 v[84:87], v[176:179], v[212:215], v[84:87]
	v_mfma_f32_16x16x32_bf16 v[100:103], v[176:179], v[204:207], v[100:103]
	v_mfma_f32_16x16x32_bf16 v[100:103], v[180:183], v[208:211], v[100:103]
	v_mfma_f32_16x16x32_bf16 v[124:127], v[180:183], v[188:191], v[124:127]
	v_mfma_f32_16x16x32_bf16 v[124:127], v[176:179], v[184:187], v[124:127]
	s_setprio 0
	s_barrier
	s_add_i32 s50, s56, s46
	s_mov_b32 m0, s50
	ds_read_b128 v[184:187], v173 offset:49152
	ds_read_b128 v[188:191], v173 offset:50176
	ds_read_b128 v[204:207], v173 offset:51200
	ds_read_b128 v[208:211], v173 offset:52224
	ds_read_b128 v[212:215], v173 offset:53248
	ds_read_b128 v[216:219], v173 offset:54272
	ds_read_b128 v[220:223], v173 offset:55296
	ds_read_b128 v[224:227], v173 offset:56320
	s_add_u32 s98, s72, 0x80
	s_addc_u32 s99, s73, 0
	global_load_lds_dwordx4 v2, s[98:99]
	s_add_i32 m0, s50, 0x2000
	s_add_u32 s50, s72, 0x100080
	s_addc_u32 s51, s73, 0
	s_add_i32 s56, s57, s46
	global_load_lds_dwordx4 v144, s[98:99]
	s_mov_b32 m0, s56
	s_nop 0
	global_load_lds_dwordx4 v2, s[50:51]
	s_add_i32 m0, s56, 0x2000
	s_nop 0
	global_load_lds_dwordx4 v144, s[50:51]
	s_cmp_eq_u32 s97, 60
	s_cbranch_scc0 .Ldefer_230_peel
	v_lshl_add_u64 v[168:169], v[240:241], 0, s[84:85]
	s_mov_b32 m0, s28
	s_nop 0
	global_load_lds_dwordx4 v[168:169], off
	v_lshl_add_u64 v[168:169], v[242:243], 0, s[84:85]
	s_mov_b32 m0, s65
	s_nop 0
	global_load_lds_dwordx4 v[168:169], off

; #define PG8_STAGE(bufoff, gbase, voff) do { _Pragma("unroll") for (int _i = 0; _i < 2; ++_i) \
;         __builtin_amdgcn_global_load_lds((const unsigned*)((const char*)(gbase) + (voff)[_i]), (PG8_LAS unsigned*)(lds + (bufoff) + ldsw + _i * 8192), 16, 0, 0); } while (0)
; #define PG8_LDA(dst, b, h) do { _Pragma("unroll") for (int m = 0; m < 4; ++m) _Pragma("unroll") for (int k = 0; k < 2; ++k) dst[m][k] = *(const PG8_LAS bf16x8*)(lds + PG8_SA(b, h) + aoff + m * 2048 + k * 1024); } while (0)
; #define PG8_LDB(dst, b, h) do { _Pragma("unroll") for (int n = 0; n < 2; ++n) _Pragma("unroll") for (int k = 0; k < 2; ++k) dst[n][k] = *(const PG8_LAS bf16x8*)(lds + PG8_SB(b, h) + boff + n * 2048 + k * 1024); } while (0)
; #define PG8_WAIT_V(n) asm volatile("s_waitcnt vmcnt(" #n ")" ::: "memory")
; #define PG8_WAIT_L(n) asm volatile("s_waitcnt lgkmcnt(" #n ")" ::: "memory")
; #define PG8_BAR __builtin_amdgcn_s_barrier()
; #define PG8_SCHED __builtin_amdgcn_sched_barrier(0)
; template <class Epi, class Sched, bool ALIGN_EPI = false, bool SP2 = false, bool I8 = false>
; __device__ __forceinline__ void gemm_phase(PG8_LAS unsigned char* lds, const Gemm g, const Sched& S, const Epi& E) {
;     ...
;             const bool last = (t == nt - 2);
;             const char* a1 = cA + (size_t)(t + 1) * kstep;
;             const char* a2 = last ? nA : cA + (size_t)(t + 2) * kstep; const char* b2 = last ? nB : cB + (size_t)(t + 2) * kstep;
;             const char* a3 = a2 + kstep; const char* b3 = b2 + kstep;
;             if (last && has_next) S.a_ready(nxt);
;             if constexpr (SP2) {
;             PG8_LDB(B0, 0, 0); PG8_LDB(B1, 0, 1); PG8_SCHED; PG8_LDA(At, 0, 0); PG8_STAGE(PG8_SA(1, 1), a1 + hstep, voffA);
;             PG8_WAIT_V(8); PG8_WAIT_L(0); PG8_BAR; PG8_MMA(0, 0, At, B0); PG8_MMA(0, 1, At, B1); PG8_BAR; PG8_SCHED;
;             PG8_LDA(At, 0, 1); PG8_STAGE(PG8_SB(0, 0), b2, voffB); PG8_STAGE(PG8_SB(0, 1), b2 + hstep, voffB); PG8_STAGE(PG8_SA(0, 0), a2, voffA);
;             PG8_WAIT_V(8); PG8_WAIT_L(0); PG8_BAR; PG8_MMA(1, 0, At, B0); PG8_MMA(1, 1, At, B1); PG8_BAR; PG8_SCHED;
.LBB0_230:
	s_add_i32 s56, 0, 0x10000
	s_add_i32 s57, 0, 0x14000
	v_add_u32_e32 v156, s56, v171
	v_add_u32_e32 v168, s57, v171
	ds_read_b128 v[112:115], v156
	ds_read_b128 v[120:123], v156 offset:1024
	ds_read_b128 v[152:155], v156 offset:2048
	ds_read_b128 v[156:159], v156 offset:3072
	ds_read_b128 v[160:163], v168
	ds_read_b128 v[164:167], v168 offset:1024
	ds_read_b128 v[176:179], v168 offset:2048
	ds_read_b128 v[180:183], v168 offset:3072
	s_add_u32 s50, s12, 0xfff00080
	s_addc_u32 s51, s13, -1
	s_cmp_eq_u32 s97, 60
	s_cselect_b32 s77, s11, s51
	s_cselect_b32 s76, s34, s50
	s_cselect_b32 s73, s27, s61
	s_cselect_b32 s72, s35, s37
	v_lshl_add_u64 v[168:169], v[240:241], 0, s[84:85]
	s_mov_b32 m0, s28
	s_nop 0
	global_load_lds_dwordx4 v[168:169], off
	v_lshl_add_u64 v[168:169], v[242:243], 0, s[84:85]
	s_mov_b32 m0, s65
	s_nop 0
	global_load_lds_dwordx4 v[168:169], off
	s_add_i32 m0, s47, 0xc000
	ds_read_b128 v[184:187], v173
	ds_read_b128 v[188:191], v173 offset:1024
	ds_read_b128 v[204:207], v173 offset:2048
	ds_read_b128 v[208:211], v173 offset:3072
	ds_read_b128 v[212:215], v173 offset:4096
	ds_read_b128 v[216:219], v173 offset:5120
	ds_read_b128 v[220:223], v173 offset:6144
	ds_read_b128 v[224:227], v173 offset:7168
	global_load_lds_dwordx4 v148, s[12:13]
	s_add_i32 m0, s47, 0xe000
	s_nop 0
	global_load_lds_dwordx4 v150, s[12:13]
	s_waitcnt vmcnt(8)
	s_waitcnt lgkmcnt(0)
	s_barrier
	s_setprio 1
	s_waitcnt lgkmcnt(0)
	v_mfma_f32_16x16x32_bf16 v[136:139], v[112:115], v[184:187], v[136:139]
	v_mfma_f32_16x16x32_bf16 v[136:139], v[120:123], v[188:191], v[136:139]
	v_mfma_f32_16x16x32_bf16 v[116:119], v[120:123], v[208:211], v[116:119]
	v_mfma_f32_16x16x32_bf16 v[116:119], v[112:115], v[204:207], v[116:119]
	v_mfma_f32_16x16x32_bf16 v[96:99], v[112:115], v[212:215], v[96:99]
	v_mfma_f32_16x16x32_bf16 v[96:99], v[120:123], v[216:219], v[96:99]
	v_mfma_f32_16x16x32_bf16 v[80:83], v[120:123], v[224:227], v[80:83]
	v_mfma_f32_16x16x32_bf16 v[80:83], v[112:115], v[220:223], v[80:83]
	v_mfma_f32_16x16x32_bf16 v[76:79], v[152:155], v[220:223], v[76:79]
	v_mfma_f32_16x16x32_bf16 v[76:79], v[156:159], v[224:227], v[76:79]
	v_mfma_f32_16x16x32_bf16 v[92:95], v[156:159], v[216:219], v[92:95]
	v_mfma_f32_16x16x32_bf16 v[92:95], v[152:155], v[212:215], v[92:95]
	v_mfma_f32_16x16x32_bf16 v[108:111], v[152:155], v[204:207], v[108:111]
	v_mfma_f32_16x16x32_bf16 v[108:111], v[156:159], v[208:211], v[108:111]
	v_mfma_f32_16x16x32_bf16 v[132:135], v[156:159], v[188:191], v[132:135]
	v_mfma_f32_16x16x32_bf16 v[132:135], v[152:155], v[184:187], v[132:135]
	v_mfma_f32_16x16x32_bf16 v[128:131], v[160:163], v[184:187], v[128:131]
	v_mfma_f32_16x16x32_bf16 v[128:131], v[164:167], v[188:191], v[128:131]
	v_mfma_f32_16x16x32_bf16 v[104:107], v[164:167], v[208:211], v[104:107]
	v_mfma_f32_16x16x32_bf16 v[104:107], v[160:163], v[204:207], v[104:107]
	v_mfma_f32_16x16x32_bf16 v[88:91], v[160:163], v[212:215], v[88:91]
	v_mfma_f32_16x16x32_bf16 v[88:91], v[164:167], v[216:219], v[88:91]
	v_mfma_f32_16x16x32_bf16 v[72:75], v[164:167], v[224:227], v[72:75]
	v_mfma_f32_16x16x32_bf16 v[72:75], v[160:163], v[220:223], v[72:75]
	v_mfma_f32_16x16x32_bf16 v[68:71], v[176:179], v[220:223], v[68:71]
	v_mfma_f32_16x16x32_bf16 v[68:71], v[180:183], v[224:227], v[68:71]
	v_mfma_f32_16x16x32_bf16 v[84:87], v[180:183], v[216:219], v[84:87]
	v_mfma_f32_16x16x32_bf16 v[84:87], v[176:179], v[212:215], v[84:87]
	v_mfma_f32_16x16x32_bf16 v[100:103], v[176:179], v[204:207], v[100:103]
	v_mfma_f32_16x16x32_bf16 v[100:103], v[180:183], v[208:211], v[100:103]
	v_mfma_f32_16x16x32_bf16 v[124:127], v[180:183], v[188:191], v[124:127]
	v_mfma_f32_16x16x32_bf16 v[124:127], v[176:179], v[184:187], v[124:127]
	s_setprio 0
	s_barrier
	s_add_i32 s50, s56, s46
	s_mov_b32 m0, s50
	ds_read_b128 v[184:187], v173 offset:16384
	ds_read_b128 v[188:191], v173 offset:17408
	ds_read_b128 v[204:207], v173 offset:18432
	ds_read_b128 v[208:211], v173 offset:19456
	ds_read_b128 v[212:215], v173 offset:20480
	ds_read_b128 v[216:219], v173 offset:21504
	ds_read_b128 v[220:223], v173 offset:22528
	ds_read_b128 v[224:227], v173 offset:23552
	global_load_lds_dwordx4 v2, s[72:73]
	s_add_i32 m0, s50, 0x2000
	s_add_u32 s50, s72, 0x100000
	s_addc_u32 s51, s73, 0
	s_add_i32 s56, s57, s46
	global_load_lds_dwordx4 v144, s[72:73]
	s_mov_b32 m0, s56
	v_lshl_add_u64 v[242:243], s[76:77], 0, v[142:143]
	global_load_lds_dwordx4 v2, s[50:51]
	s_add_i32 m0, s56, 0x2000
	s_nop 0
	global_load_lds_dwordx4 v144, s[50:51]
	v_lshl_add_u64 v[240:241], s[76:77], 0, v[140:141]
	s_waitcnt vmcnt(6)
	s_waitcnt lgkmcnt(0)
	s_barrier
; #define PG8_STAGE(bufoff, gbase, voff) do { _Pragma("unroll") for (int _i = 0; _i < 2; ++_i) \
;         __builtin_amdgcn_global_load_lds((const unsigned*)((const char*)(gbase) + (voff)[_i]), (PG8_LAS unsigned*)(lds + (bufoff) + ldsw + _i * 8192), 16, 0, 0); } while (0)
; #define PG8_LDA(dst, b, h) do { _Pragma("unroll") for (int m = 0; m < 4; ++m) _Pragma("unroll") for (int k = 0; k < 2; ++k) dst[m][k] = *(const PG8_LAS bf16x8*)(lds + PG8_SA(b, h) + aoff + m * 2048 + k * 1024); } while (0)
; #define PG8_LDB(dst, b, h) do { _Pragma("unroll") for (int n = 0; n < 2; ++n) _Pragma("unroll") for (int k = 0; k < 2; ++k) dst[n][k] = *(const PG8_LAS bf16x8*)(lds + PG8_SB(b, h) + boff + n * 2048 + k * 1024); } while (0)
; #define PG8_WAIT_V(n) asm volatile("s_waitcnt vmcnt(" #n ")" ::: "memory")
; #define PG8_WAIT_L(n) asm volatile("s_waitcnt lgkmcnt(" #n ")" ::: "memory")
; #define PG8_BAR __builtin_amdgcn_s_barrier()
; #define PG8_SCHED __builtin_amdgcn_sched_barrier(0)
; template <class Epi, class Sched, bool ALIGN_EPI = false, bool SP2 = false, bool I8 = false>
; __device__ __forceinline__ void gemm_phase(PG8_LAS unsigned char* lds, const Gemm g, const Sched& S, const Epi& E) {
;     ...
;             PG8_WAIT_V(8); PG8_WAIT_L(0); PG8_BAR; PG8_MMA(1, 0, At, B0); PG8_MMA(1, 1, At, B1); PG8_BAR; PG8_SCHED;
;             PG8_LDB(B0, 1, 0); PG8_LDB(B1, 1, 1); PG8_SCHED; PG8_LDA(At, 1, 0); PG8_STAGE(PG8_SA(0, 1), a2 + hstep, voffA);
;             PG8_WAIT_V(8); PG8_WAIT_L(0); PG8_BAR; PG8_MMA(0, 0, At, B0); PG8_MMA(0, 1, At, B1); PG8_BAR; PG8_SCHED;
;             PG8_LDA(At, 1, 1); PG8_STAGE(PG8_SB(1, 0), b3, voffB); PG8_STAGE(PG8_SB(1, 1), b3 + hstep, voffB); PG8_STAGE(PG8_SA(1, 0), a3, voffA);
;             PG8_WAIT_V(8); PG8_WAIT_L(0); PG8_BAR; PG8_MMA(1, 0, At, B0); PG8_MMA(1, 1, At, B1); PG8_BAR; PG8_SCHED;
	s_setprio 1
	s_waitcnt lgkmcnt(0)
	v_mfma_f32_16x16x32_bf16 v[64:67], v[112:115], v[184:187], v[64:67]
	v_mfma_f32_16x16x32_bf16 v[64:67], v[120:123], v[188:191], v[64:67]
	v_mfma_f32_16x16x32_bf16 v[48:51], v[120:123], v[208:211], v[48:51]
	v_mfma_f32_16x16x32_bf16 v[48:51], v[112:115], v[204:207], v[48:51]
	v_mfma_f32_16x16x32_bf16 v[32:35], v[112:115], v[212:215], v[32:35]
	v_mfma_f32_16x16x32_bf16 v[32:35], v[120:123], v[216:219], v[32:35]
	v_mfma_f32_16x16x32_bf16 v[16:19], v[120:123], v[224:227], v[16:19]
	v_mfma_f32_16x16x32_bf16 v[16:19], v[112:115], v[220:223], v[16:19]
	v_mfma_f32_16x16x32_bf16 v[12:15], v[152:155], v[220:223], v[12:15]
	v_mfma_f32_16x16x32_bf16 v[12:15], v[156:159], v[224:227], v[12:15]
	v_mfma_f32_16x16x32_bf16 v[28:31], v[156:159], v[216:219], v[28:31]
	v_mfma_f32_16x16x32_bf16 v[28:31], v[152:155], v[212:215], v[28:31]
	v_mfma_f32_16x16x32_bf16 v[44:47], v[152:155], v[204:207], v[44:47]
	v_mfma_f32_16x16x32_bf16 v[44:47], v[156:159], v[208:211], v[44:47]
	v_mfma_f32_16x16x32_bf16 v[60:63], v[156:159], v[188:191], v[60:63]
	v_mfma_f32_16x16x32_bf16 v[60:63], v[152:155], v[184:187], v[60:63]
	v_mfma_f32_16x16x32_bf16 v[56:59], v[160:163], v[184:187], v[56:59]
	v_mfma_f32_16x16x32_bf16 v[56:59], v[164:167], v[188:191], v[56:59]
	v_mfma_f32_16x16x32_bf16 v[40:43], v[164:167], v[208:211], v[40:43]
	v_mfma_f32_16x16x32_bf16 v[40:43], v[160:163], v[204:207], v[40:43]
	v_mfma_f32_16x16x32_bf16 v[24:27], v[160:163], v[212:215], v[24:27]
	v_mfma_f32_16x16x32_bf16 v[24:27], v[164:167], v[216:219], v[24:27]
	v_mfma_f32_16x16x32_bf16 v[8:11], v[164:167], v[224:227], v[8:11]
	v_mfma_f32_16x16x32_bf16 v[8:11], v[160:163], v[220:223], v[8:11]
	v_mfma_f32_16x16x32_bf16 v[4:7], v[176:179], v[220:223], v[4:7]
	v_mfma_f32_16x16x32_bf16 v[4:7], v[180:183], v[224:227], v[4:7]
	v_mfma_f32_16x16x32_bf16 v[20:23], v[180:183], v[216:219], v[20:23]
	v_mfma_f32_16x16x32_bf16 v[20:23], v[176:179], v[212:215], v[20:23]
	v_mfma_f32_16x16x32_bf16 v[36:39], v[176:179], v[204:207], v[36:39]
	v_mfma_f32_16x16x32_bf16 v[36:39], v[180:183], v[208:211], v[36:39]
	v_mfma_f32_16x16x32_bf16 v[52:55], v[180:183], v[188:191], v[52:55]
	v_mfma_f32_16x16x32_bf16 v[52:55], v[176:179], v[184:187], v[52:55]
	s_setprio 0
	s_barrier
	s_mov_b32 m0, s47
	s_nop 0
	global_load_lds_dwordx4 v[240:241], off
	s_mov_b32 m0, s52
	s_nop 0
	global_load_lds_dwordx4 v[242:243], off
	s_add_i32 s56, 0, 0x18000
	s_add_i32 s57, 0, 0x1c000
	v_add_u32_e32 v156, s56, v171
	v_add_u32_e32 v175, s57, v171
	ds_read_b128 v[112:115], v156
	ds_read_b128 v[120:123], v156 offset:1024
	ds_read_b128 v[152:155], v156 offset:2048
	ds_read_b128 v[156:159], v156 offset:3072
	ds_read_b128 v[160:163], v175
	ds_read_b128 v[164:167], v175 offset:1024
	ds_read_b128 v[176:179], v175 offset:2048
	ds_read_b128 v[180:183], v175 offset:3072
	s_add_u32 s50, s76, 0x100000
	s_addc_u32 s51, s77, 0
	s_mov_b32 m0, s53
	ds_read_b128 v[184:187], v173 offset:32768
	ds_read_b128 v[188:191], v173 offset:33792
	ds_read_b128 v[204:207], v173 offset:34816
	ds_read_b128 v[208:211], v173 offset:35840
	ds_read_b128 v[212:215], v173 offset:36864
	ds_read_b128 v[216:219], v173 offset:37888
	ds_read_b128 v[220:223], v173 offset:38912
	ds_read_b128 v[224:227], v173 offset:39936
	global_load_lds_dwordx4 v140, s[50:51]
	s_mov_b32 m0, s64
	s_nop 0
	global_load_lds_dwordx4 v142, s[50:51]
	s_waitcnt vmcnt(8)
	s_waitcnt lgkmcnt(0)
	s_barrier
	s_setprio 1
	s_waitcnt lgkmcnt(0)
	v_mfma_f32_16x16x32_bf16 v[136:139], v[112:115], v[184:187], v[136:139]
	v_mfma_f32_16x16x32_bf16 v[136:139], v[120:123], v[188:191], v[136:139]
	v_mfma_f32_16x16x32_bf16 v[116:119], v[120:123], v[208:211], v[116:119]
	v_mfma_f32_16x16x32_bf16 v[116:119], v[112:115], v[204:207], v[116:119]
	v_mfma_f32_16x16x32_bf16 v[96:99], v[112:115], v[212:215], v[96:99]
	v_mfma_f32_16x16x32_bf16 v[96:99], v[120:123], v[216:219], v[96:99]
	v_mfma_f32_16x16x32_bf16 v[80:83], v[120:123], v[224:227], v[80:83]
	v_mfma_f32_16x16x32_bf16 v[80:83], v[112:115], v[220:223], v[80:83]
	v_mfma_f32_16x16x32_bf16 v[76:79], v[152:155], v[220:223], v[76:79]
	v_mfma_f32_16x16x32_bf16 v[76:79], v[156:159], v[224:227], v[76:79]
	v_mfma_f32_16x16x32_bf16 v[92:95], v[156:159], v[216:219], v[92:95]
	v_mfma_f32_16x16x32_bf16 v[92:95], v[152:155], v[212:215], v[92:95]
	v_mfma_f32_16x16x32_bf16 v[108:111], v[152:155], v[204:207], v[108:111]
	v_mfma_f32_16x16x32_bf16 v[108:111], v[156:159], v[208:211], v[108:111]
	v_mfma_f32_16x16x32_bf16 v[132:135], v[156:159], v[188:191], v[132:135]
	v_mfma_f32_16x16x32_bf16 v[132:135], v[152:155], v[184:187], v[132:135]
	v_mfma_f32_16x16x32_bf16 v[128:131], v[160:163], v[184:187], v[128:131]
	v_mfma_f32_16x16x32_bf16 v[128:131], v[164:167], v[188:191], v[128:131]
	v_mfma_f32_16x16x32_bf16 v[104:107], v[164:167], v[208:211], v[104:107]
	v_mfma_f32_16x16x32_bf16 v[104:107], v[160:163], v[204:207], v[104:107]
	v_mfma_f32_16x16x32_bf16 v[88:91], v[160:163], v[212:215], v[88:91]
	v_mfma_f32_16x16x32_bf16 v[88:91], v[164:167], v[216:219], v[88:91]
	v_mfma_f32_16x16x32_bf16 v[72:75], v[164:167], v[224:227], v[72:75]
	v_mfma_f32_16x16x32_bf16 v[72:75], v[160:163], v[220:223], v[72:75]
	v_mfma_f32_16x16x32_bf16 v[68:71], v[176:179], v[220:223], v[68:71]
	v_mfma_f32_16x16x32_bf16 v[68:71], v[180:183], v[224:227], v[68:71]
	v_mfma_f32_16x16x32_bf16 v[84:87], v[180:183], v[216:219], v[84:87]
	v_mfma_f32_16x16x32_bf16 v[84:87], v[176:179], v[212:215], v[84:87]
	v_mfma_f32_16x16x32_bf16 v[100:103], v[176:179], v[204:207], v[100:103]
	v_mfma_f32_16x16x32_bf16 v[100:103], v[180:183], v[208:211], v[100:103]
	v_mfma_f32_16x16x32_bf16 v[124:127], v[180:183], v[188:191], v[124:127]
	v_mfma_f32_16x16x32_bf16 v[124:127], v[176:179], v[184:187], v[124:127]
	s_setprio 0
	s_barrier
	s_add_i32 s50, s56, s46
	s_mov_b32 m0, s50
	ds_read_b128 v[184:187], v173 offset:49152
	ds_read_b128 v[188:191], v173 offset:50176
	ds_read_b128 v[204:207], v173 offset:51200
	ds_read_b128 v[208:211], v173 offset:52224
	ds_read_b128 v[212:215], v173 offset:53248
	ds_read_b128 v[216:219], v173 offset:54272
	ds_read_b128 v[220:223], v173 offset:55296
	ds_read_b128 v[224:227], v173 offset:56320
	s_add_u32 s98, s72, 0x80
	s_addc_u32 s99, s73, 0
	global_load_lds_dwordx4 v2, s[98:99]
	s_add_i32 m0, s50, 0x2000
	s_add_u32 s50, s72, 0x100080
	s_addc_u32 s51, s73, 0
	s_add_i32 s56, s57, s46
	global_load_lds_dwordx4 v144, s[98:99]
	s_mov_b32 m0, s56
	s_nop 0
	global_load_lds_dwordx4 v2, s[50:51]
	s_add_i32 m0, s56, 0x2000
	s_nop 0
	global_load_lds_dwordx4 v144, s[50:51]
	s_cmp_eq_u32 s97, 60
	s_cbranch_scc0 .Ldefer_230_body
	v_lshl_add_u64 v[168:169], v[240:241], 0, s[84:85]
	s_mov_b32 m0, s28
	s_nop 0
	global_load_lds_dwordx4 v[168:169], off
	v_lshl_add_u64 v[168:169], v[242:243], 0, s[84:85]
	s_mov_b32 m0, s65
	s_nop 0
	global_load_lds_dwordx4 v[168:169], off

; #define PG8_STAGE(bufoff, gbase, voff) do { _Pragma("unroll") for (int _i = 0; _i < 2; ++_i) \
;         __builtin_amdgcn_global_load_lds((const unsigned*)((const char*)(gbase) + (voff)[_i]), (PG8_LAS unsigned*)(lds + (bufoff) + ldsw + _i * 8192), 16, 0, 0); } while (0)
; #define PG8_LDA(dst, b, h) do { _Pragma("unroll") for (int m = 0; m < 4; ++m) _Pragma("unroll") for (int k = 0; k < 2; ++k) dst[m][k] = *(const PG8_LAS bf16x8*)(lds + PG8_SA(b, h) + aoff + m * 2048 + k * 1024); } while (0)
; #define PG8_LDB(dst, b, h) do { _Pragma("unroll") for (int n = 0; n < 2; ++n) _Pragma("unroll") for (int k = 0; k < 2; ++k) dst[n][k] = *(const PG8_LAS bf16x8*)(lds + PG8_SB(b, h) + boff + n * 2048 + k * 1024); } while (0)
; #define PG8_WAIT_V(n) asm volatile("s_waitcnt vmcnt(" #n ")" ::: "memory")
; #define PG8_WAIT_L(n) asm volatile("s_waitcnt lgkmcnt(" #n ")" ::: "memory")
; #define PG8_BAR __builtin_amdgcn_s_barrier()
; #define PG8_SCHED __builtin_amdgcn_sched_barrier(0)
; template <class Epi, class Sched, bool ALIGN_EPI = false, bool SP2 = false, bool I8 = false>
; __device__ __forceinline__ void gemm_phase(PG8_LAS unsigned char* lds, const Gemm g, const Sched& S, const Epi& E) {
;     ...
;         const bool has_next = S.next(ui + 1, nxt);
;         const char* nA = has_next ? (const char*)g.A + (size_t)nxt.pm * tstep : cA; const char* nB = has_next ? (const char*)g.Bt + (size_t)nxt.pn * tstep : cB;
;         for (int t = 0; t < nt; t += 2) {
;             const bool last = (t == nt - 2);
;             const char* a1 = cA + (size_t)(t + 1) * kstep;
;             const char* a2 = last ? nA : cA + (size_t)(t + 2) * kstep; const char* b2 = last ? nB : cB + (size_t)(t + 2) * kstep;
;             const char* a3 = a2 + kstep; const char* b3 = b2 + kstep;
;             if (last && has_next) S.a_ready(nxt);
;             if constexpr (SP2) {
;             PG8_LDB(B0, 0, 0); PG8_LDB(B1, 0, 1); PG8_SCHED; PG8_LDA(At, 0, 0); PG8_STAGE(PG8_SA(1, 1), a1 + hstep, voffA);
;             PG8_WAIT_V(8); PG8_WAIT_L(0); PG8_BAR; PG8_MMA(0, 0, At, B0); PG8_MMA(0, 1, At, B1); PG8_BAR; PG8_SCHED;
;             PG8_LDA(At, 0, 1); PG8_STAGE(PG8_SB(0, 0), b2, voffB); PG8_STAGE(PG8_SB(0, 1), b2 + hstep, voffB); PG8_STAGE(PG8_SA(0, 0), a2, voffA);
;             PG8_WAIT_V(8); PG8_WAIT_L(0); PG8_BAR; PG8_MMA(1, 0, At, B0); PG8_MMA(1, 1, At, B1); PG8_BAR; PG8_SCHED;
.LBB0_1455:
	s_ashr_i32 s17, s16, 31
	s_lshl_b64 s[20:21], s[16:17], 21
	s_add_u32 s20, s28, s20
	s_addc_u32 s21, s34, s21
	s_and_b64 s[22:23], s[8:9], exec
	s_cselect_b32 s17, s21, s25
	s_cselect_b32 s51, s20, s24
	s_ashr_i32 s19, s18, 31
	s_lshl_b64 s[22:23], s[18:19], 21
	s_add_u32 s22, s35, s22
	s_addc_u32 s23, s39, s23
	s_and_b64 s[36:37], s[8:9], exec
	s_cselect_b32 s19, s23, s27
	s_cselect_b32 s52, s22, s26
	s_add_u32 s24, s24, 0x100080
	s_addc_u32 s25, s25, 0
	s_add_u32 s53, s26, 0x100
	s_addc_u32 s54, s27, 0
	s_mov_b32 s55, -2
	s_waitcnt vmcnt(0)
	s_add_i32 s56, 0, 0x10000
	s_add_i32 s58, 0, 0x14000
	v_add_u32_e32 v144, s56, v240
	v_add_u32_e32 v160, s58, v240
	ds_read_b128 v[124:127], v144
	ds_read_b128 v[128:131], v144 offset:1024
	ds_read_b128 v[132:135], v144 offset:2048
	ds_read_b128 v[144:147], v144 offset:3072
	ds_read_b128 v[148:151], v160
	ds_read_b128 v[152:155], v160 offset:1024
	ds_read_b128 v[156:159], v160 offset:2048
	ds_read_b128 v[160:163], v160 offset:3072
	s_add_u32 s26, s24, 0xfff00080
	s_addc_u32 s27, s25, -1
	s_cmp_eq_u32 s55, 60
	s_cselect_b32 s37, s17, s27
	s_cselect_b32 s36, s51, s26
	s_cselect_b32 s27, s19, s54
	s_cselect_b32 s26, s52, s53
	s_add_i32 m0, s41, 0xc000
	ds_read_b128 v[164:167], v242
	ds_read_b128 v[168:171], v242 offset:1024
	ds_read_b128 v[172:175], v242 offset:2048
	ds_read_b128 v[176:179], v242 offset:3072
	ds_read_b128 v[180:183], v242 offset:4096
	ds_read_b128 v[184:187], v242 offset:5120
	ds_read_b128 v[188:191], v242 offset:6144
	ds_read_b128 v[214:217], v242 offset:7168
	global_load_lds_dwordx4 v210, s[24:25]
	s_add_i32 m0, s41, 0xe000
	s_nop 0
	global_load_lds_dwordx4 v212, s[24:25]
	s_waitcnt vmcnt(8)
	s_waitcnt lgkmcnt(0)
	s_barrier
	s_setprio 1
	s_waitcnt lgkmcnt(0)
	v_mfma_f32_16x16x32_bf16 v[140:143], v[124:127], v[164:167], 0
	v_mfma_f32_16x16x32_bf16 v[140:143], v[128:131], v[168:171], v[140:143]
	v_mfma_f32_16x16x32_bf16 v[112:115], v[128:131], v[176:179], 0
	v_mfma_f32_16x16x32_bf16 v[112:115], v[124:127], v[172:175], v[112:115]
	v_mfma_f32_16x16x32_bf16 v[96:99], v[124:127], v[180:183], 0
	v_mfma_f32_16x16x32_bf16 v[96:99], v[128:131], v[184:187], v[96:99]
	v_mfma_f32_16x16x32_bf16 v[80:83], v[128:131], v[214:217], 0
	v_mfma_f32_16x16x32_bf16 v[80:83], v[124:127], v[188:191], v[80:83]
	v_mfma_f32_16x16x32_bf16 v[76:79], v[132:135], v[188:191], 0
	v_mfma_f32_16x16x32_bf16 v[76:79], v[144:147], v[214:217], v[76:79]
	v_mfma_f32_16x16x32_bf16 v[92:95], v[144:147], v[184:187], 0
	v_mfma_f32_16x16x32_bf16 v[92:95], v[132:135], v[180:183], v[92:95]
	v_mfma_f32_16x16x32_bf16 v[108:111], v[132:135], v[172:175], 0
	v_mfma_f32_16x16x32_bf16 v[108:111], v[144:147], v[176:179], v[108:111]
	v_mfma_f32_16x16x32_bf16 v[136:139], v[144:147], v[168:171], 0
	v_mfma_f32_16x16x32_bf16 v[136:139], v[132:135], v[164:167], v[136:139]
	v_mfma_f32_16x16x32_bf16 v[120:123], v[148:151], v[164:167], 0
	v_mfma_f32_16x16x32_bf16 v[120:123], v[152:155], v[168:171], v[120:123]
	v_mfma_f32_16x16x32_bf16 v[104:107], v[152:155], v[176:179], 0
	v_mfma_f32_16x16x32_bf16 v[104:107], v[148:151], v[172:175], v[104:107]
	v_mfma_f32_16x16x32_bf16 v[88:91], v[148:151], v[180:183], 0
	v_mfma_f32_16x16x32_bf16 v[88:91], v[152:155], v[184:187], v[88:91]
	v_mfma_f32_16x16x32_bf16 v[72:75], v[152:155], v[214:217], 0
	v_mfma_f32_16x16x32_bf16 v[72:75], v[148:151], v[188:191], v[72:75]
	v_mfma_f32_16x16x32_bf16 v[68:71], v[156:159], v[188:191], 0
	v_mfma_f32_16x16x32_bf16 v[68:71], v[160:163], v[214:217], v[68:71]
	v_mfma_f32_16x16x32_bf16 v[84:87], v[160:163], v[184:187], 0
	v_mfma_f32_16x16x32_bf16 v[84:87], v[156:159], v[180:183], v[84:87]
	v_mfma_f32_16x16x32_bf16 v[100:103], v[156:159], v[172:175], 0
	v_mfma_f32_16x16x32_bf16 v[100:103], v[160:163], v[176:179], v[100:103]
	v_mfma_f32_16x16x32_bf16 v[116:119], v[160:163], v[168:171], 0
	v_mfma_f32_16x16x32_bf16 v[116:119], v[156:159], v[164:167], v[116:119]
	s_setprio 0
	s_barrier
	s_add_i32 s56, s56, s40
	s_mov_b32 m0, s56
	ds_read_b128 v[164:167], v242 offset:16384
	ds_read_b128 v[168:171], v242 offset:17408
	ds_read_b128 v[172:175], v242 offset:18432
	ds_read_b128 v[176:179], v242 offset:19456
	ds_read_b128 v[180:183], v242 offset:20480
	ds_read_b128 v[184:187], v242 offset:21504
	ds_read_b128 v[188:191], v242 offset:22528
	ds_read_b128 v[214:217], v242 offset:23552
	global_load_lds_dwordx4 v2, s[26:27]
	s_add_i32 m0, s56, 0x2000
	s_add_u32 s56, s26, 0x100000
	s_addc_u32 s57, s27, 0
	s_add_i32 s58, s58, s40
	global_load_lds_dwordx4 v204, s[26:27]
	s_mov_b32 m0, s58
	v_lshl_add_u64 v[224:225], s[36:37], 0, v[206:207]
	global_load_lds_dwordx4 v2, s[56:57]
	s_add_i32 m0, s58, 0x2000
	s_nop 0
	global_load_lds_dwordx4 v204, s[56:57]
	v_lshl_add_u64 v[222:223], s[36:37], 0, v[208:209]
	s_waitcnt vmcnt(6)
	s_waitcnt lgkmcnt(0)
	s_barrier
; #define PG8_STAGE(bufoff, gbase, voff) do { _Pragma("unroll") for (int _i = 0; _i < 2; ++_i) \
;         __builtin_amdgcn_global_load_lds((const unsigned*)((const char*)(gbase) + (voff)[_i]), (PG8_LAS unsigned*)(lds + (bufoff) + ldsw + _i * 8192), 16, 0, 0); } while (0)
; #define PG8_LDA(dst, b, h) do { _Pragma("unroll") for (int m = 0; m < 4; ++m) _Pragma("unroll") for (int k = 0; k < 2; ++k) dst[m][k] = *(const PG8_LAS bf16x8*)(lds + PG8_SA(b, h) + aoff + m * 2048 + k * 1024); } while (0)
; #define PG8_LDB(dst, b, h) do { _Pragma("unroll") for (int n = 0; n < 2; ++n) _Pragma("unroll") for (int k = 0; k < 2; ++k) dst[n][k] = *(const PG8_LAS bf16x8*)(lds + PG8_SB(b, h) + boff + n * 2048 + k * 1024); } while (0)
; #define PG8_WAIT_V(n) asm volatile("s_waitcnt vmcnt(" #n ")" ::: "memory")
; #define PG8_WAIT_L(n) asm volatile("s_waitcnt lgkmcnt(" #n ")" ::: "memory")
; #define PG8_BAR __builtin_amdgcn_s_barrier()
; #define PG8_SCHED __builtin_amdgcn_sched_barrier(0)
; template <class Epi, class Sched, bool ALIGN_EPI = false, bool SP2 = false, bool I8 = false>
; __device__ __forceinline__ void gemm_phase(PG8_LAS unsigned char* lds, const Gemm g, const Sched& S, const Epi& E) {
;     ...
;             PG8_WAIT_V(8); PG8_WAIT_L(0); PG8_BAR; PG8_MMA(0, 0, At, B0); PG8_MMA(0, 1, At, B1); PG8_BAR; PG8_SCHED;
;             PG8_LDA(At, 0, 1); PG8_STAGE(PG8_SB(0, 0), b2, voffB); PG8_STAGE(PG8_SB(0, 1), b2 + hstep, voffB); PG8_STAGE(PG8_SA(0, 0), a2, voffA);
;             PG8_WAIT_V(8); PG8_WAIT_L(0); PG8_BAR; PG8_MMA(1, 0, At, B0); PG8_MMA(1, 1, At, B1); PG8_BAR; PG8_SCHED;
;             PG8_LDB(B0, 1, 0); PG8_LDB(B1, 1, 1); PG8_SCHED; PG8_LDA(At, 1, 0); PG8_STAGE(PG8_SA(0, 1), a2 + hstep, voffA);
;             PG8_WAIT_V(8); PG8_WAIT_L(0); PG8_BAR; PG8_MMA(0, 0, At, B0); PG8_MMA(0, 1, At, B1); PG8_BAR; PG8_SCHED;
;             PG8_LDA(At, 1, 1); PG8_STAGE(PG8_SB(1, 0), b3, voffB); PG8_STAGE(PG8_SB(1, 1), b3 + hstep, voffB); PG8_STAGE(PG8_SA(1, 0), a3, voffA);
;             PG8_WAIT_V(8); PG8_WAIT_L(0); PG8_BAR; PG8_MMA(1, 0, At, B0); PG8_MMA(1, 1, At, B1); PG8_BAR; PG8_SCHED;
	s_setprio 1
	s_waitcnt lgkmcnt(0)
	v_mfma_f32_16x16x32_bf16 v[64:67], v[124:127], v[164:167], 0
	v_mfma_f32_16x16x32_bf16 v[64:67], v[128:131], v[168:171], v[64:67]
	v_mfma_f32_16x16x32_bf16 v[48:51], v[128:131], v[176:179], 0
	v_mfma_f32_16x16x32_bf16 v[48:51], v[124:127], v[172:175], v[48:51]
	v_mfma_f32_16x16x32_bf16 v[32:35], v[124:127], v[180:183], 0
	v_mfma_f32_16x16x32_bf16 v[32:35], v[128:131], v[184:187], v[32:35]
	v_mfma_f32_16x16x32_bf16 v[16:19], v[128:131], v[214:217], 0
	v_mfma_f32_16x16x32_bf16 v[16:19], v[124:127], v[188:191], v[16:19]
	v_mfma_f32_16x16x32_bf16 v[12:15], v[132:135], v[188:191], 0
	v_mfma_f32_16x16x32_bf16 v[12:15], v[144:147], v[214:217], v[12:15]
	v_mfma_f32_16x16x32_bf16 v[28:31], v[144:147], v[184:187], 0
	v_mfma_f32_16x16x32_bf16 v[28:31], v[132:135], v[180:183], v[28:31]
	v_mfma_f32_16x16x32_bf16 v[44:47], v[132:135], v[172:175], 0
	v_mfma_f32_16x16x32_bf16 v[44:47], v[144:147], v[176:179], v[44:47]
	v_mfma_f32_16x16x32_bf16 v[60:63], v[144:147], v[168:171], 0
	v_mfma_f32_16x16x32_bf16 v[60:63], v[132:135], v[164:167], v[60:63]
	v_mfma_f32_16x16x32_bf16 v[56:59], v[148:151], v[164:167], 0
	v_mfma_f32_16x16x32_bf16 v[56:59], v[152:155], v[168:171], v[56:59]
	v_mfma_f32_16x16x32_bf16 v[40:43], v[152:155], v[176:179], 0
	v_mfma_f32_16x16x32_bf16 v[40:43], v[148:151], v[172:175], v[40:43]
	v_mfma_f32_16x16x32_bf16 v[24:27], v[148:151], v[180:183], 0
	v_mfma_f32_16x16x32_bf16 v[24:27], v[152:155], v[184:187], v[24:27]
	v_mfma_f32_16x16x32_bf16 v[8:11], v[152:155], v[214:217], 0
	v_mfma_f32_16x16x32_bf16 v[8:11], v[148:151], v[188:191], v[8:11]
	v_mfma_f32_16x16x32_bf16 v[4:7], v[156:159], v[188:191], 0
	v_mfma_f32_16x16x32_bf16 v[4:7], v[160:163], v[214:217], v[4:7]
	v_mfma_f32_16x16x32_bf16 v[20:23], v[160:163], v[184:187], 0
	v_mfma_f32_16x16x32_bf16 v[20:23], v[156:159], v[180:183], v[20:23]
	v_mfma_f32_16x16x32_bf16 v[36:39], v[156:159], v[172:175], 0
	v_mfma_f32_16x16x32_bf16 v[36:39], v[160:163], v[176:179], v[36:39]
	v_mfma_f32_16x16x32_bf16 v[52:55], v[160:163], v[168:171], 0
	v_mfma_f32_16x16x32_bf16 v[52:55], v[156:159], v[164:167], v[52:55]
	s_setprio 0
	s_barrier
	s_mov_b32 m0, s41
	s_nop 0
	global_load_lds_dwordx4 v[222:223], off
	s_mov_b32 m0, s42
	s_nop 0
	global_load_lds_dwordx4 v[224:225], off
	s_add_i32 s56, 0, 0x18000
	s_add_i32 s57, 0, 0x1c000
	v_add_u32_e32 v144, s56, v240
	v_add_u32_e32 v160, s57, v240
	ds_read_b128 v[124:127], v144
	ds_read_b128 v[128:131], v144 offset:1024
	ds_read_b128 v[132:135], v144 offset:2048
	ds_read_b128 v[144:147], v144 offset:3072
	ds_read_b128 v[148:151], v160
	ds_read_b128 v[152:155], v160 offset:1024
	ds_read_b128 v[156:159], v160 offset:2048
	ds_read_b128 v[160:163], v160 offset:3072
	s_add_u32 s36, s36, 0x100000
	s_addc_u32 s37, s37, 0
	s_mov_b32 m0, s43
	ds_read_b128 v[164:167], v242 offset:32768
	ds_read_b128 v[168:171], v242 offset:33792
	ds_read_b128 v[172:175], v242 offset:34816
	ds_read_b128 v[176:179], v242 offset:35840
	ds_read_b128 v[180:183], v242 offset:36864
	ds_read_b128 v[184:187], v242 offset:37888
	ds_read_b128 v[188:191], v242 offset:38912
	ds_read_b128 v[214:217], v242 offset:39936
	global_load_lds_dwordx4 v208, s[36:37]
	s_mov_b32 m0, s44
	s_nop 0
	global_load_lds_dwordx4 v206, s[36:37]
	s_waitcnt vmcnt(8)
	s_waitcnt lgkmcnt(0)
	s_barrier
	s_setprio 1
	s_waitcnt lgkmcnt(0)
	v_mfma_f32_16x16x32_bf16 v[140:143], v[124:127], v[164:167], v[140:143]
	v_mfma_f32_16x16x32_bf16 v[140:143], v[128:131], v[168:171], v[140:143]
	v_mfma_f32_16x16x32_bf16 v[112:115], v[128:131], v[176:179], v[112:115]
	v_mfma_f32_16x16x32_bf16 v[112:115], v[124:127], v[172:175], v[112:115]
	v_mfma_f32_16x16x32_bf16 v[96:99], v[124:127], v[180:183], v[96:99]
	v_mfma_f32_16x16x32_bf16 v[96:99], v[128:131], v[184:187], v[96:99]
	v_mfma_f32_16x16x32_bf16 v[80:83], v[128:131], v[214:217], v[80:83]
	v_mfma_f32_16x16x32_bf16 v[80:83], v[124:127], v[188:191], v[80:83]
	v_mfma_f32_16x16x32_bf16 v[76:79], v[132:135], v[188:191], v[76:79]
	v_mfma_f32_16x16x32_bf16 v[76:79], v[144:147], v[214:217], v[76:79]
	v_mfma_f32_16x16x32_bf16 v[92:95], v[144:147], v[184:187], v[92:95]
	v_mfma_f32_16x16x32_bf16 v[92:95], v[132:135], v[180:183], v[92:95]
	v_mfma_f32_16x16x32_bf16 v[108:111], v[132:135], v[172:175], v[108:111]
	v_mfma_f32_16x16x32_bf16 v[108:111], v[144:147], v[176:179], v[108:111]
	v_mfma_f32_16x16x32_bf16 v[136:139], v[144:147], v[168:171], v[136:139]
	v_mfma_f32_16x16x32_bf16 v[136:139], v[132:135], v[164:167], v[136:139]
	v_mfma_f32_16x16x32_bf16 v[120:123], v[148:151], v[164:167], v[120:123]
	v_mfma_f32_16x16x32_bf16 v[120:123], v[152:155], v[168:171], v[120:123]
	v_mfma_f32_16x16x32_bf16 v[104:107], v[152:155], v[176:179], v[104:107]
	v_mfma_f32_16x16x32_bf16 v[104:107], v[148:151], v[172:175], v[104:107]
	v_mfma_f32_16x16x32_bf16 v[88:91], v[148:151], v[180:183], v[88:91]
	v_mfma_f32_16x16x32_bf16 v[88:91], v[152:155], v[184:187], v[88:91]
	v_mfma_f32_16x16x32_bf16 v[72:75], v[152:155], v[214:217], v[72:75]
	v_mfma_f32_16x16x32_bf16 v[72:75], v[148:151], v[188:191], v[72:75]
	v_mfma_f32_16x16x32_bf16 v[68:71], v[156:159], v[188:191], v[68:71]
	v_mfma_f32_16x16x32_bf16 v[68:71], v[160:163], v[214:217], v[68:71]
	v_mfma_f32_16x16x32_bf16 v[84:87], v[160:163], v[184:187], v[84:87]
	v_mfma_f32_16x16x32_bf16 v[84:87], v[156:159], v[180:183], v[84:87]
	v_mfma_f32_16x16x32_bf16 v[100:103], v[156:159], v[172:175], v[100:103]
	v_mfma_f32_16x16x32_bf16 v[100:103], v[160:163], v[176:179], v[100:103]
	v_mfma_f32_16x16x32_bf16 v[116:119], v[160:163], v[168:171], v[116:119]
	v_mfma_f32_16x16x32_bf16 v[116:119], v[156:159], v[164:167], v[116:119]
	s_setprio 0
	s_barrier
	s_add_i32 s36, s56, s40
	s_mov_b32 m0, s36
	ds_read_b128 v[164:167], v242 offset:49152
	ds_read_b128 v[168:171], v242 offset:50176
	ds_read_b128 v[172:175], v242 offset:51200
	ds_read_b128 v[176:179], v242 offset:52224
	ds_read_b128 v[180:183], v242 offset:53248
	ds_read_b128 v[184:187], v242 offset:54272
	ds_read_b128 v[188:191], v242 offset:55296
	ds_read_b128 v[214:217], v242 offset:56320
	s_add_u32 s98, s26, 0x80
	s_addc_u32 s99, s27, 0
	global_load_lds_dwordx4 v2, s[98:99]
	s_add_i32 m0, s36, 0x2000
	s_add_u32 s26, s26, 0x100080
	s_addc_u32 s27, s27, 0
	s_add_i32 s36, s57, s40
	global_load_lds_dwordx4 v204, s[98:99]
	s_mov_b32 m0, s36
	s_nop 0
	global_load_lds_dwordx4 v2, s[26:27]
	s_add_i32 m0, s36, 0x2000
	s_nop 0
	global_load_lds_dwordx4 v204, s[26:27]
	s_cmp_eq_u32 s55, 60
	s_cbranch_scc0 .Ldefer_1456_peel
	v_lshl_add_u64 v[218:219], v[222:223], 0, s[84:85]
	s_mov_b32 m0, s45
	s_nop 0
	global_load_lds_dwordx4 v[218:219], off
	v_lshl_add_u64 v[218:219], v[224:225], 0, s[84:85]
	s_mov_b32 m0, s46
	s_nop 0
	global_load_lds_dwordx4 v[218:219], off

; #define PG8_STAGE(bufoff, gbase, voff) do { _Pragma("unroll") for (int _i = 0; _i < 2; ++_i) \
;         __builtin_amdgcn_global_load_lds((const unsigned*)((const char*)(gbase) + (voff)[_i]), (PG8_LAS unsigned*)(lds + (bufoff) + ldsw + _i * 8192), 16, 0, 0); } while (0)
; #define PG8_LDA(dst, b, h) do { _Pragma("unroll") for (int m = 0; m < 4; ++m) _Pragma("unroll") for (int k = 0; k < 2; ++k) dst[m][k] = *(const PG8_LAS bf16x8*)(lds + PG8_SA(b, h) + aoff + m * 2048 + k * 1024); } while (0)
; #define PG8_LDB(dst, b, h) do { _Pragma("unroll") for (int n = 0; n < 2; ++n) _Pragma("unroll") for (int k = 0; k < 2; ++k) dst[n][k] = *(const PG8_LAS bf16x8*)(lds + PG8_SB(b, h) + boff + n * 2048 + k * 1024); } while (0)
; #define PG8_WAIT_V(n) asm volatile("s_waitcnt vmcnt(" #n ")" ::: "memory")
; #define PG8_WAIT_L(n) asm volatile("s_waitcnt lgkmcnt(" #n ")" ::: "memory")
; #define PG8_BAR __builtin_amdgcn_s_barrier()
; #define PG8_SCHED __builtin_amdgcn_sched_barrier(0)
; template <class Epi, class Sched, bool ALIGN_EPI = false, bool SP2 = false, bool I8 = false>
; __device__ __forceinline__ void gemm_phase(PG8_LAS unsigned char* lds, const Gemm g, const Sched& S, const Epi& E) {
;     ...
;             const char* a2 = last ? nA : cA + (size_t)(t + 2) * kstep; const char* b2 = last ? nB : cB + (size_t)(t + 2) * kstep;
;             const char* a3 = a2 + kstep; const char* b3 = b2 + kstep;
;             if (last && has_next) S.a_ready(nxt);
;             if constexpr (SP2) {
;             PG8_LDB(B0, 0, 0); PG8_LDB(B1, 0, 1); PG8_SCHED; PG8_LDA(At, 0, 0); PG8_STAGE(PG8_SA(1, 1), a1 + hstep, voffA);
;             PG8_WAIT_V(8); PG8_WAIT_L(0); PG8_BAR; PG8_MMA(0, 0, At, B0); PG8_MMA(0, 1, At, B1); PG8_BAR; PG8_SCHED;
;             PG8_LDA(At, 0, 1); PG8_STAGE(PG8_SB(0, 0), b2, voffB); PG8_STAGE(PG8_SB(0, 1), b2 + hstep, voffB); PG8_STAGE(PG8_SA(0, 0), a2, voffA);
;             PG8_WAIT_V(8); PG8_WAIT_L(0); PG8_BAR; PG8_MMA(1, 0, At, B0); PG8_MMA(1, 1, At, B1); PG8_BAR; PG8_SCHED;
;             PG8_LDB(B0, 1, 0); PG8_LDB(B1, 1, 1); PG8_SCHED; PG8_LDA(At, 1, 0); PG8_STAGE(PG8_SA(0, 1), a2 + hstep, voffA);
;             PG8_WAIT_V(8); PG8_WAIT_L(0); PG8_BAR; PG8_MMA(0, 0, At, B0); PG8_MMA(0, 1, At, B1); PG8_BAR; PG8_SCHED;
.LBB0_1456:
	s_add_i32 s56, 0, 0x10000
	s_add_i32 s58, 0, 0x14000
	v_add_u32_e32 v144, s56, v240
	v_add_u32_e32 v160, s58, v240
	ds_read_b128 v[124:127], v144
	ds_read_b128 v[128:131], v144 offset:1024
	ds_read_b128 v[132:135], v144 offset:2048
	ds_read_b128 v[144:147], v144 offset:3072
	ds_read_b128 v[148:151], v160
	ds_read_b128 v[152:155], v160 offset:1024
	ds_read_b128 v[156:159], v160 offset:2048
	ds_read_b128 v[160:163], v160 offset:3072
	s_add_u32 s26, s24, 0xfff00080
	s_addc_u32 s27, s25, -1
	s_cmp_eq_u32 s55, 60
	s_cselect_b32 s37, s17, s27
	s_cselect_b32 s36, s51, s26
	s_cselect_b32 s27, s19, s54
	s_cselect_b32 s26, s52, s53
	v_lshl_add_u64 v[218:219], v[222:223], 0, s[84:85]
	s_mov_b32 m0, s45
	s_nop 0
	global_load_lds_dwordx4 v[218:219], off
	v_lshl_add_u64 v[218:219], v[224:225], 0, s[84:85]
	s_mov_b32 m0, s46
	s_nop 0
	global_load_lds_dwordx4 v[218:219], off
	s_add_i32 m0, s41, 0xc000
	ds_read_b128 v[164:167], v242
	ds_read_b128 v[168:171], v242 offset:1024
	ds_read_b128 v[172:175], v242 offset:2048
	ds_read_b128 v[176:179], v242 offset:3072
	ds_read_b128 v[180:183], v242 offset:4096
	ds_read_b128 v[184:187], v242 offset:5120
	ds_read_b128 v[188:191], v242 offset:6144
	ds_read_b128 v[214:217], v242 offset:7168
	global_load_lds_dwordx4 v210, s[24:25]
	s_add_i32 m0, s41, 0xe000
	s_nop 0
	global_load_lds_dwordx4 v212, s[24:25]
	s_waitcnt vmcnt(8)
	s_waitcnt lgkmcnt(0)
	s_barrier
	s_setprio 1
	s_waitcnt lgkmcnt(0)
	v_mfma_f32_16x16x32_bf16 v[140:143], v[124:127], v[164:167], v[140:143]
	v_mfma_f32_16x16x32_bf16 v[140:143], v[128:131], v[168:171], v[140:143]
	v_mfma_f32_16x16x32_bf16 v[112:115], v[128:131], v[176:179], v[112:115]
	v_mfma_f32_16x16x32_bf16 v[112:115], v[124:127], v[172:175], v[112:115]
	v_mfma_f32_16x16x32_bf16 v[96:99], v[124:127], v[180:183], v[96:99]
	v_mfma_f32_16x16x32_bf16 v[96:99], v[128:131], v[184:187], v[96:99]
	v_mfma_f32_16x16x32_bf16 v[80:83], v[128:131], v[214:217], v[80:83]
	v_mfma_f32_16x16x32_bf16 v[80:83], v[124:127], v[188:191], v[80:83]
	v_mfma_f32_16x16x32_bf16 v[76:79], v[132:135], v[188:191], v[76:79]
	v_mfma_f32_16x16x32_bf16 v[76:79], v[144:147], v[214:217], v[76:79]
	v_mfma_f32_16x16x32_bf16 v[92:95], v[144:147], v[184:187], v[92:95]
	v_mfma_f32_16x16x32_bf16 v[92:95], v[132:135], v[180:183], v[92:95]
	v_mfma_f32_16x16x32_bf16 v[108:111], v[132:135], v[172:175], v[108:111]
	v_mfma_f32_16x16x32_bf16 v[108:111], v[144:147], v[176:179], v[108:111]
	v_mfma_f32_16x16x32_bf16 v[136:139], v[144:147], v[168:171], v[136:139]
	v_mfma_f32_16x16x32_bf16 v[136:139], v[132:135], v[164:167], v[136:139]
	v_mfma_f32_16x16x32_bf16 v[120:123], v[148:151], v[164:167], v[120:123]
	v_mfma_f32_16x16x32_bf16 v[120:123], v[152:155], v[168:171], v[120:123]
	v_mfma_f32_16x16x32_bf16 v[104:107], v[152:155], v[176:179], v[104:107]
	v_mfma_f32_16x16x32_bf16 v[104:107], v[148:151], v[172:175], v[104:107]
	v_mfma_f32_16x16x32_bf16 v[88:91], v[148:151], v[180:183], v[88:91]
	v_mfma_f32_16x16x32_bf16 v[88:91], v[152:155], v[184:187], v[88:91]
	v_mfma_f32_16x16x32_bf16 v[72:75], v[152:155], v[214:217], v[72:75]
	v_mfma_f32_16x16x32_bf16 v[72:75], v[148:151], v[188:191], v[72:75]
	v_mfma_f32_16x16x32_bf16 v[68:71], v[156:159], v[188:191], v[68:71]
	v_mfma_f32_16x16x32_bf16 v[68:71], v[160:163], v[214:217], v[68:71]
	v_mfma_f32_16x16x32_bf16 v[84:87], v[160:163], v[184:187], v[84:87]
	v_mfma_f32_16x16x32_bf16 v[84:87], v[156:159], v[180:183], v[84:87]
	v_mfma_f32_16x16x32_bf16 v[100:103], v[156:159], v[172:175], v[100:103]
	v_mfma_f32_16x16x32_bf16 v[100:103], v[160:163], v[176:179], v[100:103]
	v_mfma_f32_16x16x32_bf16 v[116:119], v[160:163], v[168:171], v[116:119]
	v_mfma_f32_16x16x32_bf16 v[116:119], v[156:159], v[164:167], v[116:119]
	s_setprio 0
	s_barrier
	s_add_i32 s56, s56, s40
	s_mov_b32 m0, s56
	ds_read_b128 v[164:167], v242 offset:16384
	ds_read_b128 v[168:171], v242 offset:17408
	ds_read_b128 v[172:175], v242 offset:18432
	ds_read_b128 v[176:179], v242 offset:19456
	ds_read_b128 v[180:183], v242 offset:20480
	ds_read_b128 v[184:187], v242 offset:21504
	ds_read_b128 v[188:191], v242 offset:22528
	ds_read_b128 v[214:217], v242 offset:23552
	global_load_lds_dwordx4 v2, s[26:27]
	s_add_i32 m0, s56, 0x2000
	s_add_u32 s56, s26, 0x100000
	s_addc_u32 s57, s27, 0
	s_add_i32 s58, s58, s40
	global_load_lds_dwordx4 v204, s[26:27]
	s_mov_b32 m0, s58
	v_lshl_add_u64 v[224:225], s[36:37], 0, v[206:207]
	global_load_lds_dwordx4 v2, s[56:57]
	s_add_i32 m0, s58, 0x2000
	s_nop 0
	global_load_lds_dwordx4 v204, s[56:57]
	v_lshl_add_u64 v[222:223], s[36:37], 0, v[208:209]
	s_waitcnt vmcnt(6)
	s_waitcnt lgkmcnt(0)
	s_barrier
; #define PG8_STAGE(bufoff, gbase, voff) do { _Pragma("unroll") for (int _i = 0; _i < 2; ++_i) \
;         __builtin_amdgcn_global_load_lds((const unsigned*)((const char*)(gbase) + (voff)[_i]), (PG8_LAS unsigned*)(lds + (bufoff) + ldsw + _i * 8192), 16, 0, 0); } while (0)
; #define PG8_LDA(dst, b, h) do { _Pragma("unroll") for (int m = 0; m < 4; ++m) _Pragma("unroll") for (int k = 0; k < 2; ++k) dst[m][k] = *(const PG8_LAS bf16x8*)(lds + PG8_SA(b, h) + aoff + m * 2048 + k * 1024); } while (0)
; #define PG8_WAIT_V(n) asm volatile("s_waitcnt vmcnt(" #n ")" ::: "memory")
; #define PG8_WAIT_L(n) asm volatile("s_waitcnt lgkmcnt(" #n ")" ::: "memory")
; #define PG8_BAR __builtin_amdgcn_s_barrier()
; #define PG8_SCHED __builtin_amdgcn_sched_barrier(0)
; template <class Epi, class Sched, bool ALIGN_EPI = false, bool SP2 = false, bool I8 = false>
; __device__ __forceinline__ void gemm_phase(PG8_LAS unsigned char* lds, const Gemm g, const Sched& S, const Epi& E) {
;     ...
;             PG8_WAIT_V(8); PG8_WAIT_L(0); PG8_BAR; PG8_MMA(0, 0, At, B0); PG8_MMA(0, 1, At, B1); PG8_BAR; PG8_SCHED;
;             PG8_LDA(At, 1, 1); PG8_STAGE(PG8_SB(1, 0), b3, voffB); PG8_STAGE(PG8_SB(1, 1), b3 + hstep, voffB); PG8_STAGE(PG8_SA(1, 0), a3, voffA);
;             PG8_WAIT_V(8); PG8_WAIT_L(0); PG8_BAR; PG8_MMA(1, 0, At, B0); PG8_MMA(1, 1, At, B1); PG8_BAR; PG8_SCHED;
	s_setprio 1
	s_waitcnt lgkmcnt(0)
	v_mfma_f32_16x16x32_bf16 v[64:67], v[124:127], v[164:167], v[64:67]
	v_mfma_f32_16x16x32_bf16 v[64:67], v[128:131], v[168:171], v[64:67]
	v_mfma_f32_16x16x32_bf16 v[48:51], v[128:131], v[176:179], v[48:51]
	v_mfma_f32_16x16x32_bf16 v[48:51], v[124:127], v[172:175], v[48:51]
	v_mfma_f32_16x16x32_bf16 v[32:35], v[124:127], v[180:183], v[32:35]
	v_mfma_f32_16x16x32_bf16 v[32:35], v[128:131], v[184:187], v[32:35]
	v_mfma_f32_16x16x32_bf16 v[16:19], v[128:131], v[214:217], v[16:19]
	v_mfma_f32_16x16x32_bf16 v[16:19], v[124:127], v[188:191], v[16:19]
	v_mfma_f32_16x16x32_bf16 v[12:15], v[132:135], v[188:191], v[12:15]
	v_mfma_f32_16x16x32_bf16 v[12:15], v[144:147], v[214:217], v[12:15]
	v_mfma_f32_16x16x32_bf16 v[28:31], v[144:147], v[184:187], v[28:31]
	v_mfma_f32_16x16x32_bf16 v[28:31], v[132:135], v[180:183], v[28:31]
	v_mfma_f32_16x16x32_bf16 v[44:47], v[132:135], v[172:175], v[44:47]
	v_mfma_f32_16x16x32_bf16 v[44:47], v[144:147], v[176:179], v[44:47]
	v_mfma_f32_16x16x32_bf16 v[60:63], v[144:147], v[168:171], v[60:63]
	v_mfma_f32_16x16x32_bf16 v[60:63], v[132:135], v[164:167], v[60:63]
	v_mfma_f32_16x16x32_bf16 v[56:59], v[148:151], v[164:167], v[56:59]
	v_mfma_f32_16x16x32_bf16 v[56:59], v[152:155], v[168:171], v[56:59]
	v_mfma_f32_16x16x32_bf16 v[40:43], v[152:155], v[176:179], v[40:43]
	v_mfma_f32_16x16x32_bf16 v[40:43], v[148:151], v[172:175], v[40:43]
	v_mfma_f32_16x16x32_bf16 v[24:27], v[148:151], v[180:183], v[24:27]
	v_mfma_f32_16x16x32_bf16 v[24:27], v[152:155], v[184:187], v[24:27]
	v_mfma_f32_16x16x32_bf16 v[8:11], v[152:155], v[214:217], v[8:11]
	v_mfma_f32_16x16x32_bf16 v[8:11], v[148:151], v[188:191], v[8:11]
	v_mfma_f32_16x16x32_bf16 v[4:7], v[156:159], v[188:191], v[4:7]
	v_mfma_f32_16x16x32_bf16 v[4:7], v[160:163], v[214:217], v[4:7]
	v_mfma_f32_16x16x32_bf16 v[20:23], v[160:163], v[184:187], v[20:23]
	v_mfma_f32_16x16x32_bf16 v[20:23], v[156:159], v[180:183], v[20:23]
	v_mfma_f32_16x16x32_bf16 v[36:39], v[156:159], v[172:175], v[36:39]
	v_mfma_f32_16x16x32_bf16 v[36:39], v[160:163], v[176:179], v[36:39]
	v_mfma_f32_16x16x32_bf16 v[52:55], v[160:163], v[168:171], v[52:55]
	v_mfma_f32_16x16x32_bf16 v[52:55], v[156:159], v[164:167], v[52:55]
	s_setprio 0
	s_barrier
	s_mov_b32 m0, s41
	s_nop 0
	global_load_lds_dwordx4 v[222:223], off
	s_mov_b32 m0, s42
	s_nop 0
	global_load_lds_dwordx4 v[224:225], off
	s_add_i32 s56, 0, 0x18000
	s_add_i32 s57, 0, 0x1c000
	v_add_u32_e32 v144, s56, v240
	v_add_u32_e32 v160, s57, v240
	ds_read_b128 v[124:127], v144
	ds_read_b128 v[128:131], v144 offset:1024
	ds_read_b128 v[132:135], v144 offset:2048
	ds_read_b128 v[144:147], v144 offset:3072
	ds_read_b128 v[148:151], v160
	ds_read_b128 v[152:155], v160 offset:1024
	ds_read_b128 v[156:159], v160 offset:2048
	ds_read_b128 v[160:163], v160 offset:3072
	s_add_u32 s36, s36, 0x100000
	s_addc_u32 s37, s37, 0
	s_mov_b32 m0, s43
	ds_read_b128 v[164:167], v242 offset:32768
	ds_read_b128 v[168:171], v242 offset:33792
	ds_read_b128 v[172:175], v242 offset:34816
	ds_read_b128 v[176:179], v242 offset:35840
	ds_read_b128 v[180:183], v242 offset:36864
	ds_read_b128 v[184:187], v242 offset:37888
	ds_read_b128 v[188:191], v242 offset:38912
	ds_read_b128 v[214:217], v242 offset:39936
	global_load_lds_dwordx4 v208, s[36:37]
	s_mov_b32 m0, s44
	s_nop 0
	global_load_lds_dwordx4 v206, s[36:37]
	s_waitcnt vmcnt(8)
	s_waitcnt lgkmcnt(0)
	s_barrier
	s_setprio 1
	s_waitcnt lgkmcnt(0)
	v_mfma_f32_16x16x32_bf16 v[140:143], v[124:127], v[164:167], v[140:143]
	v_mfma_f32_16x16x32_bf16 v[140:143], v[128:131], v[168:171], v[140:143]
	v_mfma_f32_16x16x32_bf16 v[112:115], v[128:131], v[176:179], v[112:115]
	v_mfma_f32_16x16x32_bf16 v[112:115], v[124:127], v[172:175], v[112:115]
	v_mfma_f32_16x16x32_bf16 v[96:99], v[124:127], v[180:183], v[96:99]
	v_mfma_f32_16x16x32_bf16 v[96:99], v[128:131], v[184:187], v[96:99]
	v_mfma_f32_16x16x32_bf16 v[80:83], v[128:131], v[214:217], v[80:83]
	v_mfma_f32_16x16x32_bf16 v[80:83], v[124:127], v[188:191], v[80:83]
	v_mfma_f32_16x16x32_bf16 v[76:79], v[132:135], v[188:191], v[76:79]
	v_mfma_f32_16x16x32_bf16 v[76:79], v[144:147], v[214:217], v[76:79]
	v_mfma_f32_16x16x32_bf16 v[92:95], v[144:147], v[184:187], v[92:95]
	v_mfma_f32_16x16x32_bf16 v[92:95], v[132:135], v[180:183], v[92:95]
	v_mfma_f32_16x16x32_bf16 v[108:111], v[132:135], v[172:175], v[108:111]
	v_mfma_f32_16x16x32_bf16 v[108:111], v[144:147], v[176:179], v[108:111]
	v_mfma_f32_16x16x32_bf16 v[136:139], v[144:147], v[168:171], v[136:139]
	v_mfma_f32_16x16x32_bf16 v[136:139], v[132:135], v[164:167], v[136:139]
	v_mfma_f32_16x16x32_bf16 v[120:123], v[148:151], v[164:167], v[120:123]
	v_mfma_f32_16x16x32_bf16 v[120:123], v[152:155], v[168:171], v[120:123]
	v_mfma_f32_16x16x32_bf16 v[104:107], v[152:155], v[176:179], v[104:107]
	v_mfma_f32_16x16x32_bf16 v[104:107], v[148:151], v[172:175], v[104:107]
	v_mfma_f32_16x16x32_bf16 v[88:91], v[148:151], v[180:183], v[88:91]
	v_mfma_f32_16x16x32_bf16 v[88:91], v[152:155], v[184:187], v[88:91]
	v_mfma_f32_16x16x32_bf16 v[72:75], v[152:155], v[214:217], v[72:75]
	v_mfma_f32_16x16x32_bf16 v[72:75], v[148:151], v[188:191], v[72:75]
	v_mfma_f32_16x16x32_bf16 v[68:71], v[156:159], v[188:191], v[68:71]
	v_mfma_f32_16x16x32_bf16 v[68:71], v[160:163], v[214:217], v[68:71]
	v_mfma_f32_16x16x32_bf16 v[84:87], v[160:163], v[184:187], v[84:87]
	v_mfma_f32_16x16x32_bf16 v[84:87], v[156:159], v[180:183], v[84:87]
	v_mfma_f32_16x16x32_bf16 v[100:103], v[156:159], v[172:175], v[100:103]
	v_mfma_f32_16x16x32_bf16 v[100:103], v[160:163], v[176:179], v[100:103]
	v_mfma_f32_16x16x32_bf16 v[116:119], v[160:163], v[168:171], v[116:119]
	v_mfma_f32_16x16x32_bf16 v[116:119], v[156:159], v[164:167], v[116:119]
	s_setprio 0
	s_barrier
	s_add_i32 s36, s56, s40
	s_mov_b32 m0, s36
	ds_read_b128 v[164:167], v242 offset:49152
	ds_read_b128 v[168:171], v242 offset:50176
	ds_read_b128 v[172:175], v242 offset:51200
	ds_read_b128 v[176:179], v242 offset:52224
	ds_read_b128 v[180:183], v242 offset:53248
	ds_read_b128 v[184:187], v242 offset:54272
	ds_read_b128 v[188:191], v242 offset:55296
	ds_read_b128 v[214:217], v242 offset:56320
	s_add_u32 s98, s26, 0x80
	s_addc_u32 s99, s27, 0
	global_load_lds_dwordx4 v2, s[98:99]
	s_add_i32 m0, s36, 0x2000
	s_add_u32 s26, s26, 0x100080
	s_addc_u32 s27, s27, 0
	s_add_i32 s36, s57, s40
	global_load_lds_dwordx4 v204, s[98:99]
	s_mov_b32 m0, s36
	s_nop 0
	global_load_lds_dwordx4 v2, s[26:27]
	s_add_i32 m0, s36, 0x2000
	s_nop 0
	global_load_lds_dwordx4 v204, s[26:27]
	s_cmp_eq_u32 s55, 60
	s_cbranch_scc0 .Ldefer_1456_body
	v_lshl_add_u64 v[218:219], v[222:223], 0, s[84:85]
	s_mov_b32 m0, s45
	s_nop 0
	global_load_lds_dwordx4 v[218:219], off
	v_lshl_add_u64 v[218:219], v[224:225], 0, s[84:85]
	s_mov_b32 m0, s46
	s_nop 0
	global_load_lds_dwordx4 v[218:219], off

; #define PG8_STAGE(bufoff, gbase, voff) do { _Pragma("unroll") for (int _i = 0; _i < 2; ++_i) \
;         __builtin_amdgcn_global_load_lds((const unsigned*)((const char*)(gbase) + (voff)[_i]), (PG8_LAS unsigned*)(lds + (bufoff) + ldsw + _i * 8192), 16, 0, 0); } while (0)
; #define PG8_LDA(dst, b, h) do { _Pragma("unroll") for (int m = 0; m < 4; ++m) _Pragma("unroll") for (int k = 0; k < 2; ++k) dst[m][k] = *(const PG8_LAS bf16x8*)(lds + PG8_SA(b, h) + aoff + m * 2048 + k * 1024); } while (0)
; #define PG8_LDB(dst, b, h) do { _Pragma("unroll") for (int n = 0; n < 2; ++n) _Pragma("unroll") for (int k = 0; k < 2; ++k) dst[n][k] = *(const PG8_LAS bf16x8*)(lds + PG8_SB(b, h) + boff + n * 2048 + k * 1024); } while (0)
; #define PG8_WAIT_V(n) asm volatile("s_waitcnt vmcnt(" #n ")" ::: "memory")
; #define PG8_WAIT_L(n) asm volatile("s_waitcnt lgkmcnt(" #n ")" ::: "memory")
; #define PG8_BAR __builtin_amdgcn_s_barrier()
; #define PG8_SCHED __builtin_amdgcn_sched_barrier(0)
; template <class Epi, class Sched, bool ALIGN_EPI = false, bool SP2 = false, bool I8 = false>
; __device__ __forceinline__ void gemm_phase(PG8_LAS unsigned char* lds, const Gemm g, const Sched& S, const Epi& E) {
;     ...
;         const bool has_next = S.next(ui + 1, nxt);
;         const char* nA = has_next ? (const char*)g.A + (size_t)nxt.pm * tstep : cA; const char* nB = has_next ? (const char*)g.Bt + (size_t)nxt.pn * tstep : cB;
;         for (int t = 0; t < nt; t += 2) {
;             const bool last = (t == nt - 2);
;             const char* a1 = cA + (size_t)(t + 1) * kstep;
;             const char* a2 = last ? nA : cA + (size_t)(t + 2) * kstep; const char* b2 = last ? nB : cB + (size_t)(t + 2) * kstep;
;             const char* a3 = a2 + kstep; const char* b3 = b2 + kstep;
;             if (last && has_next) S.a_ready(nxt);
;             if constexpr (SP2) {
;             PG8_LDB(B0, 0, 0); PG8_LDB(B1, 0, 1); PG8_SCHED; PG8_LDA(At, 0, 0); PG8_STAGE(PG8_SA(1, 1), a1 + hstep, voffA);
;             PG8_WAIT_V(8); PG8_WAIT_L(0); PG8_BAR; PG8_MMA(0, 0, At, B0); PG8_MMA(0, 1, At, B1); PG8_BAR; PG8_SCHED;
;             PG8_LDA(At, 0, 1); PG8_STAGE(PG8_SB(0, 0), b2, voffB); PG8_STAGE(PG8_SB(0, 1), b2 + hstep, voffB); PG8_STAGE(PG8_SA(0, 0), a2, voffA);
;             PG8_WAIT_V(8); PG8_WAIT_L(0); PG8_BAR; PG8_MMA(1, 0, At, B0); PG8_MMA(1, 1, At, B1); PG8_BAR; PG8_SCHED;
.LBB0_1590:
	s_ashr_i32 s25, s24, 31
	s_lshl_b64 s[26:27], s[24:25], 20
	s_add_u32 s26, s28, s26
	s_addc_u32 s27, s42, s27
	s_and_b64 s[36:37], s[10:11], exec
	s_cselect_b32 s25, s27, s41
	s_cselect_b32 s57, s26, s40
	s_ashr_i32 s23, s22, 31
	s_lshl_b64 s[36:37], s[22:23], 20
	s_add_u32 s36, s43, s36
	s_addc_u32 s37, s46, s37
	s_and_b64 s[48:49], s[10:11], exec
	s_cselect_b32 s23, s37, s45
	s_cselect_b32 s58, s36, s44
	s_add_u32 s40, s40, 0x80080
	s_addc_u32 s41, s41, 0
	s_add_u32 s59, s44, 0x100
	s_addc_u32 s60, s45, 0
	s_mov_b32 s61, -2
	s_add_i32 s64, 0, 0x10000
	s_add_i32 s67, 0, 0x14000
	v_add_u32_e32 v144, s64, v167
	v_add_u32_e32 v158, s67, v167
	ds_read_b128 v[36:39], v144
	ds_read_b128 v[44:47], v144 offset:1024
	ds_read_b128 v[140:143], v144 offset:2048
	ds_read_b128 v[144:147], v144 offset:3072
	ds_read_b128 v[160:163], v158
	ds_read_b128 v[172:175], v158 offset:1024
	ds_read_b128 v[176:179], v158 offset:2048
	ds_read_b128 v[180:183], v158 offset:3072
	s_add_u32 s44, s40, 0xfff80080
	s_addc_u32 s45, s41, -1
	s_cmp_eq_u32 s61, 28
	s_cselect_b32 s49, s25, s45
	s_cselect_b32 s48, s57, s44
	s_cselect_b32 s45, s23, s60
	s_cselect_b32 s44, s58, s59
	s_add_i32 m0, s50, 0xc000
	ds_read_b128 v[184:187], v171
	ds_read_b128 v[188:191], v171 offset:1024
	ds_read_b128 v[204:207], v171 offset:2048
	ds_read_b128 v[208:211], v171 offset:3072
	ds_read_b128 v[212:215], v171 offset:4096
	ds_read_b128 v[216:219], v171 offset:5120
	ds_read_b128 v[220:223], v171 offset:6144
	ds_read_b128 v[224:227], v171 offset:7168
	global_load_lds_dwordx4 v154, s[40:41]
	s_add_i32 m0, s50, 0xe000
	s_nop 0
	global_load_lds_dwordx4 v156, s[40:41]
	s_waitcnt vmcnt(8)
	s_waitcnt lgkmcnt(0)
	s_barrier
	s_setprio 1
	s_waitcnt lgkmcnt(0)
	v_mfma_i32_16x16x64_i8 v[136:139], v[36:39], v[184:187], 0
	v_mfma_i32_16x16x64_i8 v[136:139], v[44:47], v[188:191], v[136:139]
	v_mfma_i32_16x16x64_i8 v[120:123], v[44:47], v[208:211], 0
	v_mfma_i32_16x16x64_i8 v[120:123], v[36:39], v[204:207], v[120:123]
	v_mfma_i32_16x16x64_i8 v[104:107], v[36:39], v[212:215], 0
	v_mfma_i32_16x16x64_i8 v[104:107], v[44:47], v[216:219], v[104:107]
	v_mfma_i32_16x16x64_i8 v[88:91], v[44:47], v[224:227], 0
	v_mfma_i32_16x16x64_i8 v[88:91], v[36:39], v[220:223], v[88:91]
	v_mfma_i32_16x16x64_i8 v[80:83], v[140:143], v[220:223], 0
	v_mfma_i32_16x16x64_i8 v[80:83], v[144:147], v[224:227], v[80:83]
	v_mfma_i32_16x16x64_i8 v[96:99], v[144:147], v[216:219], 0
	v_mfma_i32_16x16x64_i8 v[96:99], v[140:143], v[212:215], v[96:99]
	v_mfma_i32_16x16x64_i8 v[112:115], v[140:143], v[204:207], 0
	v_mfma_i32_16x16x64_i8 v[112:115], v[144:147], v[208:211], v[112:115]
	v_mfma_i32_16x16x64_i8 v[128:131], v[144:147], v[188:191], 0
	v_mfma_i32_16x16x64_i8 v[128:131], v[140:143], v[184:187], v[128:131]
	v_mfma_i32_16x16x64_i8 v[132:135], v[160:163], v[184:187], 0
	v_mfma_i32_16x16x64_i8 v[132:135], v[172:175], v[188:191], v[132:135]
	v_mfma_i32_16x16x64_i8 v[116:119], v[172:175], v[208:211], 0
	v_mfma_i32_16x16x64_i8 v[116:119], v[160:163], v[204:207], v[116:119]
	v_mfma_i32_16x16x64_i8 v[100:103], v[160:163], v[212:215], 0
	v_mfma_i32_16x16x64_i8 v[100:103], v[172:175], v[216:219], v[100:103]
	v_mfma_i32_16x16x64_i8 v[84:87], v[172:175], v[224:227], 0
	v_mfma_i32_16x16x64_i8 v[84:87], v[160:163], v[220:223], v[84:87]
	v_mfma_i32_16x16x64_i8 v[76:79], v[176:179], v[220:223], 0
	v_mfma_i32_16x16x64_i8 v[76:79], v[180:183], v[224:227], v[76:79]
	v_mfma_i32_16x16x64_i8 v[92:95], v[180:183], v[216:219], 0
	v_mfma_i32_16x16x64_i8 v[92:95], v[176:179], v[212:215], v[92:95]
	v_mfma_i32_16x16x64_i8 v[108:111], v[176:179], v[204:207], 0
	v_mfma_i32_16x16x64_i8 v[108:111], v[180:183], v[208:211], v[108:111]
	v_mfma_i32_16x16x64_i8 v[124:127], v[180:183], v[188:191], 0
	v_mfma_i32_16x16x64_i8 v[124:127], v[176:179], v[184:187], v[124:127]
	s_setprio 0
	s_barrier
	s_add_i32 s64, s64, s47
	s_mov_b32 m0, s64
	ds_read_b128 v[184:187], v171 offset:16384
	ds_read_b128 v[188:191], v171 offset:17408
	ds_read_b128 v[204:207], v171 offset:18432
	ds_read_b128 v[208:211], v171 offset:19456
	ds_read_b128 v[212:215], v171 offset:20480
	ds_read_b128 v[216:219], v171 offset:21504
	ds_read_b128 v[220:223], v171 offset:22528
	ds_read_b128 v[224:227], v171 offset:23552
	global_load_lds_dwordx4 v2, s[44:45]
	s_add_i32 m0, s64, 0x2000
	s_add_u32 s64, s44, 0x80000
	s_addc_u32 s65, s45, 0
	s_add_i32 s67, s67, s47
	global_load_lds_dwordx4 v148, s[44:45]
	s_mov_b32 m0, s67
	v_lshl_add_u64 v[242:243], s[48:49], 0, v[150:151]
	global_load_lds_dwordx4 v2, s[64:65]
	s_add_i32 m0, s67, 0x2000
	s_nop 0
	global_load_lds_dwordx4 v148, s[64:65]
	v_lshl_add_u64 v[240:241], s[48:49], 0, v[152:153]
	s_waitcnt vmcnt(6)
	s_waitcnt lgkmcnt(0)
	s_barrier
; #define PG8_STAGE(bufoff, gbase, voff) do { _Pragma("unroll") for (int _i = 0; _i < 2; ++_i) \
;         __builtin_amdgcn_global_load_lds((const unsigned*)((const char*)(gbase) + (voff)[_i]), (PG8_LAS unsigned*)(lds + (bufoff) + ldsw + _i * 8192), 16, 0, 0); } while (0)
; #define PG8_LDA(dst, b, h) do { _Pragma("unroll") for (int m = 0; m < 4; ++m) _Pragma("unroll") for (int k = 0; k < 2; ++k) dst[m][k] = *(const PG8_LAS bf16x8*)(lds + PG8_SA(b, h) + aoff + m * 2048 + k * 1024); } while (0)
; #define PG8_LDB(dst, b, h) do { _Pragma("unroll") for (int n = 0; n < 2; ++n) _Pragma("unroll") for (int k = 0; k < 2; ++k) dst[n][k] = *(const PG8_LAS bf16x8*)(lds + PG8_SB(b, h) + boff + n * 2048 + k * 1024); } while (0)
; #define PG8_WAIT_V(n) asm volatile("s_waitcnt vmcnt(" #n ")" ::: "memory")
; #define PG8_WAIT_L(n) asm volatile("s_waitcnt lgkmcnt(" #n ")" ::: "memory")
; #define PG8_BAR __builtin_amdgcn_s_barrier()
; #define PG8_SCHED __builtin_amdgcn_sched_barrier(0)
; template <class Epi, class Sched, bool ALIGN_EPI = false, bool SP2 = false, bool I8 = false>
; __device__ __forceinline__ void gemm_phase(PG8_LAS unsigned char* lds, const Gemm g, const Sched& S, const Epi& E) {
;     ...
;             PG8_WAIT_V(8); PG8_WAIT_L(0); PG8_BAR; PG8_MMA(0, 0, At, B0); PG8_MMA(0, 1, At, B1); PG8_BAR; PG8_SCHED;
;             PG8_LDA(At, 0, 1); PG8_STAGE(PG8_SB(0, 0), b2, voffB); PG8_STAGE(PG8_SB(0, 1), b2 + hstep, voffB); PG8_STAGE(PG8_SA(0, 0), a2, voffA);
;             PG8_WAIT_V(8); PG8_WAIT_L(0); PG8_BAR; PG8_MMA(1, 0, At, B0); PG8_MMA(1, 1, At, B1); PG8_BAR; PG8_SCHED;
;             PG8_LDB(B0, 1, 0); PG8_LDB(B1, 1, 1); PG8_SCHED; PG8_LDA(At, 1, 0); PG8_STAGE(PG8_SA(0, 1), a2 + hstep, voffA);
;             PG8_WAIT_V(8); PG8_WAIT_L(0); PG8_BAR; PG8_MMA(0, 0, At, B0); PG8_MMA(0, 1, At, B1); PG8_BAR; PG8_SCHED;
;             PG8_LDA(At, 1, 1); PG8_STAGE(PG8_SB(1, 0), b3, voffB); PG8_STAGE(PG8_SB(1, 1), b3 + hstep, voffB); PG8_STAGE(PG8_SA(1, 0), a3, voffA);
;             PG8_WAIT_V(8); PG8_WAIT_L(0); PG8_BAR; PG8_MMA(1, 0, At, B0); PG8_MMA(1, 1, At, B1); PG8_BAR; PG8_SCHED;
	s_setprio 1
	s_waitcnt lgkmcnt(0)
	v_mfma_i32_16x16x64_i8 v[72:75], v[36:39], v[184:187], 0
	v_mfma_i32_16x16x64_i8 v[72:75], v[44:47], v[188:191], v[72:75]
	v_mfma_i32_16x16x64_i8 v[56:59], v[44:47], v[208:211], 0
	v_mfma_i32_16x16x64_i8 v[56:59], v[36:39], v[204:207], v[56:59]
	v_mfma_i32_16x16x64_i8 v[32:35], v[36:39], v[212:215], 0
	v_mfma_i32_16x16x64_i8 v[32:35], v[44:47], v[216:219], v[32:35]
	v_mfma_i32_16x16x64_i8 v[16:19], v[44:47], v[224:227], 0
	v_mfma_i32_16x16x64_i8 v[16:19], v[36:39], v[220:223], v[16:19]
	v_mfma_i32_16x16x64_i8 v[8:11], v[140:143], v[220:223], 0
	v_mfma_i32_16x16x64_i8 v[8:11], v[144:147], v[224:227], v[8:11]
	v_mfma_i32_16x16x64_i8 v[24:27], v[144:147], v[216:219], 0
	v_mfma_i32_16x16x64_i8 v[24:27], v[140:143], v[212:215], v[24:27]
	v_mfma_i32_16x16x64_i8 v[48:51], v[140:143], v[204:207], 0
	v_mfma_i32_16x16x64_i8 v[48:51], v[144:147], v[208:211], v[48:51]
	v_mfma_i32_16x16x64_i8 v[64:67], v[144:147], v[188:191], 0
	v_mfma_i32_16x16x64_i8 v[64:67], v[140:143], v[184:187], v[64:67]
	v_mfma_i32_16x16x64_i8 v[36:39], v[160:163], v[184:187], 0
	v_mfma_i32_16x16x64_i8 v[36:39], v[172:175], v[188:191], v[36:39]
	v_mfma_i32_16x16x64_i8 v[52:55], v[172:175], v[208:211], 0
	v_mfma_i32_16x16x64_i8 v[52:55], v[160:163], v[204:207], v[52:55]
	v_mfma_i32_16x16x64_i8 v[28:31], v[160:163], v[212:215], 0
	v_mfma_i32_16x16x64_i8 v[28:31], v[172:175], v[216:219], v[28:31]
	v_mfma_i32_16x16x64_i8 v[12:15], v[172:175], v[224:227], 0
	v_mfma_i32_16x16x64_i8 v[12:15], v[160:163], v[220:223], v[12:15]
	v_mfma_i32_16x16x64_i8 v[4:7], v[176:179], v[220:223], 0
	v_mfma_i32_16x16x64_i8 v[4:7], v[180:183], v[224:227], v[4:7]
	v_mfma_i32_16x16x64_i8 v[20:23], v[180:183], v[216:219], 0
	v_mfma_i32_16x16x64_i8 v[20:23], v[176:179], v[212:215], v[20:23]
	v_mfma_i32_16x16x64_i8 v[40:43], v[176:179], v[204:207], 0
	v_mfma_i32_16x16x64_i8 v[40:43], v[180:183], v[208:211], v[40:43]
	v_mfma_i32_16x16x64_i8 v[44:47], v[180:183], v[188:191], 0
	v_mfma_i32_16x16x64_i8 v[44:47], v[176:179], v[184:187], v[44:47]
	s_setprio 0
	s_barrier
	s_mov_b32 m0, s50
	s_nop 0
	global_load_lds_dwordx4 v[240:241], off
	s_mov_b32 m0, s51
	s_nop 0
	global_load_lds_dwordx4 v[242:243], off
	s_add_i32 s64, 0, 0x18000
	s_add_i32 s65, 0, 0x1c000
	v_add_u32_e32 v144, s64, v167
	v_add_u32_e32 v158, s65, v167
	ds_read_b128 v[60:63], v144
	ds_read_b128 v[68:71], v144 offset:1024
	ds_read_b128 v[140:143], v144 offset:2048
	ds_read_b128 v[144:147], v144 offset:3072
	ds_read_b128 v[160:163], v158
	ds_read_b128 v[172:175], v158 offset:1024
	ds_read_b128 v[176:179], v158 offset:2048
	ds_read_b128 v[180:183], v158 offset:3072
	s_add_u32 s48, s48, 0x80000
	s_addc_u32 s49, s49, 0
	s_mov_b32 m0, s52
	ds_read_b128 v[184:187], v171 offset:32768
	ds_read_b128 v[188:191], v171 offset:33792
	ds_read_b128 v[204:207], v171 offset:34816
	ds_read_b128 v[208:211], v171 offset:35840
	ds_read_b128 v[212:215], v171 offset:36864
	ds_read_b128 v[216:219], v171 offset:37888
	ds_read_b128 v[220:223], v171 offset:38912
	ds_read_b128 v[224:227], v171 offset:39936
	global_load_lds_dwordx4 v152, s[48:49]
	s_mov_b32 m0, s53
	s_nop 0
	global_load_lds_dwordx4 v150, s[48:49]
	s_waitcnt vmcnt(8)
	s_waitcnt lgkmcnt(0)
	s_barrier
	s_setprio 1
	s_waitcnt lgkmcnt(0)
	v_mfma_i32_16x16x64_i8 v[136:139], v[60:63], v[184:187], v[136:139]
	v_mfma_i32_16x16x64_i8 v[136:139], v[68:71], v[188:191], v[136:139]
	v_mfma_i32_16x16x64_i8 v[120:123], v[68:71], v[208:211], v[120:123]
	v_mfma_i32_16x16x64_i8 v[120:123], v[60:63], v[204:207], v[120:123]
	v_mfma_i32_16x16x64_i8 v[104:107], v[60:63], v[212:215], v[104:107]
	v_mfma_i32_16x16x64_i8 v[104:107], v[68:71], v[216:219], v[104:107]
	v_mfma_i32_16x16x64_i8 v[88:91], v[68:71], v[224:227], v[88:91]
	v_mfma_i32_16x16x64_i8 v[88:91], v[60:63], v[220:223], v[88:91]
	v_mfma_i32_16x16x64_i8 v[80:83], v[140:143], v[220:223], v[80:83]
	v_mfma_i32_16x16x64_i8 v[80:83], v[144:147], v[224:227], v[80:83]
	v_mfma_i32_16x16x64_i8 v[96:99], v[144:147], v[216:219], v[96:99]
	v_mfma_i32_16x16x64_i8 v[96:99], v[140:143], v[212:215], v[96:99]
	v_mfma_i32_16x16x64_i8 v[112:115], v[140:143], v[204:207], v[112:115]
	v_mfma_i32_16x16x64_i8 v[112:115], v[144:147], v[208:211], v[112:115]
	v_mfma_i32_16x16x64_i8 v[128:131], v[144:147], v[188:191], v[128:131]
	v_mfma_i32_16x16x64_i8 v[128:131], v[140:143], v[184:187], v[128:131]
	v_mfma_i32_16x16x64_i8 v[132:135], v[160:163], v[184:187], v[132:135]
	v_mfma_i32_16x16x64_i8 v[132:135], v[172:175], v[188:191], v[132:135]
	v_mfma_i32_16x16x64_i8 v[116:119], v[172:175], v[208:211], v[116:119]
	v_mfma_i32_16x16x64_i8 v[116:119], v[160:163], v[204:207], v[116:119]
	v_mfma_i32_16x16x64_i8 v[100:103], v[160:163], v[212:215], v[100:103]
	v_mfma_i32_16x16x64_i8 v[100:103], v[172:175], v[216:219], v[100:103]
	v_mfma_i32_16x16x64_i8 v[84:87], v[172:175], v[224:227], v[84:87]
	v_mfma_i32_16x16x64_i8 v[84:87], v[160:163], v[220:223], v[84:87]
	v_mfma_i32_16x16x64_i8 v[76:79], v[176:179], v[220:223], v[76:79]
	v_mfma_i32_16x16x64_i8 v[76:79], v[180:183], v[224:227], v[76:79]
	v_mfma_i32_16x16x64_i8 v[92:95], v[180:183], v[216:219], v[92:95]
	v_mfma_i32_16x16x64_i8 v[92:95], v[176:179], v[212:215], v[92:95]
	v_mfma_i32_16x16x64_i8 v[108:111], v[176:179], v[204:207], v[108:111]
	v_mfma_i32_16x16x64_i8 v[108:111], v[180:183], v[208:211], v[108:111]
	v_mfma_i32_16x16x64_i8 v[124:127], v[180:183], v[188:191], v[124:127]
	v_mfma_i32_16x16x64_i8 v[124:127], v[176:179], v[184:187], v[124:127]
	s_setprio 0
	s_barrier
	s_add_i32 s48, s64, s47
	s_mov_b32 m0, s48
	ds_read_b128 v[184:187], v171 offset:49152
	ds_read_b128 v[188:191], v171 offset:50176
	ds_read_b128 v[204:207], v171 offset:51200
	ds_read_b128 v[208:211], v171 offset:52224
	ds_read_b128 v[212:215], v171 offset:53248
	ds_read_b128 v[216:219], v171 offset:54272
	ds_read_b128 v[220:223], v171 offset:55296
	ds_read_b128 v[224:227], v171 offset:56320
	s_add_u32 s98, s44, 0x80
	s_addc_u32 s99, s45, 0
	global_load_lds_dwordx4 v2, s[98:99]
	s_add_i32 m0, s48, 0x2000
	s_add_u32 s44, s44, 0x80080
	s_addc_u32 s45, s45, 0
	s_add_i32 s48, s65, s47
	global_load_lds_dwordx4 v148, s[98:99]
	s_mov_b32 m0, s48
	s_nop 0
	global_load_lds_dwordx4 v2, s[44:45]
	s_add_i32 m0, s48, 0x2000
	s_nop 0
	global_load_lds_dwordx4 v148, s[44:45]
	s_cmp_eq_u32 s61, 28
	s_cbranch_scc0 .Ldefer_1591_peel
	v_lshl_add_u64 v[164:165], v[240:241], 0, s[84:85]
	s_mov_b32 m0, s54
	s_nop 0
	global_load_lds_dwordx4 v[164:165], off
	v_lshl_add_u64 v[164:165], v[242:243], 0, s[84:85]
	s_mov_b32 m0, s55
	s_nop 0
	global_load_lds_dwordx4 v[164:165], off

; #define PG8_STAGE(bufoff, gbase, voff) do { _Pragma("unroll") for (int _i = 0; _i < 2; ++_i) \
;         __builtin_amdgcn_global_load_lds((const unsigned*)((const char*)(gbase) + (voff)[_i]), (PG8_LAS unsigned*)(lds + (bufoff) + ldsw + _i * 8192), 16, 0, 0); } while (0)
; #define PG8_LDA(dst, b, h) do { _Pragma("unroll") for (int m = 0; m < 4; ++m) _Pragma("unroll") for (int k = 0; k < 2; ++k) dst[m][k] = *(const PG8_LAS bf16x8*)(lds + PG8_SA(b, h) + aoff + m * 2048 + k * 1024); } while (0)
; #define PG8_LDB(dst, b, h) do { _Pragma("unroll") for (int n = 0; n < 2; ++n) _Pragma("unroll") for (int k = 0; k < 2; ++k) dst[n][k] = *(const PG8_LAS bf16x8*)(lds + PG8_SB(b, h) + boff + n * 2048 + k * 1024); } while (0)
; #define PG8_WAIT_V(n) asm volatile("s_waitcnt vmcnt(" #n ")" ::: "memory")
; #define PG8_WAIT_L(n) asm volatile("s_waitcnt lgkmcnt(" #n ")" ::: "memory")
; #define PG8_BAR __builtin_amdgcn_s_barrier()
; #define PG8_SCHED __builtin_amdgcn_sched_barrier(0)
; template <class Epi, class Sched, bool ALIGN_EPI = false, bool SP2 = false, bool I8 = false>
; __device__ __forceinline__ void gemm_phase(PG8_LAS unsigned char* lds, const Gemm g, const Sched& S, const Epi& E) {
;     ...
;             const char* a2 = last ? nA : cA + (size_t)(t + 2) * kstep; const char* b2 = last ? nB : cB + (size_t)(t + 2) * kstep;
;             const char* a3 = a2 + kstep; const char* b3 = b2 + kstep;
;             if (last && has_next) S.a_ready(nxt);
;             if constexpr (SP2) {
;             PG8_LDB(B0, 0, 0); PG8_LDB(B1, 0, 1); PG8_SCHED; PG8_LDA(At, 0, 0); PG8_STAGE(PG8_SA(1, 1), a1 + hstep, voffA);
;             PG8_WAIT_V(8); PG8_WAIT_L(0); PG8_BAR; PG8_MMA(0, 0, At, B0); PG8_MMA(0, 1, At, B1); PG8_BAR; PG8_SCHED;
;             PG8_LDA(At, 0, 1); PG8_STAGE(PG8_SB(0, 0), b2, voffB); PG8_STAGE(PG8_SB(0, 1), b2 + hstep, voffB); PG8_STAGE(PG8_SA(0, 0), a2, voffA);
;             PG8_WAIT_V(8); PG8_WAIT_L(0); PG8_BAR; PG8_MMA(1, 0, At, B0); PG8_MMA(1, 1, At, B1); PG8_BAR; PG8_SCHED;
;             PG8_LDB(B0, 1, 0); PG8_LDB(B1, 1, 1); PG8_SCHED; PG8_LDA(At, 1, 0); PG8_STAGE(PG8_SA(0, 1), a2 + hstep, voffA);
;             PG8_WAIT_V(8); PG8_WAIT_L(0); PG8_BAR; PG8_MMA(0, 0, At, B0); PG8_MMA(0, 1, At, B1); PG8_BAR; PG8_SCHED;
.LBB0_1591:
	s_add_i32 s64, 0, 0x10000
	s_add_i32 s67, 0, 0x14000
	v_add_u32_e32 v144, s64, v167
	v_add_u32_e32 v158, s67, v167
	ds_read_b128 v[36:39], v144
	ds_read_b128 v[44:47], v144 offset:1024
	ds_read_b128 v[140:143], v144 offset:2048
	ds_read_b128 v[144:147], v144 offset:3072
	ds_read_b128 v[160:163], v158
	ds_read_b128 v[172:175], v158 offset:1024
	ds_read_b128 v[176:179], v158 offset:2048
	ds_read_b128 v[180:183], v158 offset:3072
	s_add_u32 s44, s40, 0xfff80080
	s_addc_u32 s45, s41, -1
	s_cmp_eq_u32 s61, 28
	s_cselect_b32 s49, s25, s45
	s_cselect_b32 s48, s57, s44
	s_cselect_b32 s45, s23, s60
	s_cselect_b32 s44, s58, s59
	v_lshl_add_u64 v[164:165], v[240:241], 0, s[84:85]
	s_mov_b32 m0, s54
	s_nop 0
	global_load_lds_dwordx4 v[164:165], off
	v_lshl_add_u64 v[164:165], v[242:243], 0, s[84:85]
	s_mov_b32 m0, s55
	s_nop 0
	global_load_lds_dwordx4 v[164:165], off
	s_add_i32 m0, s50, 0xc000
	ds_read_b128 v[184:187], v171
	ds_read_b128 v[188:191], v171 offset:1024
	ds_read_b128 v[204:207], v171 offset:2048
	ds_read_b128 v[208:211], v171 offset:3072
	ds_read_b128 v[212:215], v171 offset:4096
	ds_read_b128 v[216:219], v171 offset:5120
	ds_read_b128 v[220:223], v171 offset:6144
	ds_read_b128 v[224:227], v171 offset:7168
	global_load_lds_dwordx4 v154, s[40:41]
	s_add_i32 m0, s50, 0xe000
	s_nop 0
	global_load_lds_dwordx4 v156, s[40:41]
	s_waitcnt vmcnt(8)
	s_waitcnt lgkmcnt(0)
	s_barrier
	s_setprio 1
	s_waitcnt lgkmcnt(0)
	v_mfma_i32_16x16x64_i8 v[136:139], v[36:39], v[184:187], v[136:139]
	v_mfma_i32_16x16x64_i8 v[136:139], v[44:47], v[188:191], v[136:139]
	v_mfma_i32_16x16x64_i8 v[120:123], v[44:47], v[208:211], v[120:123]
	v_mfma_i32_16x16x64_i8 v[120:123], v[36:39], v[204:207], v[120:123]
	v_mfma_i32_16x16x64_i8 v[104:107], v[36:39], v[212:215], v[104:107]
	v_mfma_i32_16x16x64_i8 v[104:107], v[44:47], v[216:219], v[104:107]
	v_mfma_i32_16x16x64_i8 v[88:91], v[44:47], v[224:227], v[88:91]
	v_mfma_i32_16x16x64_i8 v[88:91], v[36:39], v[220:223], v[88:91]
	v_mfma_i32_16x16x64_i8 v[80:83], v[140:143], v[220:223], v[80:83]
	v_mfma_i32_16x16x64_i8 v[80:83], v[144:147], v[224:227], v[80:83]
	v_mfma_i32_16x16x64_i8 v[96:99], v[144:147], v[216:219], v[96:99]
	v_mfma_i32_16x16x64_i8 v[96:99], v[140:143], v[212:215], v[96:99]
	v_mfma_i32_16x16x64_i8 v[112:115], v[140:143], v[204:207], v[112:115]
	v_mfma_i32_16x16x64_i8 v[112:115], v[144:147], v[208:211], v[112:115]
	v_mfma_i32_16x16x64_i8 v[128:131], v[144:147], v[188:191], v[128:131]
	v_mfma_i32_16x16x64_i8 v[128:131], v[140:143], v[184:187], v[128:131]
	v_mfma_i32_16x16x64_i8 v[132:135], v[160:163], v[184:187], v[132:135]
	v_mfma_i32_16x16x64_i8 v[132:135], v[172:175], v[188:191], v[132:135]
	v_mfma_i32_16x16x64_i8 v[116:119], v[172:175], v[208:211], v[116:119]
	v_mfma_i32_16x16x64_i8 v[116:119], v[160:163], v[204:207], v[116:119]
	v_mfma_i32_16x16x64_i8 v[100:103], v[160:163], v[212:215], v[100:103]
	v_mfma_i32_16x16x64_i8 v[100:103], v[172:175], v[216:219], v[100:103]
	v_mfma_i32_16x16x64_i8 v[84:87], v[172:175], v[224:227], v[84:87]
	v_mfma_i32_16x16x64_i8 v[84:87], v[160:163], v[220:223], v[84:87]
	v_mfma_i32_16x16x64_i8 v[76:79], v[176:179], v[220:223], v[76:79]
	v_mfma_i32_16x16x64_i8 v[76:79], v[180:183], v[224:227], v[76:79]
	v_mfma_i32_16x16x64_i8 v[92:95], v[180:183], v[216:219], v[92:95]
	v_mfma_i32_16x16x64_i8 v[92:95], v[176:179], v[212:215], v[92:95]
	v_mfma_i32_16x16x64_i8 v[108:111], v[176:179], v[204:207], v[108:111]
	v_mfma_i32_16x16x64_i8 v[108:111], v[180:183], v[208:211], v[108:111]
	v_mfma_i32_16x16x64_i8 v[124:127], v[180:183], v[188:191], v[124:127]
	v_mfma_i32_16x16x64_i8 v[124:127], v[176:179], v[184:187], v[124:127]
	s_setprio 0
	s_barrier
	s_add_i32 s64, s64, s47
	s_mov_b32 m0, s64
	ds_read_b128 v[184:187], v171 offset:16384
	ds_read_b128 v[188:191], v171 offset:17408
	ds_read_b128 v[204:207], v171 offset:18432
	ds_read_b128 v[208:211], v171 offset:19456
	ds_read_b128 v[212:215], v171 offset:20480
	ds_read_b128 v[216:219], v171 offset:21504
	ds_read_b128 v[220:223], v171 offset:22528
	ds_read_b128 v[224:227], v171 offset:23552
	global_load_lds_dwordx4 v2, s[44:45]
	s_add_i32 m0, s64, 0x2000
	s_add_u32 s64, s44, 0x80000
	s_addc_u32 s65, s45, 0
	s_add_i32 s67, s67, s47
	global_load_lds_dwordx4 v148, s[44:45]
	s_mov_b32 m0, s67
	v_lshl_add_u64 v[242:243], s[48:49], 0, v[150:151]
	global_load_lds_dwordx4 v2, s[64:65]
	s_add_i32 m0, s67, 0x2000
	s_nop 0
	global_load_lds_dwordx4 v148, s[64:65]
	v_lshl_add_u64 v[240:241], s[48:49], 0, v[152:153]
	s_waitcnt vmcnt(6)
	s_waitcnt lgkmcnt(0)
	s_barrier
; #define PG8_STAGE(bufoff, gbase, voff) do { _Pragma("unroll") for (int _i = 0; _i < 2; ++_i) \
;         __builtin_amdgcn_global_load_lds((const unsigned*)((const char*)(gbase) + (voff)[_i]), (PG8_LAS unsigned*)(lds + (bufoff) + ldsw + _i * 8192), 16, 0, 0); } while (0)
; #define PG8_LDA(dst, b, h) do { _Pragma("unroll") for (int m = 0; m < 4; ++m) _Pragma("unroll") for (int k = 0; k < 2; ++k) dst[m][k] = *(const PG8_LAS bf16x8*)(lds + PG8_SA(b, h) + aoff + m * 2048 + k * 1024); } while (0)
; #define PG8_WAIT_V(n) asm volatile("s_waitcnt vmcnt(" #n ")" ::: "memory")
; #define PG8_WAIT_L(n) asm volatile("s_waitcnt lgkmcnt(" #n ")" ::: "memory")
; #define PG8_BAR __builtin_amdgcn_s_barrier()
; #define PG8_SCHED __builtin_amdgcn_sched_barrier(0)
; template <class Epi, class Sched, bool ALIGN_EPI = false, bool SP2 = false, bool I8 = false>
; __device__ __forceinline__ void gemm_phase(PG8_LAS unsigned char* lds, const Gemm g, const Sched& S, const Epi& E) {
;     ...
;             PG8_WAIT_V(8); PG8_WAIT_L(0); PG8_BAR; PG8_MMA(0, 0, At, B0); PG8_MMA(0, 1, At, B1); PG8_BAR; PG8_SCHED;
;             PG8_LDA(At, 1, 1); PG8_STAGE(PG8_SB(1, 0), b3, voffB); PG8_STAGE(PG8_SB(1, 1), b3 + hstep, voffB); PG8_STAGE(PG8_SA(1, 0), a3, voffA);
;             PG8_WAIT_V(8); PG8_WAIT_L(0); PG8_BAR; PG8_MMA(1, 0, At, B0); PG8_MMA(1, 1, At, B1); PG8_BAR; PG8_SCHED;
	s_setprio 1
	s_waitcnt lgkmcnt(0)
	v_mfma_i32_16x16x64_i8 v[72:75], v[36:39], v[184:187], v[72:75]
	v_mfma_i32_16x16x64_i8 v[72:75], v[44:47], v[188:191], v[72:75]
	v_mfma_i32_16x16x64_i8 v[56:59], v[44:47], v[208:211], v[56:59]
	v_mfma_i32_16x16x64_i8 v[56:59], v[36:39], v[204:207], v[56:59]
	v_mfma_i32_16x16x64_i8 v[32:35], v[36:39], v[212:215], v[32:35]
	v_mfma_i32_16x16x64_i8 v[32:35], v[44:47], v[216:219], v[32:35]
	v_mfma_i32_16x16x64_i8 v[16:19], v[44:47], v[224:227], v[16:19]
	v_mfma_i32_16x16x64_i8 v[16:19], v[36:39], v[220:223], v[16:19]
	v_mfma_i32_16x16x64_i8 v[8:11], v[140:143], v[220:223], v[8:11]
	v_mfma_i32_16x16x64_i8 v[8:11], v[144:147], v[224:227], v[8:11]
	v_mfma_i32_16x16x64_i8 v[24:27], v[144:147], v[216:219], v[24:27]
	v_mfma_i32_16x16x64_i8 v[24:27], v[140:143], v[212:215], v[24:27]
	v_mfma_i32_16x16x64_i8 v[48:51], v[140:143], v[204:207], v[48:51]
	v_mfma_i32_16x16x64_i8 v[48:51], v[144:147], v[208:211], v[48:51]
	v_mfma_i32_16x16x64_i8 v[64:67], v[144:147], v[188:191], v[64:67]
	v_mfma_i32_16x16x64_i8 v[64:67], v[140:143], v[184:187], v[64:67]
	v_mfma_i32_16x16x64_i8 v[36:39], v[160:163], v[184:187], v[68:71]
	v_mfma_i32_16x16x64_i8 v[36:39], v[172:175], v[188:191], v[36:39]
	v_mfma_i32_16x16x64_i8 v[52:55], v[172:175], v[208:211], v[52:55]
	v_mfma_i32_16x16x64_i8 v[52:55], v[160:163], v[204:207], v[52:55]
	v_mfma_i32_16x16x64_i8 v[28:31], v[160:163], v[212:215], v[28:31]
	v_mfma_i32_16x16x64_i8 v[28:31], v[172:175], v[216:219], v[28:31]
	v_mfma_i32_16x16x64_i8 v[12:15], v[172:175], v[224:227], v[12:15]
	v_mfma_i32_16x16x64_i8 v[12:15], v[160:163], v[220:223], v[12:15]
	v_mfma_i32_16x16x64_i8 v[4:7], v[176:179], v[220:223], v[4:7]
	v_mfma_i32_16x16x64_i8 v[4:7], v[180:183], v[224:227], v[4:7]
	v_mfma_i32_16x16x64_i8 v[20:23], v[180:183], v[216:219], v[20:23]
	v_mfma_i32_16x16x64_i8 v[20:23], v[176:179], v[212:215], v[20:23]
	v_mfma_i32_16x16x64_i8 v[40:43], v[176:179], v[204:207], v[40:43]
	v_mfma_i32_16x16x64_i8 v[40:43], v[180:183], v[208:211], v[40:43]
	v_mfma_i32_16x16x64_i8 v[44:47], v[180:183], v[188:191], v[60:63]
	v_mfma_i32_16x16x64_i8 v[44:47], v[176:179], v[184:187], v[44:47]
	s_setprio 0
	s_barrier
	s_mov_b32 m0, s50
	s_nop 0
	global_load_lds_dwordx4 v[240:241], off
	s_mov_b32 m0, s51
	s_nop 0
	global_load_lds_dwordx4 v[242:243], off
	s_add_i32 s64, 0, 0x18000
	s_add_i32 s65, 0, 0x1c000
	v_add_u32_e32 v144, s64, v167
	v_add_u32_e32 v158, s65, v167
	ds_read_b128 v[60:63], v144
	ds_read_b128 v[68:71], v144 offset:1024
	ds_read_b128 v[140:143], v144 offset:2048
	ds_read_b128 v[144:147], v144 offset:3072
	ds_read_b128 v[160:163], v158
	ds_read_b128 v[172:175], v158 offset:1024
	ds_read_b128 v[176:179], v158 offset:2048
	ds_read_b128 v[180:183], v158 offset:3072
	s_add_u32 s48, s48, 0x80000
	s_addc_u32 s49, s49, 0
	s_mov_b32 m0, s52
	ds_read_b128 v[184:187], v171 offset:32768
	ds_read_b128 v[188:191], v171 offset:33792
	ds_read_b128 v[204:207], v171 offset:34816
	ds_read_b128 v[208:211], v171 offset:35840
	ds_read_b128 v[212:215], v171 offset:36864
	ds_read_b128 v[216:219], v171 offset:37888
	ds_read_b128 v[220:223], v171 offset:38912
	ds_read_b128 v[224:227], v171 offset:39936
	global_load_lds_dwordx4 v152, s[48:49]
	s_mov_b32 m0, s53
	s_nop 0
	global_load_lds_dwordx4 v150, s[48:49]
	s_waitcnt vmcnt(8)
	s_waitcnt lgkmcnt(0)
	s_barrier
	s_setprio 1
	s_waitcnt lgkmcnt(0)
	v_mfma_i32_16x16x64_i8 v[136:139], v[60:63], v[184:187], v[136:139]
	v_mfma_i32_16x16x64_i8 v[136:139], v[68:71], v[188:191], v[136:139]
	v_mfma_i32_16x16x64_i8 v[120:123], v[68:71], v[208:211], v[120:123]
	v_mfma_i32_16x16x64_i8 v[120:123], v[60:63], v[204:207], v[120:123]
	v_mfma_i32_16x16x64_i8 v[104:107], v[60:63], v[212:215], v[104:107]
	v_mfma_i32_16x16x64_i8 v[104:107], v[68:71], v[216:219], v[104:107]
	v_mfma_i32_16x16x64_i8 v[88:91], v[68:71], v[224:227], v[88:91]
	v_mfma_i32_16x16x64_i8 v[88:91], v[60:63], v[220:223], v[88:91]
	v_mfma_i32_16x16x64_i8 v[80:83], v[140:143], v[220:223], v[80:83]
	v_mfma_i32_16x16x64_i8 v[80:83], v[144:147], v[224:227], v[80:83]
	v_mfma_i32_16x16x64_i8 v[96:99], v[144:147], v[216:219], v[96:99]
	v_mfma_i32_16x16x64_i8 v[96:99], v[140:143], v[212:215], v[96:99]
	v_mfma_i32_16x16x64_i8 v[112:115], v[140:143], v[204:207], v[112:115]
	v_mfma_i32_16x16x64_i8 v[112:115], v[144:147], v[208:211], v[112:115]
	v_mfma_i32_16x16x64_i8 v[128:131], v[144:147], v[188:191], v[128:131]
	v_mfma_i32_16x16x64_i8 v[128:131], v[140:143], v[184:187], v[128:131]
	v_mfma_i32_16x16x64_i8 v[132:135], v[160:163], v[184:187], v[132:135]
	v_mfma_i32_16x16x64_i8 v[132:135], v[172:175], v[188:191], v[132:135]
	v_mfma_i32_16x16x64_i8 v[116:119], v[172:175], v[208:211], v[116:119]
	v_mfma_i32_16x16x64_i8 v[116:119], v[160:163], v[204:207], v[116:119]
	v_mfma_i32_16x16x64_i8 v[100:103], v[160:163], v[212:215], v[100:103]
	v_mfma_i32_16x16x64_i8 v[100:103], v[172:175], v[216:219], v[100:103]
	v_mfma_i32_16x16x64_i8 v[84:87], v[172:175], v[224:227], v[84:87]
	v_mfma_i32_16x16x64_i8 v[84:87], v[160:163], v[220:223], v[84:87]
	v_mfma_i32_16x16x64_i8 v[76:79], v[176:179], v[220:223], v[76:79]
	v_mfma_i32_16x16x64_i8 v[76:79], v[180:183], v[224:227], v[76:79]
	v_mfma_i32_16x16x64_i8 v[92:95], v[180:183], v[216:219], v[92:95]
	v_mfma_i32_16x16x64_i8 v[92:95], v[176:179], v[212:215], v[92:95]
	v_mfma_i32_16x16x64_i8 v[108:111], v[176:179], v[204:207], v[108:111]
	v_mfma_i32_16x16x64_i8 v[108:111], v[180:183], v[208:211], v[108:111]
	v_mfma_i32_16x16x64_i8 v[124:127], v[180:183], v[188:191], v[124:127]
	v_mfma_i32_16x16x64_i8 v[124:127], v[176:179], v[184:187], v[124:127]
	s_setprio 0
	s_barrier
	s_add_i32 s48, s64, s47
	s_mov_b32 m0, s48
	ds_read_b128 v[184:187], v171 offset:49152
	ds_read_b128 v[188:191], v171 offset:50176
	ds_read_b128 v[204:207], v171 offset:51200
	ds_read_b128 v[208:211], v171 offset:52224
	ds_read_b128 v[212:215], v171 offset:53248
	ds_read_b128 v[216:219], v171 offset:54272
	ds_read_b128 v[220:223], v171 offset:55296
	ds_read_b128 v[224:227], v171 offset:56320
	s_add_u32 s98, s44, 0x80
	s_addc_u32 s99, s45, 0
	global_load_lds_dwordx4 v2, s[98:99]
	s_add_i32 m0, s48, 0x2000
	s_add_u32 s44, s44, 0x80080
	s_addc_u32 s45, s45, 0
	s_add_i32 s48, s65, s47
	global_load_lds_dwordx4 v148, s[98:99]
	s_mov_b32 m0, s48
	s_nop 0
	global_load_lds_dwordx4 v2, s[44:45]
	s_add_i32 m0, s48, 0x2000
	s_nop 0
	global_load_lds_dwordx4 v148, s[44:45]
	s_cmp_eq_u32 s61, 28
	s_cbranch_scc0 .Ldefer_1591_body
	v_lshl_add_u64 v[164:165], v[240:241], 0, s[84:85]
	s_mov_b32 m0, s54
	s_nop 0
	global_load_lds_dwordx4 v[164:165], off
	v_lshl_add_u64 v[164:165], v[242:243], 0, s[84:85]
	s_mov_b32 m0, s55
	s_nop 0
	global_load_lds_dwordx4 v[164:165], off

; #define PG8_STAGE(bufoff, gbase, voff) do { _Pragma("unroll") for (int _i = 0; _i < 2; ++_i) \
;         __builtin_amdgcn_global_load_lds((const unsigned*)((const char*)(gbase) + (voff)[_i]), (PG8_LAS unsigned*)(lds + (bufoff) + ldsw + _i * 8192), 16, 0, 0); } while (0)
; #define PG8_LDA(dst, b, h) do { _Pragma("unroll") for (int m = 0; m < 4; ++m) _Pragma("unroll") for (int k = 0; k < 2; ++k) dst[m][k] = *(const PG8_LAS bf16x8*)(lds + PG8_SA(b, h) + aoff + m * 2048 + k * 1024); } while (0)
; #define PG8_LDB(dst, b, h) do { _Pragma("unroll") for (int n = 0; n < 2; ++n) _Pragma("unroll") for (int k = 0; k < 2; ++k) dst[n][k] = *(const PG8_LAS bf16x8*)(lds + PG8_SB(b, h) + boff + n * 2048 + k * 1024); } while (0)
; template <class Epi, class Sched, bool ALIGN_EPI = false, bool SP2 = false, bool I8 = false>
; __device__ __forceinline__ void gemm_phase(PG8_LAS unsigned char* lds, const Gemm g, const Sched& S, const Epi& E) {
;     ...
;         const bool has_next = S.next(ui + 1, nxt);
;         const char* nA = has_next ? (const char*)g.A + (size_t)nxt.pm * tstep : cA; const char* nB = has_next ? (const char*)g.Bt + (size_t)nxt.pn * tstep : cB;
;         for (int t = 0; t < nt; t += 2) {
;             const bool last = (t == nt - 2);
;             const char* a1 = cA + (size_t)(t + 1) * kstep;
;             const char* a2 = last ? nA : cA + (size_t)(t + 2) * kstep; const char* b2 = last ? nB : cB + (size_t)(t + 2) * kstep;
;             const char* a3 = a2 + kstep; const char* b3 = b2 + kstep;
;             if (last && has_next) S.a_ready(nxt);
;             if constexpr (SP2) {
;             PG8_LDB(B0, 0, 0); PG8_LDB(B1, 0, 1); PG8_SCHED; PG8_LDA(At, 0, 0); PG8_STAGE(PG8_SA(1, 1), a1 + hstep, voffA);
;             PG8_WAIT_V(8); PG8_WAIT_L(0); PG8_BAR; PG8_MMA(0, 0, At, B0); PG8_MMA(0, 1, At, B1); PG8_BAR; PG8_SCHED;
;             PG8_LDA(At, 0, 1); PG8_STAGE(PG8_SB(0, 0), b2, voffB); PG8_STAGE(PG8_SB(0, 1), b2 + hstep, voffB); PG8_STAGE(PG8_SA(0, 0), a2, voffA);
;             PG8_WAIT_V(8); PG8_WAIT_L(0); PG8_BAR; PG8_MMA(1, 0, At, B0); PG8_MMA(1, 1, At, B1); PG8_BAR; PG8_SCHED;
;             PG8_LDB(B0, 1, 0); PG8_LDB(B1, 1, 1); PG8_SCHED; PG8_LDA(At, 1, 0); PG8_STAGE(PG8_SA(0, 1), a2 + hstep, voffA);
;             PG8_WAIT_V(8); PG8_WAIT_L(0); PG8_BAR; PG8_MMA(0, 0, At, B0); PG8_MMA(0, 1, At, B1); PG8_BAR; PG8_SCHED;
.LBB0_1699:
	s_add_u32 s53, s24, 0x100
	s_addc_u32 s54, s25, 0
	s_mov_b32 s55, -2
	s_add_i32 s56, 0, 0x10000
	s_add_i32 s57, 0, 0x14000
	v_add_u32_e32 v144, s56, v240
	v_add_u32_e32 v160, s57, v240
	ds_read_b128 v[124:127], v144
	ds_read_b128 v[128:131], v144 offset:1024
	ds_read_b128 v[132:135], v144 offset:2048
	ds_read_b128 v[144:147], v144 offset:3072
	ds_read_b128 v[148:151], v160
	ds_read_b128 v[152:155], v160 offset:1024
	ds_read_b128 v[156:159], v160 offset:2048
	ds_read_b128 v[160:163], v160 offset:3072
	s_add_u32 s24, s22, 0x100
	s_addc_u32 s25, s23, 0
	s_cmpk_eq_i32 s55, 0xa8
	s_cselect_b32 s37, s13, s25
	s_cselect_b32 s36, s12, s24
	s_cselect_b32 s27, s21, s54
	s_cselect_b32 s26, s20, s53
	v_lshl_add_u64 v[218:219], s[22:23], 0, v[210:211]
	s_add_i32 m0, s42, 0xc000
	ds_read_b128 v[164:167], v242
	ds_read_b128 v[168:171], v242 offset:1024
	ds_read_b128 v[172:175], v242 offset:2048
	ds_read_b128 v[176:179], v242 offset:3072
	ds_read_b128 v[180:183], v242 offset:4096
	ds_read_b128 v[184:187], v242 offset:5120
	ds_read_b128 v[188:191], v242 offset:6144
	ds_read_b128 v[214:217], v242 offset:7168
	global_load_lds_dwordx4 v[218:219], off
	v_lshl_add_u64 v[218:219], s[22:23], 0, v[212:213]
	s_add_i32 m0, s42, 0xe000
	s_nop 0
	global_load_lds_dwordx4 v[218:219], off
	s_waitcnt vmcnt(8)
	s_waitcnt lgkmcnt(0)
	s_barrier
	s_setprio 1
	s_waitcnt lgkmcnt(0)
	v_mfma_f32_16x16x32_bf16 v[140:143], v[124:127], v[164:167], 0
	v_mfma_f32_16x16x32_bf16 v[140:143], v[128:131], v[168:171], v[140:143]
	v_mfma_f32_16x16x32_bf16 v[112:115], v[128:131], v[176:179], 0
	v_mfma_f32_16x16x32_bf16 v[112:115], v[124:127], v[172:175], v[112:115]
	v_mfma_f32_16x16x32_bf16 v[96:99], v[124:127], v[180:183], 0
	v_mfma_f32_16x16x32_bf16 v[96:99], v[128:131], v[184:187], v[96:99]
	v_mfma_f32_16x16x32_bf16 v[80:83], v[128:131], v[214:217], 0
	v_mfma_f32_16x16x32_bf16 v[80:83], v[124:127], v[188:191], v[80:83]
	v_mfma_f32_16x16x32_bf16 v[76:79], v[132:135], v[188:191], 0
	v_mfma_f32_16x16x32_bf16 v[76:79], v[144:147], v[214:217], v[76:79]
	v_mfma_f32_16x16x32_bf16 v[92:95], v[144:147], v[184:187], 0
	v_mfma_f32_16x16x32_bf16 v[92:95], v[132:135], v[180:183], v[92:95]
	v_mfma_f32_16x16x32_bf16 v[108:111], v[132:135], v[172:175], 0
	v_mfma_f32_16x16x32_bf16 v[108:111], v[144:147], v[176:179], v[108:111]
	v_mfma_f32_16x16x32_bf16 v[136:139], v[144:147], v[168:171], 0
	v_mfma_f32_16x16x32_bf16 v[136:139], v[132:135], v[164:167], v[136:139]
	v_mfma_f32_16x16x32_bf16 v[120:123], v[148:151], v[164:167], 0
	v_mfma_f32_16x16x32_bf16 v[120:123], v[152:155], v[168:171], v[120:123]
	v_mfma_f32_16x16x32_bf16 v[104:107], v[152:155], v[176:179], 0
	v_mfma_f32_16x16x32_bf16 v[104:107], v[148:151], v[172:175], v[104:107]
	v_mfma_f32_16x16x32_bf16 v[88:91], v[148:151], v[180:183], 0
	v_mfma_f32_16x16x32_bf16 v[88:91], v[152:155], v[184:187], v[88:91]
	v_mfma_f32_16x16x32_bf16 v[72:75], v[152:155], v[214:217], 0
	v_mfma_f32_16x16x32_bf16 v[72:75], v[148:151], v[188:191], v[72:75]
	v_mfma_f32_16x16x32_bf16 v[68:71], v[156:159], v[188:191], 0
	v_mfma_f32_16x16x32_bf16 v[68:71], v[160:163], v[214:217], v[68:71]
	v_mfma_f32_16x16x32_bf16 v[84:87], v[160:163], v[184:187], 0
	v_mfma_f32_16x16x32_bf16 v[84:87], v[156:159], v[180:183], v[84:87]
	v_mfma_f32_16x16x32_bf16 v[100:103], v[156:159], v[172:175], 0
	v_mfma_f32_16x16x32_bf16 v[100:103], v[160:163], v[176:179], v[100:103]
	v_mfma_f32_16x16x32_bf16 v[116:119], v[160:163], v[168:171], 0
	v_mfma_f32_16x16x32_bf16 v[116:119], v[156:159], v[164:167], v[116:119]
	s_setprio 0
	s_barrier
	s_add_i32 s22, s56, s41
	s_mov_b32 m0, s22
	ds_read_b128 v[164:167], v242 offset:16384
	ds_read_b128 v[168:171], v242 offset:17408
	ds_read_b128 v[172:175], v242 offset:18432
	ds_read_b128 v[176:179], v242 offset:19456
	ds_read_b128 v[180:183], v242 offset:20480
	ds_read_b128 v[184:187], v242 offset:21504
	ds_read_b128 v[188:191], v242 offset:22528
	ds_read_b128 v[214:217], v242 offset:23552
	global_load_lds_dwordx4 v2, s[26:27]
	s_add_i32 m0, s22, 0x2000
	s_add_u32 s22, s26, 0x2b0000
	s_addc_u32 s23, s27, 0
	s_add_i32 s56, s57, s41
	global_load_lds_dwordx4 v204, s[26:27]
	s_mov_b32 m0, s56
	v_lshl_add_u64 v[224:225], s[36:37], 0, v[206:207]
	global_load_lds_dwordx4 v2, s[22:23]
	s_add_i32 m0, s56, 0x2000
	s_nop 0
	global_load_lds_dwordx4 v204, s[22:23]
	v_lshl_add_u64 v[222:223], s[36:37], 0, v[208:209]
	s_waitcnt vmcnt(6)
	s_waitcnt lgkmcnt(0)
	s_barrier
	s_setprio 1
	s_waitcnt lgkmcnt(0)
	v_mfma_f32_16x16x32_bf16 v[64:67], v[124:127], v[164:167], 0
	v_mfma_f32_16x16x32_bf16 v[64:67], v[128:131], v[168:171], v[64:67]
	v_mfma_f32_16x16x32_bf16 v[48:51], v[128:131], v[176:179], 0
	v_mfma_f32_16x16x32_bf16 v[48:51], v[124:127], v[172:175], v[48:51]
	v_mfma_f32_16x16x32_bf16 v[32:35], v[124:127], v[180:183], 0
	v_mfma_f32_16x16x32_bf16 v[32:35], v[128:131], v[184:187], v[32:35]
	v_mfma_f32_16x16x32_bf16 v[16:19], v[128:131], v[214:217], 0
	v_mfma_f32_16x16x32_bf16 v[16:19], v[124:127], v[188:191], v[16:19]
	v_mfma_f32_16x16x32_bf16 v[12:15], v[132:135], v[188:191], 0
	v_mfma_f32_16x16x32_bf16 v[12:15], v[144:147], v[214:217], v[12:15]
	v_mfma_f32_16x16x32_bf16 v[28:31], v[144:147], v[184:187], 0
	v_mfma_f32_16x16x32_bf16 v[28:31], v[132:135], v[180:183], v[28:31]
	v_mfma_f32_16x16x32_bf16 v[44:47], v[132:135], v[172:175], 0
	v_mfma_f32_16x16x32_bf16 v[44:47], v[144:147], v[176:179], v[44:47]
	v_mfma_f32_16x16x32_bf16 v[60:63], v[144:147], v[168:171], 0
	v_mfma_f32_16x16x32_bf16 v[60:63], v[132:135], v[164:167], v[60:63]
	v_mfma_f32_16x16x32_bf16 v[56:59], v[148:151], v[164:167], 0
	v_mfma_f32_16x16x32_bf16 v[56:59], v[152:155], v[168:171], v[56:59]
	v_mfma_f32_16x16x32_bf16 v[40:43], v[152:155], v[176:179], 0
	v_mfma_f32_16x16x32_bf16 v[40:43], v[148:151], v[172:175], v[40:43]
	v_mfma_f32_16x16x32_bf16 v[24:27], v[148:151], v[180:183], 0
	v_mfma_f32_16x16x32_bf16 v[24:27], v[152:155], v[184:187], v[24:27]
	v_mfma_f32_16x16x32_bf16 v[8:11], v[152:155], v[214:217], 0
	v_mfma_f32_16x16x32_bf16 v[8:11], v[148:151], v[188:191], v[8:11]
	v_mfma_f32_16x16x32_bf16 v[4:7], v[156:159], v[188:191], 0
	v_mfma_f32_16x16x32_bf16 v[4:7], v[160:163], v[214:217], v[4:7]
	v_mfma_f32_16x16x32_bf16 v[20:23], v[160:163], v[184:187], 0
	v_mfma_f32_16x16x32_bf16 v[20:23], v[156:159], v[180:183], v[20:23]
	v_mfma_f32_16x16x32_bf16 v[36:39], v[156:159], v[172:175], 0
	v_mfma_f32_16x16x32_bf16 v[36:39], v[160:163], v[176:179], v[36:39]
	v_mfma_f32_16x16x32_bf16 v[52:55], v[160:163], v[168:171], 0
	v_mfma_f32_16x16x32_bf16 v[52:55], v[156:159], v[164:167], v[52:55]
	s_setprio 0
	s_barrier
; #define PG8_STAGE(bufoff, gbase, voff) do { _Pragma("unroll") for (int _i = 0; _i < 2; ++_i) \
;         __builtin_amdgcn_global_load_lds((const unsigned*)((const char*)(gbase) + (voff)[_i]), (PG8_LAS unsigned*)(lds + (bufoff) + ldsw + _i * 8192), 16, 0, 0); } while (0)
; #define PG8_LDA(dst, b, h) do { _Pragma("unroll") for (int m = 0; m < 4; ++m) _Pragma("unroll") for (int k = 0; k < 2; ++k) dst[m][k] = *(const PG8_LAS bf16x8*)(lds + PG8_SA(b, h) + aoff + m * 2048 + k * 1024); } while (0)
; #define PG8_WAIT_V(n) asm volatile("s_waitcnt vmcnt(" #n ")" ::: "memory")
; #define PG8_WAIT_L(n) asm volatile("s_waitcnt lgkmcnt(" #n ")" ::: "memory")
; #define PG8_BAR __builtin_amdgcn_s_barrier()
; #define PG8_SCHED __builtin_amdgcn_sched_barrier(0)
; template <class Epi, class Sched, bool ALIGN_EPI = false, bool SP2 = false, bool I8 = false>
; __device__ __forceinline__ void gemm_phase(PG8_LAS unsigned char* lds, const Gemm g, const Sched& S, const Epi& E) {
;     ...
;             PG8_WAIT_V(8); PG8_WAIT_L(0); PG8_BAR; PG8_MMA(0, 0, At, B0); PG8_MMA(0, 1, At, B1); PG8_BAR; PG8_SCHED;
;             PG8_LDA(At, 1, 1); PG8_STAGE(PG8_SB(1, 0), b3, voffB); PG8_STAGE(PG8_SB(1, 1), b3 + hstep, voffB); PG8_STAGE(PG8_SA(1, 0), a3, voffA);
;             PG8_WAIT_V(8); PG8_WAIT_L(0); PG8_BAR; PG8_MMA(1, 0, At, B0); PG8_MMA(1, 1, At, B1); PG8_BAR; PG8_SCHED;
	s_mov_b32 m0, s42
	s_nop 0
	global_load_lds_dwordx4 v[222:223], off
	s_mov_b32 m0, s43
	s_nop 0
	global_load_lds_dwordx4 v[224:225], off
	s_add_i32 s56, 0, 0x18000
	s_add_i32 s57, 0, 0x1c000
	v_add_u32_e32 v144, s56, v240
	v_add_u32_e32 v160, s57, v240
	ds_read_b128 v[124:127], v144
	ds_read_b128 v[128:131], v144 offset:1024
	ds_read_b128 v[132:135], v144 offset:2048
	ds_read_b128 v[144:147], v144 offset:3072
	ds_read_b128 v[148:151], v160
	ds_read_b128 v[152:155], v160 offset:1024
	ds_read_b128 v[156:159], v160 offset:2048
	ds_read_b128 v[160:163], v160 offset:3072
	s_add_u32 s22, s36, 0x2b0000
	s_addc_u32 s23, s37, 0
	s_mov_b32 m0, s44
	ds_read_b128 v[164:167], v242 offset:32768
	ds_read_b128 v[168:171], v242 offset:33792
	ds_read_b128 v[172:175], v242 offset:34816
	ds_read_b128 v[176:179], v242 offset:35840
	ds_read_b128 v[180:183], v242 offset:36864
	ds_read_b128 v[184:187], v242 offset:37888
	ds_read_b128 v[188:191], v242 offset:38912
	ds_read_b128 v[214:217], v242 offset:39936
	global_load_lds_dwordx4 v208, s[22:23]
	s_mov_b32 m0, s45
	s_nop 0
	global_load_lds_dwordx4 v206, s[22:23]
	s_waitcnt vmcnt(8)
	s_waitcnt lgkmcnt(0)
	s_barrier
	s_setprio 1
	s_waitcnt lgkmcnt(0)
	v_mfma_f32_16x16x32_bf16 v[140:143], v[124:127], v[164:167], v[140:143]
	v_mfma_f32_16x16x32_bf16 v[140:143], v[128:131], v[168:171], v[140:143]
	v_mfma_f32_16x16x32_bf16 v[112:115], v[128:131], v[176:179], v[112:115]
	v_mfma_f32_16x16x32_bf16 v[112:115], v[124:127], v[172:175], v[112:115]
	v_mfma_f32_16x16x32_bf16 v[96:99], v[124:127], v[180:183], v[96:99]
	v_mfma_f32_16x16x32_bf16 v[96:99], v[128:131], v[184:187], v[96:99]
	v_mfma_f32_16x16x32_bf16 v[80:83], v[128:131], v[214:217], v[80:83]
	v_mfma_f32_16x16x32_bf16 v[80:83], v[124:127], v[188:191], v[80:83]
	v_mfma_f32_16x16x32_bf16 v[76:79], v[132:135], v[188:191], v[76:79]
	v_mfma_f32_16x16x32_bf16 v[76:79], v[144:147], v[214:217], v[76:79]
	v_mfma_f32_16x16x32_bf16 v[92:95], v[144:147], v[184:187], v[92:95]
	v_mfma_f32_16x16x32_bf16 v[92:95], v[132:135], v[180:183], v[92:95]
	v_mfma_f32_16x16x32_bf16 v[108:111], v[132:135], v[172:175], v[108:111]
	v_mfma_f32_16x16x32_bf16 v[108:111], v[144:147], v[176:179], v[108:111]
	v_mfma_f32_16x16x32_bf16 v[136:139], v[144:147], v[168:171], v[136:139]
	v_mfma_f32_16x16x32_bf16 v[136:139], v[132:135], v[164:167], v[136:139]
	v_mfma_f32_16x16x32_bf16 v[120:123], v[148:151], v[164:167], v[120:123]
	v_mfma_f32_16x16x32_bf16 v[120:123], v[152:155], v[168:171], v[120:123]
	v_mfma_f32_16x16x32_bf16 v[104:107], v[152:155], v[176:179], v[104:107]
	v_mfma_f32_16x16x32_bf16 v[104:107], v[148:151], v[172:175], v[104:107]
	v_mfma_f32_16x16x32_bf16 v[88:91], v[148:151], v[180:183], v[88:91]
	v_mfma_f32_16x16x32_bf16 v[88:91], v[152:155], v[184:187], v[88:91]
	v_mfma_f32_16x16x32_bf16 v[72:75], v[152:155], v[214:217], v[72:75]
	v_mfma_f32_16x16x32_bf16 v[72:75], v[148:151], v[188:191], v[72:75]
	v_mfma_f32_16x16x32_bf16 v[68:71], v[156:159], v[188:191], v[68:71]
	v_mfma_f32_16x16x32_bf16 v[68:71], v[160:163], v[214:217], v[68:71]
	v_mfma_f32_16x16x32_bf16 v[84:87], v[160:163], v[184:187], v[84:87]
	v_mfma_f32_16x16x32_bf16 v[84:87], v[156:159], v[180:183], v[84:87]
	v_mfma_f32_16x16x32_bf16 v[100:103], v[156:159], v[172:175], v[100:103]
	v_mfma_f32_16x16x32_bf16 v[100:103], v[160:163], v[176:179], v[100:103]
	v_mfma_f32_16x16x32_bf16 v[116:119], v[160:163], v[168:171], v[116:119]
	v_mfma_f32_16x16x32_bf16 v[116:119], v[156:159], v[164:167], v[116:119]
	s_setprio 0
	s_barrier
	s_add_i32 s22, s56, s41
	s_mov_b32 m0, s22
	ds_read_b128 v[164:167], v242 offset:49152
	ds_read_b128 v[168:171], v242 offset:50176
	ds_read_b128 v[172:175], v242 offset:51200
	ds_read_b128 v[176:179], v242 offset:52224
	ds_read_b128 v[180:183], v242 offset:53248
	ds_read_b128 v[184:187], v242 offset:54272
	ds_read_b128 v[188:191], v242 offset:55296
	ds_read_b128 v[214:217], v242 offset:56320
	s_add_u32 s98, s26, 0x80
	s_addc_u32 s99, s27, 0
	global_load_lds_dwordx4 v2, s[98:99]
	s_add_i32 m0, s22, 0x2000
	s_add_u32 s22, s26, 0x2b0080
	s_addc_u32 s23, s27, 0
	s_add_i32 s26, s57, s41
	global_load_lds_dwordx4 v204, s[98:99]
	s_mov_b32 m0, s26
	s_nop 0
	global_load_lds_dwordx4 v2, s[22:23]
	s_add_i32 m0, s26, 0x2000
	s_nop 0
	global_load_lds_dwordx4 v204, s[22:23]
	s_cmpk_eq_i32 s55, 0xa8
	s_cbranch_scc0 .Ldefer_1700_peel
	v_lshl_add_u64 v[218:219], v[222:223], 0, s[84:85]
	s_mov_b32 m0, s46
	s_nop 0
	global_load_lds_dwordx4 v[218:219], off
	v_lshl_add_u64 v[218:219], v[224:225], 0, s[84:85]
	s_mov_b32 m0, s47
	s_nop 0
	global_load_lds_dwordx4 v[218:219], off

; #define PG8_STAGE(bufoff, gbase, voff) do { _Pragma("unroll") for (int _i = 0; _i < 2; ++_i) \
;         __builtin_amdgcn_global_load_lds((const unsigned*)((const char*)(gbase) + (voff)[_i]), (PG8_LAS unsigned*)(lds + (bufoff) + ldsw + _i * 8192), 16, 0, 0); } while (0)
; #define PG8_LDA(dst, b, h) do { _Pragma("unroll") for (int m = 0; m < 4; ++m) _Pragma("unroll") for (int k = 0; k < 2; ++k) dst[m][k] = *(const PG8_LAS bf16x8*)(lds + PG8_SA(b, h) + aoff + m * 2048 + k * 1024); } while (0)
; #define PG8_LDB(dst, b, h) do { _Pragma("unroll") for (int n = 0; n < 2; ++n) _Pragma("unroll") for (int k = 0; k < 2; ++k) dst[n][k] = *(const PG8_LAS bf16x8*)(lds + PG8_SB(b, h) + boff + n * 2048 + k * 1024); } while (0)
; #define PG8_WAIT_V(n) asm volatile("s_waitcnt vmcnt(" #n ")" ::: "memory")
; #define PG8_WAIT_L(n) asm volatile("s_waitcnt lgkmcnt(" #n ")" ::: "memory")
; #define PG8_BAR __builtin_amdgcn_s_barrier()
; #define PG8_SCHED __builtin_amdgcn_sched_barrier(0)
; template <class Epi, class Sched, bool ALIGN_EPI = false, bool SP2 = false, bool I8 = false>
; __device__ __forceinline__ void gemm_phase(PG8_LAS unsigned char* lds, const Gemm g, const Sched& S, const Epi& E) {
;     ...
;             const char* a2 = last ? nA : cA + (size_t)(t + 2) * kstep; const char* b2 = last ? nB : cB + (size_t)(t + 2) * kstep;
;             const char* a3 = a2 + kstep; const char* b3 = b2 + kstep;
;             if (last && has_next) S.a_ready(nxt);
;             if constexpr (SP2) {
;             PG8_LDB(B0, 0, 0); PG8_LDB(B1, 0, 1); PG8_SCHED; PG8_LDA(At, 0, 0); PG8_STAGE(PG8_SA(1, 1), a1 + hstep, voffA);
;             PG8_WAIT_V(8); PG8_WAIT_L(0); PG8_BAR; PG8_MMA(0, 0, At, B0); PG8_MMA(0, 1, At, B1); PG8_BAR; PG8_SCHED;
;             PG8_LDA(At, 0, 1); PG8_STAGE(PG8_SB(0, 0), b2, voffB); PG8_STAGE(PG8_SB(0, 1), b2 + hstep, voffB); PG8_STAGE(PG8_SA(0, 0), a2, voffA);
;             PG8_WAIT_V(8); PG8_WAIT_L(0); PG8_BAR; PG8_MMA(1, 0, At, B0); PG8_MMA(1, 1, At, B1); PG8_BAR; PG8_SCHED;
;             PG8_LDB(B0, 1, 0); PG8_LDB(B1, 1, 1); PG8_SCHED; PG8_LDA(At, 1, 0); PG8_STAGE(PG8_SA(0, 1), a2 + hstep, voffA);
;             PG8_WAIT_V(8); PG8_WAIT_L(0); PG8_BAR; PG8_MMA(0, 0, At, B0); PG8_MMA(0, 1, At, B1); PG8_BAR; PG8_SCHED;
.LBB0_1700:
	s_add_i32 s56, 0, 0x10000
	s_add_i32 s57, 0, 0x14000
	v_add_u32_e32 v144, s56, v240
	v_add_u32_e32 v160, s57, v240
	ds_read_b128 v[124:127], v144
	ds_read_b128 v[128:131], v144 offset:1024
	ds_read_b128 v[132:135], v144 offset:2048
	ds_read_b128 v[144:147], v144 offset:3072
	ds_read_b128 v[148:151], v160
	ds_read_b128 v[152:155], v160 offset:1024
	ds_read_b128 v[156:159], v160 offset:2048
	ds_read_b128 v[160:163], v160 offset:3072
	s_add_u32 s24, s22, 0x100
	s_addc_u32 s25, s23, 0
	s_cmpk_eq_i32 s55, 0xa8
	s_cselect_b32 s37, s13, s25
	s_cselect_b32 s36, s12, s24
	s_cselect_b32 s27, s21, s54
	s_cselect_b32 s26, s20, s53
	v_lshl_add_u64 v[218:219], v[222:223], 0, s[84:85]
	s_mov_b32 m0, s46
	s_nop 0
	global_load_lds_dwordx4 v[218:219], off
	v_lshl_add_u64 v[218:219], v[224:225], 0, s[84:85]
	s_mov_b32 m0, s47
	s_nop 0
	global_load_lds_dwordx4 v[218:219], off
	v_lshl_add_u64 v[218:219], s[22:23], 0, v[210:211]
	s_add_i32 m0, s42, 0xc000
	ds_read_b128 v[164:167], v242
	ds_read_b128 v[168:171], v242 offset:1024
	ds_read_b128 v[172:175], v242 offset:2048
	ds_read_b128 v[176:179], v242 offset:3072
	ds_read_b128 v[180:183], v242 offset:4096
	ds_read_b128 v[184:187], v242 offset:5120
	ds_read_b128 v[188:191], v242 offset:6144
	ds_read_b128 v[214:217], v242 offset:7168
	global_load_lds_dwordx4 v[218:219], off
	v_lshl_add_u64 v[218:219], s[22:23], 0, v[212:213]
	s_add_i32 m0, s42, 0xe000
	s_nop 0
	global_load_lds_dwordx4 v[218:219], off
	s_waitcnt vmcnt(8)
	s_waitcnt lgkmcnt(0)
	s_barrier
	s_setprio 1
	s_waitcnt lgkmcnt(0)
	v_mfma_f32_16x16x32_bf16 v[140:143], v[124:127], v[164:167], v[140:143]
	v_mfma_f32_16x16x32_bf16 v[140:143], v[128:131], v[168:171], v[140:143]
	v_mfma_f32_16x16x32_bf16 v[112:115], v[128:131], v[176:179], v[112:115]
	v_mfma_f32_16x16x32_bf16 v[112:115], v[124:127], v[172:175], v[112:115]
	v_mfma_f32_16x16x32_bf16 v[96:99], v[124:127], v[180:183], v[96:99]
	v_mfma_f32_16x16x32_bf16 v[96:99], v[128:131], v[184:187], v[96:99]
	v_mfma_f32_16x16x32_bf16 v[80:83], v[128:131], v[214:217], v[80:83]
	v_mfma_f32_16x16x32_bf16 v[80:83], v[124:127], v[188:191], v[80:83]
	v_mfma_f32_16x16x32_bf16 v[76:79], v[132:135], v[188:191], v[76:79]
	v_mfma_f32_16x16x32_bf16 v[76:79], v[144:147], v[214:217], v[76:79]
	v_mfma_f32_16x16x32_bf16 v[92:95], v[144:147], v[184:187], v[92:95]
	v_mfma_f32_16x16x32_bf16 v[92:95], v[132:135], v[180:183], v[92:95]
	v_mfma_f32_16x16x32_bf16 v[108:111], v[132:135], v[172:175], v[108:111]
	v_mfma_f32_16x16x32_bf16 v[108:111], v[144:147], v[176:179], v[108:111]
	v_mfma_f32_16x16x32_bf16 v[136:139], v[144:147], v[168:171], v[136:139]
	v_mfma_f32_16x16x32_bf16 v[136:139], v[132:135], v[164:167], v[136:139]
	v_mfma_f32_16x16x32_bf16 v[120:123], v[148:151], v[164:167], v[120:123]
	v_mfma_f32_16x16x32_bf16 v[120:123], v[152:155], v[168:171], v[120:123]
	v_mfma_f32_16x16x32_bf16 v[104:107], v[152:155], v[176:179], v[104:107]
	v_mfma_f32_16x16x32_bf16 v[104:107], v[148:151], v[172:175], v[104:107]
	v_mfma_f32_16x16x32_bf16 v[88:91], v[148:151], v[180:183], v[88:91]
	v_mfma_f32_16x16x32_bf16 v[88:91], v[152:155], v[184:187], v[88:91]
	v_mfma_f32_16x16x32_bf16 v[72:75], v[152:155], v[214:217], v[72:75]
	v_mfma_f32_16x16x32_bf16 v[72:75], v[148:151], v[188:191], v[72:75]
	v_mfma_f32_16x16x32_bf16 v[68:71], v[156:159], v[188:191], v[68:71]
	v_mfma_f32_16x16x32_bf16 v[68:71], v[160:163], v[214:217], v[68:71]
	v_mfma_f32_16x16x32_bf16 v[84:87], v[160:163], v[184:187], v[84:87]
	v_mfma_f32_16x16x32_bf16 v[84:87], v[156:159], v[180:183], v[84:87]
	v_mfma_f32_16x16x32_bf16 v[100:103], v[156:159], v[172:175], v[100:103]
	v_mfma_f32_16x16x32_bf16 v[100:103], v[160:163], v[176:179], v[100:103]
	v_mfma_f32_16x16x32_bf16 v[116:119], v[160:163], v[168:171], v[116:119]
	v_mfma_f32_16x16x32_bf16 v[116:119], v[156:159], v[164:167], v[116:119]
	s_setprio 0
	s_barrier
	s_add_i32 s22, s56, s41
	s_mov_b32 m0, s22
	ds_read_b128 v[164:167], v242 offset:16384
	ds_read_b128 v[168:171], v242 offset:17408
	ds_read_b128 v[172:175], v242 offset:18432
	ds_read_b128 v[176:179], v242 offset:19456
	ds_read_b128 v[180:183], v242 offset:20480
	ds_read_b128 v[184:187], v242 offset:21504
	ds_read_b128 v[188:191], v242 offset:22528
	ds_read_b128 v[214:217], v242 offset:23552
	global_load_lds_dwordx4 v2, s[26:27]
	s_add_i32 m0, s22, 0x2000
	s_add_u32 s22, s26, 0x2b0000
	s_addc_u32 s23, s27, 0
	s_add_i32 s56, s57, s41
	global_load_lds_dwordx4 v204, s[26:27]
	s_mov_b32 m0, s56
	v_lshl_add_u64 v[224:225], s[36:37], 0, v[206:207]
	global_load_lds_dwordx4 v2, s[22:23]
	s_add_i32 m0, s56, 0x2000
	s_nop 0
	global_load_lds_dwordx4 v204, s[22:23]
	v_lshl_add_u64 v[222:223], s[36:37], 0, v[208:209]
	s_waitcnt vmcnt(6)
	s_waitcnt lgkmcnt(0)
	s_barrier
; #define PG8_STAGE(bufoff, gbase, voff) do { _Pragma("unroll") for (int _i = 0; _i < 2; ++_i) \
;         __builtin_amdgcn_global_load_lds((const unsigned*)((const char*)(gbase) + (voff)[_i]), (PG8_LAS unsigned*)(lds + (bufoff) + ldsw + _i * 8192), 16, 0, 0); } while (0)
; #define PG8_LDA(dst, b, h) do { _Pragma("unroll") for (int m = 0; m < 4; ++m) _Pragma("unroll") for (int k = 0; k < 2; ++k) dst[m][k] = *(const PG8_LAS bf16x8*)(lds + PG8_SA(b, h) + aoff + m * 2048 + k * 1024); } while (0)
; #define PG8_WAIT_V(n) asm volatile("s_waitcnt vmcnt(" #n ")" ::: "memory")
; #define PG8_WAIT_L(n) asm volatile("s_waitcnt lgkmcnt(" #n ")" ::: "memory")
; #define PG8_BAR __builtin_amdgcn_s_barrier()
; #define PG8_SCHED __builtin_amdgcn_sched_barrier(0)
; template <class Epi, class Sched, bool ALIGN_EPI = false, bool SP2 = false, bool I8 = false>
; __device__ __forceinline__ void gemm_phase(PG8_LAS unsigned char* lds, const Gemm g, const Sched& S, const Epi& E) {
;     ...
;             PG8_WAIT_V(8); PG8_WAIT_L(0); PG8_BAR; PG8_MMA(0, 0, At, B0); PG8_MMA(0, 1, At, B1); PG8_BAR; PG8_SCHED;
;             PG8_LDA(At, 1, 1); PG8_STAGE(PG8_SB(1, 0), b3, voffB); PG8_STAGE(PG8_SB(1, 1), b3 + hstep, voffB); PG8_STAGE(PG8_SA(1, 0), a3, voffA);
;             PG8_WAIT_V(8); PG8_WAIT_L(0); PG8_BAR; PG8_MMA(1, 0, At, B0); PG8_MMA(1, 1, At, B1); PG8_BAR; PG8_SCHED;
	s_setprio 1
	s_waitcnt lgkmcnt(0)
	v_mfma_f32_16x16x32_bf16 v[64:67], v[124:127], v[164:167], v[64:67]
	v_mfma_f32_16x16x32_bf16 v[64:67], v[128:131], v[168:171], v[64:67]
	v_mfma_f32_16x16x32_bf16 v[48:51], v[128:131], v[176:179], v[48:51]
	v_mfma_f32_16x16x32_bf16 v[48:51], v[124:127], v[172:175], v[48:51]
	v_mfma_f32_16x16x32_bf16 v[32:35], v[124:127], v[180:183], v[32:35]
	v_mfma_f32_16x16x32_bf16 v[32:35], v[128:131], v[184:187], v[32:35]
	v_mfma_f32_16x16x32_bf16 v[16:19], v[128:131], v[214:217], v[16:19]
	v_mfma_f32_16x16x32_bf16 v[16:19], v[124:127], v[188:191], v[16:19]
	v_mfma_f32_16x16x32_bf16 v[12:15], v[132:135], v[188:191], v[12:15]
	v_mfma_f32_16x16x32_bf16 v[12:15], v[144:147], v[214:217], v[12:15]
	v_mfma_f32_16x16x32_bf16 v[28:31], v[144:147], v[184:187], v[28:31]
	v_mfma_f32_16x16x32_bf16 v[28:31], v[132:135], v[180:183], v[28:31]
	v_mfma_f32_16x16x32_bf16 v[44:47], v[132:135], v[172:175], v[44:47]
	v_mfma_f32_16x16x32_bf16 v[44:47], v[144:147], v[176:179], v[44:47]
	v_mfma_f32_16x16x32_bf16 v[60:63], v[144:147], v[168:171], v[60:63]
	v_mfma_f32_16x16x32_bf16 v[60:63], v[132:135], v[164:167], v[60:63]
	v_mfma_f32_16x16x32_bf16 v[56:59], v[148:151], v[164:167], v[56:59]
	v_mfma_f32_16x16x32_bf16 v[56:59], v[152:155], v[168:171], v[56:59]
	v_mfma_f32_16x16x32_bf16 v[40:43], v[152:155], v[176:179], v[40:43]
	v_mfma_f32_16x16x32_bf16 v[40:43], v[148:151], v[172:175], v[40:43]
	v_mfma_f32_16x16x32_bf16 v[24:27], v[148:151], v[180:183], v[24:27]
	v_mfma_f32_16x16x32_bf16 v[24:27], v[152:155], v[184:187], v[24:27]
	v_mfma_f32_16x16x32_bf16 v[8:11], v[152:155], v[214:217], v[8:11]
	v_mfma_f32_16x16x32_bf16 v[8:11], v[148:151], v[188:191], v[8:11]
	v_mfma_f32_16x16x32_bf16 v[4:7], v[156:159], v[188:191], v[4:7]
	v_mfma_f32_16x16x32_bf16 v[4:7], v[160:163], v[214:217], v[4:7]
	v_mfma_f32_16x16x32_bf16 v[20:23], v[160:163], v[184:187], v[20:23]
	v_mfma_f32_16x16x32_bf16 v[20:23], v[156:159], v[180:183], v[20:23]
	v_mfma_f32_16x16x32_bf16 v[36:39], v[156:159], v[172:175], v[36:39]
	v_mfma_f32_16x16x32_bf16 v[36:39], v[160:163], v[176:179], v[36:39]
	v_mfma_f32_16x16x32_bf16 v[52:55], v[160:163], v[168:171], v[52:55]
	v_mfma_f32_16x16x32_bf16 v[52:55], v[156:159], v[164:167], v[52:55]
	s_setprio 0
	s_barrier
	s_mov_b32 m0, s42
	s_nop 0
	global_load_lds_dwordx4 v[222:223], off
	s_mov_b32 m0, s43
	s_nop 0
	global_load_lds_dwordx4 v[224:225], off
	s_add_i32 s56, 0, 0x18000
	s_add_i32 s57, 0, 0x1c000
	v_add_u32_e32 v144, s56, v240
	v_add_u32_e32 v160, s57, v240
	ds_read_b128 v[124:127], v144
	ds_read_b128 v[128:131], v144 offset:1024
	ds_read_b128 v[132:135], v144 offset:2048
	ds_read_b128 v[144:147], v144 offset:3072
	ds_read_b128 v[148:151], v160
	ds_read_b128 v[152:155], v160 offset:1024
	ds_read_b128 v[156:159], v160 offset:2048
	ds_read_b128 v[160:163], v160 offset:3072
	s_add_u32 s22, s36, 0x2b0000
	s_addc_u32 s23, s37, 0
	s_mov_b32 m0, s44
	ds_read_b128 v[164:167], v242 offset:32768
	ds_read_b128 v[168:171], v242 offset:33792
	ds_read_b128 v[172:175], v242 offset:34816
	ds_read_b128 v[176:179], v242 offset:35840
	ds_read_b128 v[180:183], v242 offset:36864
	ds_read_b128 v[184:187], v242 offset:37888
	ds_read_b128 v[188:191], v242 offset:38912
	ds_read_b128 v[214:217], v242 offset:39936
	global_load_lds_dwordx4 v208, s[22:23]
	s_mov_b32 m0, s45
	s_nop 0
	global_load_lds_dwordx4 v206, s[22:23]
	s_waitcnt vmcnt(8)
	s_waitcnt lgkmcnt(0)
	s_barrier
	s_setprio 1
	s_waitcnt lgkmcnt(0)
	v_mfma_f32_16x16x32_bf16 v[140:143], v[124:127], v[164:167], v[140:143]
	v_mfma_f32_16x16x32_bf16 v[140:143], v[128:131], v[168:171], v[140:143]
	v_mfma_f32_16x16x32_bf16 v[112:115], v[128:131], v[176:179], v[112:115]
	v_mfma_f32_16x16x32_bf16 v[112:115], v[124:127], v[172:175], v[112:115]
	v_mfma_f32_16x16x32_bf16 v[96:99], v[124:127], v[180:183], v[96:99]
	v_mfma_f32_16x16x32_bf16 v[96:99], v[128:131], v[184:187], v[96:99]
	v_mfma_f32_16x16x32_bf16 v[80:83], v[128:131], v[214:217], v[80:83]
	v_mfma_f32_16x16x32_bf16 v[80:83], v[124:127], v[188:191], v[80:83]
	v_mfma_f32_16x16x32_bf16 v[76:79], v[132:135], v[188:191], v[76:79]
	v_mfma_f32_16x16x32_bf16 v[76:79], v[144:147], v[214:217], v[76:79]
	v_mfma_f32_16x16x32_bf16 v[92:95], v[144:147], v[184:187], v[92:95]
	v_mfma_f32_16x16x32_bf16 v[92:95], v[132:135], v[180:183], v[92:95]
	v_mfma_f32_16x16x32_bf16 v[108:111], v[132:135], v[172:175], v[108:111]
	v_mfma_f32_16x16x32_bf16 v[108:111], v[144:147], v[176:179], v[108:111]
	v_mfma_f32_16x16x32_bf16 v[136:139], v[144:147], v[168:171], v[136:139]
	v_mfma_f32_16x16x32_bf16 v[136:139], v[132:135], v[164:167], v[136:139]
	v_mfma_f32_16x16x32_bf16 v[120:123], v[148:151], v[164:167], v[120:123]
	v_mfma_f32_16x16x32_bf16 v[120:123], v[152:155], v[168:171], v[120:123]
	v_mfma_f32_16x16x32_bf16 v[104:107], v[152:155], v[176:179], v[104:107]
	v_mfma_f32_16x16x32_bf16 v[104:107], v[148:151], v[172:175], v[104:107]
	v_mfma_f32_16x16x32_bf16 v[88:91], v[148:151], v[180:183], v[88:91]
	v_mfma_f32_16x16x32_bf16 v[88:91], v[152:155], v[184:187], v[88:91]
	v_mfma_f32_16x16x32_bf16 v[72:75], v[152:155], v[214:217], v[72:75]
	v_mfma_f32_16x16x32_bf16 v[72:75], v[148:151], v[188:191], v[72:75]
	v_mfma_f32_16x16x32_bf16 v[68:71], v[156:159], v[188:191], v[68:71]
	v_mfma_f32_16x16x32_bf16 v[68:71], v[160:163], v[214:217], v[68:71]
	v_mfma_f32_16x16x32_bf16 v[84:87], v[160:163], v[184:187], v[84:87]
	v_mfma_f32_16x16x32_bf16 v[84:87], v[156:159], v[180:183], v[84:87]
	v_mfma_f32_16x16x32_bf16 v[100:103], v[156:159], v[172:175], v[100:103]
	v_mfma_f32_16x16x32_bf16 v[100:103], v[160:163], v[176:179], v[100:103]
	v_mfma_f32_16x16x32_bf16 v[116:119], v[160:163], v[168:171], v[116:119]
	v_mfma_f32_16x16x32_bf16 v[116:119], v[156:159], v[164:167], v[116:119]
	s_setprio 0
	s_barrier
	s_add_i32 s22, s56, s41
	s_mov_b32 m0, s22
	ds_read_b128 v[164:167], v242 offset:49152
	ds_read_b128 v[168:171], v242 offset:50176
	ds_read_b128 v[172:175], v242 offset:51200
	ds_read_b128 v[176:179], v242 offset:52224
	ds_read_b128 v[180:183], v242 offset:53248
	ds_read_b128 v[184:187], v242 offset:54272
	ds_read_b128 v[188:191], v242 offset:55296
	ds_read_b128 v[214:217], v242 offset:56320
	s_add_u32 s98, s26, 0x80
	s_addc_u32 s99, s27, 0
	global_load_lds_dwordx4 v2, s[98:99]
	s_add_i32 m0, s22, 0x2000
	s_add_u32 s22, s26, 0x2b0080
	s_addc_u32 s23, s27, 0
	s_add_i32 s26, s57, s41
	global_load_lds_dwordx4 v204, s[98:99]
	s_mov_b32 m0, s26
	s_nop 0
	global_load_lds_dwordx4 v2, s[22:23]
	s_add_i32 m0, s26, 0x2000
	s_nop 0
	global_load_lds_dwordx4 v204, s[22:23]
	s_cmpk_eq_i32 s55, 0xa8
	s_cbranch_scc0 .Ldefer_1700_body
	v_lshl_add_u64 v[218:219], v[222:223], 0, s[84:85]
	s_mov_b32 m0, s46
	s_nop 0
	global_load_lds_dwordx4 v[218:219], off
	v_lshl_add_u64 v[218:219], v[224:225], 0, s[84:85]
	s_mov_b32 m0, s47
	s_nop 0
	global_load_lds_dwordx4 v[218:219], off

; #define PG8_STAGE(bufoff, gbase, voff) do { _Pragma("unroll") for (int _i = 0; _i < 2; ++_i) \
;         __builtin_amdgcn_global_load_lds((const unsigned*)((const char*)(gbase) + (voff)[_i]), (PG8_LAS unsigned*)(lds + (bufoff) + ldsw + _i * 8192), 16, 0, 0); } while (0)
; #define PG8_LDA(dst, b, h) do { _Pragma("unroll") for (int m = 0; m < 4; ++m) _Pragma("unroll") for (int k = 0; k < 2; ++k) dst[m][k] = *(const PG8_LAS bf16x8*)(lds + PG8_SA(b, h) + aoff + m * 2048 + k * 1024); } while (0)
; #define PG8_LDB(dst, b, h) do { _Pragma("unroll") for (int n = 0; n < 2; ++n) _Pragma("unroll") for (int k = 0; k < 2; ++k) dst[n][k] = *(const PG8_LAS bf16x8*)(lds + PG8_SB(b, h) + boff + n * 2048 + k * 1024); } while (0)
; #define PG8_WAIT_V(n) asm volatile("s_waitcnt vmcnt(" #n ")" ::: "memory")
; #define PG8_WAIT_L(n) asm volatile("s_waitcnt lgkmcnt(" #n ")" ::: "memory")
; #define PG8_BAR __builtin_amdgcn_s_barrier()
; #define PG8_SCHED __builtin_amdgcn_sched_barrier(0)
; template <class Epi, class Sched, bool ALIGN_EPI = false, bool SP2 = false, bool I8 = false>
; __device__ __forceinline__ void gemm_phase(PG8_LAS unsigned char* lds, const Gemm g, const Sched& S, const Epi& E) {
;     ...
;         const bool has_next = S.next(ui + 1, nxt);
;         const char* nA = has_next ? (const char*)g.A + (size_t)nxt.pm * tstep : cA; const char* nB = has_next ? (const char*)g.Bt + (size_t)nxt.pn * tstep : cB;
;         for (int t = 0; t < nt; t += 2) {
;             const bool last = (t == nt - 2);
;             const char* a1 = cA + (size_t)(t + 1) * kstep;
;             const char* a2 = last ? nA : cA + (size_t)(t + 2) * kstep; const char* b2 = last ? nB : cB + (size_t)(t + 2) * kstep;
;             const char* a3 = a2 + kstep; const char* b3 = b2 + kstep;
;             if (last && has_next) S.a_ready(nxt);
;             if constexpr (SP2) {
;             PG8_LDB(B0, 0, 0); PG8_LDB(B1, 0, 1); PG8_SCHED; PG8_LDA(At, 0, 0); PG8_STAGE(PG8_SA(1, 1), a1 + hstep, voffA);
;             PG8_WAIT_V(8); PG8_WAIT_L(0); PG8_BAR; PG8_MMA(0, 0, At, B0); PG8_MMA(0, 1, At, B1); PG8_BAR; PG8_SCHED;
;             PG8_LDA(At, 0, 1); PG8_STAGE(PG8_SB(0, 0), b2, voffB); PG8_STAGE(PG8_SB(0, 1), b2 + hstep, voffB); PG8_STAGE(PG8_SA(0, 0), a2, voffA);
;             PG8_WAIT_V(8); PG8_WAIT_L(0); PG8_BAR; PG8_MMA(1, 0, At, B0); PG8_MMA(1, 1, At, B1); PG8_BAR; PG8_SCHED;
.LBB0_1842:
	s_ashr_i32 s45, s44, 31
	s_lshl_b64 s[34:35], s[44:45], 20
	s_add_u32 s50, s47, s34
	s_addc_u32 s51, s52, s35
	s_and_b64 s[34:35], s[8:9], exec
	s_cselect_b32 s11, s51, s55
	s_cselect_b32 s13, s50, s54
	s_ashr_i32 s49, s48, 31
	s_lshl_b64 s[34:35], s[48:49], 20
	s_add_u32 s56, s53, s34
	s_addc_u32 s57, s64, s35
	s_and_b64 s[34:35], s[8:9], exec
	s_cselect_b32 s34, s57, s59
	s_cselect_b32 s35, s56, s58
	s_add_u32 s54, s54, 0x80080
	s_addc_u32 s55, s55, 0
	s_add_u32 s45, s58, 0x100
	s_addc_u32 s49, s59, 0
	s_mov_b32 s86, -2
	s_waitcnt lgkmcnt(0)
	s_add_i32 s87, 0, 0x10000
	s_add_i32 vcc_lo, 0, 0x14000
	v_add_u32_e32 v40, s87, v217
	v_add_u32_e32 v160, vcc_lo, v217
	ds_read_b128 v[28:31], v40
	ds_read_b128 v[32:35], v40 offset:1024
	ds_read_b128 v[36:39], v40 offset:2048
	ds_read_b128 v[40:43], v40 offset:3072
	ds_read_b128 v[140:143], v160
	ds_read_b128 v[144:147], v160 offset:1024
	ds_read_b128 v[156:159], v160 offset:2048
	ds_read_b128 v[160:163], v160 offset:3072
	s_add_u32 s58, s54, 0xfff80080
	s_addc_u32 s59, s55, -1
	s_cmp_eq_u32 s86, 28
	s_cselect_b32 s61, s11, s59
	s_cselect_b32 s60, s13, s58
	s_cselect_b32 s59, s34, s49
	s_cselect_b32 s58, s35, s45
	s_add_i32 m0, s65, 0xc000
	ds_read_b128 v[164:167], v219
	ds_read_b128 v[168:171], v219 offset:1024
	ds_read_b128 v[172:175], v219 offset:2048
	ds_read_b128 v[176:179], v219 offset:3072
	ds_read_b128 v[204:207], v219 offset:4096
	ds_read_b128 v[208:211], v219 offset:5120
	ds_read_b128 v[212:215], v219 offset:6144
	ds_read_b128 v[220:223], v219 offset:7168
	global_load_lds_dwordx4 v186, s[54:55]
	s_add_i32 m0, s65, 0xe000
	s_nop 0
	global_load_lds_dwordx4 v188, s[54:55]
	s_waitcnt vmcnt(8)
	s_waitcnt lgkmcnt(0)
	s_barrier
	s_setprio 1
	s_waitcnt lgkmcnt(0)
	v_mfma_i32_16x16x64_i8 v[152:155], v[28:31], v[164:167], 0
	v_mfma_i32_16x16x64_i8 v[152:155], v[32:35], v[168:171], v[152:155]
	v_mfma_i32_16x16x64_i8 v[128:131], v[32:35], v[176:179], 0
	v_mfma_i32_16x16x64_i8 v[128:131], v[28:31], v[172:175], v[128:131]
	v_mfma_i32_16x16x64_i8 v[112:115], v[28:31], v[204:207], 0
	v_mfma_i32_16x16x64_i8 v[112:115], v[32:35], v[208:211], v[112:115]
	v_mfma_i32_16x16x64_i8 v[96:99], v[32:35], v[220:223], 0
	v_mfma_i32_16x16x64_i8 v[96:99], v[28:31], v[212:215], v[96:99]
	v_mfma_i32_16x16x64_i8 v[92:95], v[36:39], v[212:215], 0
	v_mfma_i32_16x16x64_i8 v[92:95], v[40:43], v[220:223], v[92:95]
	v_mfma_i32_16x16x64_i8 v[108:111], v[40:43], v[208:211], 0
	v_mfma_i32_16x16x64_i8 v[108:111], v[36:39], v[204:207], v[108:111]
	v_mfma_i32_16x16x64_i8 v[124:127], v[36:39], v[172:175], 0
	v_mfma_i32_16x16x64_i8 v[124:127], v[40:43], v[176:179], v[124:127]
	v_mfma_i32_16x16x64_i8 v[148:151], v[40:43], v[168:171], 0
	v_mfma_i32_16x16x64_i8 v[148:151], v[36:39], v[164:167], v[148:151]
	v_mfma_i32_16x16x64_i8 v[136:139], v[140:143], v[164:167], 0
	v_mfma_i32_16x16x64_i8 v[136:139], v[144:147], v[168:171], v[136:139]
	v_mfma_i32_16x16x64_i8 v[120:123], v[144:147], v[176:179], 0
	v_mfma_i32_16x16x64_i8 v[120:123], v[140:143], v[172:175], v[120:123]
	v_mfma_i32_16x16x64_i8 v[104:107], v[140:143], v[204:207], 0
	v_mfma_i32_16x16x64_i8 v[104:107], v[144:147], v[208:211], v[104:107]
	v_mfma_i32_16x16x64_i8 v[88:91], v[144:147], v[220:223], 0
	v_mfma_i32_16x16x64_i8 v[88:91], v[140:143], v[212:215], v[88:91]
	v_mfma_i32_16x16x64_i8 v[84:87], v[156:159], v[212:215], 0
	v_mfma_i32_16x16x64_i8 v[84:87], v[160:163], v[220:223], v[84:87]
	v_mfma_i32_16x16x64_i8 v[100:103], v[160:163], v[208:211], 0
	v_mfma_i32_16x16x64_i8 v[100:103], v[156:159], v[204:207], v[100:103]
	v_mfma_i32_16x16x64_i8 v[116:119], v[156:159], v[172:175], 0
	v_mfma_i32_16x16x64_i8 v[116:119], v[160:163], v[176:179], v[116:119]
	v_mfma_i32_16x16x64_i8 v[132:135], v[160:163], v[168:171], 0
	v_mfma_i32_16x16x64_i8 v[132:135], v[156:159], v[164:167], v[132:135]
	s_setprio 0
	s_barrier
	s_add_i32 s87, s87, s46
	s_mov_b32 m0, s87
	ds_read_b128 v[164:167], v219 offset:16384
	ds_read_b128 v[168:171], v219 offset:17408
	ds_read_b128 v[172:175], v219 offset:18432
	ds_read_b128 v[176:179], v219 offset:19456
	ds_read_b128 v[204:207], v219 offset:20480
	ds_read_b128 v[208:211], v219 offset:21504
	ds_read_b128 v[212:215], v219 offset:22528
	ds_read_b128 v[220:223], v219 offset:23552
	global_load_lds_dwordx4 v2, s[58:59]
	s_add_i32 m0, s87, 0x2000
	s_add_u32 s96, s58, 0x80000
	s_addc_u32 s97, s59, 0
	s_add_i32 s87, vcc_lo, s46
	global_load_lds_dwordx4 v184, s[58:59]
	s_mov_b32 m0, s87
	v_lshl_add_u64 v[228:229], s[60:61], 0, v[182:183]
	global_load_lds_dwordx4 v2, s[96:97]
	s_add_i32 m0, s87, 0x2000
	s_nop 0
	global_load_lds_dwordx4 v184, s[96:97]
	v_lshl_add_u64 v[226:227], s[60:61], 0, v[180:181]
	s_waitcnt vmcnt(6)
	s_waitcnt lgkmcnt(0)
	s_barrier
; #define PG8_STAGE(bufoff, gbase, voff) do { _Pragma("unroll") for (int _i = 0; _i < 2; ++_i) \
;         __builtin_amdgcn_global_load_lds((const unsigned*)((const char*)(gbase) + (voff)[_i]), (PG8_LAS unsigned*)(lds + (bufoff) + ldsw + _i * 8192), 16, 0, 0); } while (0)
; #define PG8_LDA(dst, b, h) do { _Pragma("unroll") for (int m = 0; m < 4; ++m) _Pragma("unroll") for (int k = 0; k < 2; ++k) dst[m][k] = *(const PG8_LAS bf16x8*)(lds + PG8_SA(b, h) + aoff + m * 2048 + k * 1024); } while (0)
; #define PG8_LDB(dst, b, h) do { _Pragma("unroll") for (int n = 0; n < 2; ++n) _Pragma("unroll") for (int k = 0; k < 2; ++k) dst[n][k] = *(const PG8_LAS bf16x8*)(lds + PG8_SB(b, h) + boff + n * 2048 + k * 1024); } while (0)
; #define PG8_WAIT_V(n) asm volatile("s_waitcnt vmcnt(" #n ")" ::: "memory")
; #define PG8_WAIT_L(n) asm volatile("s_waitcnt lgkmcnt(" #n ")" ::: "memory")
; #define PG8_BAR __builtin_amdgcn_s_barrier()
; #define PG8_SCHED __builtin_amdgcn_sched_barrier(0)
; template <class Epi, class Sched, bool ALIGN_EPI = false, bool SP2 = false, bool I8 = false>
; __device__ __forceinline__ void gemm_phase(PG8_LAS unsigned char* lds, const Gemm g, const Sched& S, const Epi& E) {
;     ...
;             PG8_WAIT_V(8); PG8_WAIT_L(0); PG8_BAR; PG8_MMA(0, 0, At, B0); PG8_MMA(0, 1, At, B1); PG8_BAR; PG8_SCHED;
;             PG8_LDA(At, 0, 1); PG8_STAGE(PG8_SB(0, 0), b2, voffB); PG8_STAGE(PG8_SB(0, 1), b2 + hstep, voffB); PG8_STAGE(PG8_SA(0, 0), a2, voffA);
;             PG8_WAIT_V(8); PG8_WAIT_L(0); PG8_BAR; PG8_MMA(1, 0, At, B0); PG8_MMA(1, 1, At, B1); PG8_BAR; PG8_SCHED;
;             PG8_LDB(B0, 1, 0); PG8_LDB(B1, 1, 1); PG8_SCHED; PG8_LDA(At, 1, 0); PG8_STAGE(PG8_SA(0, 1), a2 + hstep, voffA);
;             PG8_WAIT_V(8); PG8_WAIT_L(0); PG8_BAR; PG8_MMA(0, 0, At, B0); PG8_MMA(0, 1, At, B1); PG8_BAR; PG8_SCHED;
;             PG8_LDA(At, 1, 1); PG8_STAGE(PG8_SB(1, 0), b3, voffB); PG8_STAGE(PG8_SB(1, 1), b3 + hstep, voffB); PG8_STAGE(PG8_SA(1, 0), a3, voffA);
;             PG8_WAIT_V(8); PG8_WAIT_L(0); PG8_BAR; PG8_MMA(1, 0, At, B0); PG8_MMA(1, 1, At, B1); PG8_BAR; PG8_SCHED;
	s_setprio 1
	s_waitcnt lgkmcnt(0)
	v_mfma_i32_16x16x64_i8 v[80:83], v[28:31], v[164:167], 0
	v_mfma_i32_16x16x64_i8 v[80:83], v[32:35], v[168:171], v[80:83]
	v_mfma_i32_16x16x64_i8 v[64:67], v[32:35], v[176:179], 0
	v_mfma_i32_16x16x64_i8 v[64:67], v[28:31], v[172:175], v[64:67]
	v_mfma_i32_16x16x64_i8 v[48:51], v[28:31], v[204:207], 0
	v_mfma_i32_16x16x64_i8 v[48:51], v[32:35], v[208:211], v[48:51]
	v_mfma_i32_16x16x64_i8 v[16:19], v[32:35], v[220:223], 0
	v_mfma_i32_16x16x64_i8 v[16:19], v[28:31], v[212:215], v[16:19]
	v_mfma_i32_16x16x64_i8 v[12:15], v[36:39], v[212:215], 0
	v_mfma_i32_16x16x64_i8 v[12:15], v[40:43], v[220:223], v[12:15]
	v_mfma_i32_16x16x64_i8 v[44:47], v[40:43], v[208:211], 0
	v_mfma_i32_16x16x64_i8 v[44:47], v[36:39], v[204:207], v[44:47]
	v_mfma_i32_16x16x64_i8 v[60:63], v[36:39], v[172:175], 0
	v_mfma_i32_16x16x64_i8 v[60:63], v[40:43], v[176:179], v[60:63]
	v_mfma_i32_16x16x64_i8 v[76:79], v[40:43], v[168:171], 0
	v_mfma_i32_16x16x64_i8 v[76:79], v[36:39], v[164:167], v[76:79]
	v_mfma_i32_16x16x64_i8 v[28:31], v[140:143], v[164:167], 0
	v_mfma_i32_16x16x64_i8 v[28:31], v[144:147], v[168:171], v[28:31]
	v_mfma_i32_16x16x64_i8 v[36:39], v[144:147], v[176:179], 0
	v_mfma_i32_16x16x64_i8 v[36:39], v[140:143], v[172:175], v[36:39]
	v_mfma_i32_16x16x64_i8 v[24:27], v[140:143], v[204:207], 0
	v_mfma_i32_16x16x64_i8 v[24:27], v[144:147], v[208:211], v[24:27]
	v_mfma_i32_16x16x64_i8 v[8:11], v[144:147], v[220:223], 0
	v_mfma_i32_16x16x64_i8 v[8:11], v[140:143], v[212:215], v[8:11]
	v_mfma_i32_16x16x64_i8 v[4:7], v[156:159], v[212:215], 0
	v_mfma_i32_16x16x64_i8 v[4:7], v[160:163], v[220:223], v[4:7]
	v_mfma_i32_16x16x64_i8 v[20:23], v[160:163], v[208:211], 0
	v_mfma_i32_16x16x64_i8 v[20:23], v[156:159], v[204:207], v[20:23]
	v_mfma_i32_16x16x64_i8 v[40:43], v[156:159], v[172:175], 0
	v_mfma_i32_16x16x64_i8 v[40:43], v[160:163], v[176:179], v[40:43]
	v_mfma_i32_16x16x64_i8 v[32:35], v[160:163], v[168:171], 0
	v_mfma_i32_16x16x64_i8 v[32:35], v[156:159], v[164:167], v[32:35]
	s_setprio 0
	s_barrier
	s_mov_b32 m0, s65
	s_nop 0
	global_load_lds_dwordx4 v[226:227], off
	s_mov_b32 m0, s67
	s_nop 0
	global_load_lds_dwordx4 v[228:229], off
	s_add_i32 s87, 0, 0x18000
	s_add_i32 s96, 0, 0x1c000
	v_add_u32_e32 v72, s87, v217
	v_add_u32_e32 v160, s96, v217
	ds_read_b128 v[52:55], v72
	ds_read_b128 v[56:59], v72 offset:1024
	ds_read_b128 v[68:71], v72 offset:2048
	ds_read_b128 v[72:75], v72 offset:3072
	ds_read_b128 v[140:143], v160
	ds_read_b128 v[144:147], v160 offset:1024
	ds_read_b128 v[156:159], v160 offset:2048
	ds_read_b128 v[160:163], v160 offset:3072
	s_add_u32 s60, s60, 0x80000
	s_addc_u32 s61, s61, 0
	s_mov_b32 m0, s72
	ds_read_b128 v[164:167], v219 offset:32768
	ds_read_b128 v[168:171], v219 offset:33792
	ds_read_b128 v[172:175], v219 offset:34816
	ds_read_b128 v[176:179], v219 offset:35840
	ds_read_b128 v[204:207], v219 offset:36864
	ds_read_b128 v[208:211], v219 offset:37888
	ds_read_b128 v[212:215], v219 offset:38912
	ds_read_b128 v[220:223], v219 offset:39936
	global_load_lds_dwordx4 v180, s[60:61]
	s_mov_b32 m0, s73
	s_nop 0
	global_load_lds_dwordx4 v182, s[60:61]
	s_waitcnt vmcnt(8)
	s_waitcnt lgkmcnt(0)
	s_barrier
	s_setprio 1
	s_waitcnt lgkmcnt(0)
	v_mfma_i32_16x16x64_i8 v[152:155], v[52:55], v[164:167], v[152:155]
	v_mfma_i32_16x16x64_i8 v[152:155], v[56:59], v[168:171], v[152:155]
	v_mfma_i32_16x16x64_i8 v[128:131], v[56:59], v[176:179], v[128:131]
	v_mfma_i32_16x16x64_i8 v[128:131], v[52:55], v[172:175], v[128:131]
	v_mfma_i32_16x16x64_i8 v[112:115], v[52:55], v[204:207], v[112:115]
	v_mfma_i32_16x16x64_i8 v[112:115], v[56:59], v[208:211], v[112:115]
	v_mfma_i32_16x16x64_i8 v[96:99], v[56:59], v[220:223], v[96:99]
	v_mfma_i32_16x16x64_i8 v[96:99], v[52:55], v[212:215], v[96:99]
	v_mfma_i32_16x16x64_i8 v[92:95], v[68:71], v[212:215], v[92:95]
	v_mfma_i32_16x16x64_i8 v[92:95], v[72:75], v[220:223], v[92:95]
	v_mfma_i32_16x16x64_i8 v[108:111], v[72:75], v[208:211], v[108:111]
	v_mfma_i32_16x16x64_i8 v[108:111], v[68:71], v[204:207], v[108:111]
	v_mfma_i32_16x16x64_i8 v[124:127], v[68:71], v[172:175], v[124:127]
	v_mfma_i32_16x16x64_i8 v[124:127], v[72:75], v[176:179], v[124:127]
	v_mfma_i32_16x16x64_i8 v[148:151], v[72:75], v[168:171], v[148:151]
	v_mfma_i32_16x16x64_i8 v[148:151], v[68:71], v[164:167], v[148:151]
	v_mfma_i32_16x16x64_i8 v[136:139], v[140:143], v[164:167], v[136:139]
	v_mfma_i32_16x16x64_i8 v[136:139], v[144:147], v[168:171], v[136:139]
	v_mfma_i32_16x16x64_i8 v[120:123], v[144:147], v[176:179], v[120:123]
	v_mfma_i32_16x16x64_i8 v[120:123], v[140:143], v[172:175], v[120:123]
	v_mfma_i32_16x16x64_i8 v[104:107], v[140:143], v[204:207], v[104:107]
	v_mfma_i32_16x16x64_i8 v[104:107], v[144:147], v[208:211], v[104:107]
	v_mfma_i32_16x16x64_i8 v[88:91], v[144:147], v[220:223], v[88:91]
	v_mfma_i32_16x16x64_i8 v[88:91], v[140:143], v[212:215], v[88:91]
	v_mfma_i32_16x16x64_i8 v[84:87], v[156:159], v[212:215], v[84:87]
	v_mfma_i32_16x16x64_i8 v[84:87], v[160:163], v[220:223], v[84:87]
	v_mfma_i32_16x16x64_i8 v[100:103], v[160:163], v[208:211], v[100:103]
	v_mfma_i32_16x16x64_i8 v[100:103], v[156:159], v[204:207], v[100:103]
	v_mfma_i32_16x16x64_i8 v[116:119], v[156:159], v[172:175], v[116:119]
	v_mfma_i32_16x16x64_i8 v[116:119], v[160:163], v[176:179], v[116:119]
	v_mfma_i32_16x16x64_i8 v[132:135], v[160:163], v[168:171], v[132:135]
	v_mfma_i32_16x16x64_i8 v[132:135], v[156:159], v[164:167], v[132:135]
	s_setprio 0
	s_barrier
	s_add_i32 s60, s87, s46
	s_mov_b32 m0, s60
	ds_read_b128 v[164:167], v219 offset:49152
	ds_read_b128 v[168:171], v219 offset:50176
	ds_read_b128 v[172:175], v219 offset:51200
	ds_read_b128 v[176:179], v219 offset:52224
	ds_read_b128 v[204:207], v219 offset:53248
	ds_read_b128 v[208:211], v219 offset:54272
	ds_read_b128 v[212:215], v219 offset:55296
	ds_read_b128 v[220:223], v219 offset:56320
	s_add_u32 s98, s58, 0x80
	s_addc_u32 s99, s59, 0
	global_load_lds_dwordx4 v2, s[98:99]
	s_add_i32 m0, s60, 0x2000
	s_add_u32 s58, s58, 0x80080
	s_addc_u32 s59, s59, 0
	s_add_i32 s60, s96, s46
	global_load_lds_dwordx4 v184, s[98:99]
	s_mov_b32 m0, s60
	s_nop 0
	global_load_lds_dwordx4 v2, s[58:59]
	s_add_i32 m0, s60, 0x2000
	s_nop 0
	global_load_lds_dwordx4 v184, s[58:59]
	s_cmp_eq_u32 s86, 28
	s_cbranch_scc0 .Ldefer_1843_peel
	v_lshl_add_u64 v[190:191], v[226:227], 0, s[84:85]
	s_mov_b32 m0, s28
	s_nop 0
	global_load_lds_dwordx4 v[190:191], off
	v_lshl_add_u64 v[190:191], v[228:229], 0, s[84:85]
	s_mov_b32 m0, s77
	s_nop 0
	global_load_lds_dwordx4 v[190:191], off

; #define PG8_STAGE(bufoff, gbase, voff) do { _Pragma("unroll") for (int _i = 0; _i < 2; ++_i) \
;         __builtin_amdgcn_global_load_lds((const unsigned*)((const char*)(gbase) + (voff)[_i]), (PG8_LAS unsigned*)(lds + (bufoff) + ldsw + _i * 8192), 16, 0, 0); } while (0)
; #define PG8_LDA(dst, b, h) do { _Pragma("unroll") for (int m = 0; m < 4; ++m) _Pragma("unroll") for (int k = 0; k < 2; ++k) dst[m][k] = *(const PG8_LAS bf16x8*)(lds + PG8_SA(b, h) + aoff + m * 2048 + k * 1024); } while (0)
; #define PG8_LDB(dst, b, h) do { _Pragma("unroll") for (int n = 0; n < 2; ++n) _Pragma("unroll") for (int k = 0; k < 2; ++k) dst[n][k] = *(const PG8_LAS bf16x8*)(lds + PG8_SB(b, h) + boff + n * 2048 + k * 1024); } while (0)
; #define PG8_WAIT_V(n) asm volatile("s_waitcnt vmcnt(" #n ")" ::: "memory")
; #define PG8_WAIT_L(n) asm volatile("s_waitcnt lgkmcnt(" #n ")" ::: "memory")
; #define PG8_BAR __builtin_amdgcn_s_barrier()
; #define PG8_SCHED __builtin_amdgcn_sched_barrier(0)
; template <class Epi, class Sched, bool ALIGN_EPI = false, bool SP2 = false, bool I8 = false>
; __device__ __forceinline__ void gemm_phase(PG8_LAS unsigned char* lds, const Gemm g, const Sched& S, const Epi& E) {
;     ...
;             const char* a2 = last ? nA : cA + (size_t)(t + 2) * kstep; const char* b2 = last ? nB : cB + (size_t)(t + 2) * kstep;
;             const char* a3 = a2 + kstep; const char* b3 = b2 + kstep;
;             if (last && has_next) S.a_ready(nxt);
;             if constexpr (SP2) {
;             PG8_LDB(B0, 0, 0); PG8_LDB(B1, 0, 1); PG8_SCHED; PG8_LDA(At, 0, 0); PG8_STAGE(PG8_SA(1, 1), a1 + hstep, voffA);
;             PG8_WAIT_V(8); PG8_WAIT_L(0); PG8_BAR; PG8_MMA(0, 0, At, B0); PG8_MMA(0, 1, At, B1); PG8_BAR; PG8_SCHED;
;             PG8_LDA(At, 0, 1); PG8_STAGE(PG8_SB(0, 0), b2, voffB); PG8_STAGE(PG8_SB(0, 1), b2 + hstep, voffB); PG8_STAGE(PG8_SA(0, 0), a2, voffA);
;             PG8_WAIT_V(8); PG8_WAIT_L(0); PG8_BAR; PG8_MMA(1, 0, At, B0); PG8_MMA(1, 1, At, B1); PG8_BAR; PG8_SCHED;
;             PG8_LDB(B0, 1, 0); PG8_LDB(B1, 1, 1); PG8_SCHED; PG8_LDA(At, 1, 0); PG8_STAGE(PG8_SA(0, 1), a2 + hstep, voffA);
;             PG8_WAIT_V(8); PG8_WAIT_L(0); PG8_BAR; PG8_MMA(0, 0, At, B0); PG8_MMA(0, 1, At, B1); PG8_BAR; PG8_SCHED;
.LBB0_1843:
	s_add_i32 s87, 0, 0x10000
	s_add_i32 vcc_lo, 0, 0x14000
	v_add_u32_e32 v40, s87, v217
	v_add_u32_e32 v160, vcc_lo, v217
	ds_read_b128 v[28:31], v40
	ds_read_b128 v[32:35], v40 offset:1024
	ds_read_b128 v[36:39], v40 offset:2048
	ds_read_b128 v[40:43], v40 offset:3072
	ds_read_b128 v[140:143], v160
	ds_read_b128 v[144:147], v160 offset:1024
	ds_read_b128 v[156:159], v160 offset:2048
	ds_read_b128 v[160:163], v160 offset:3072
	s_add_u32 s58, s54, 0xfff80080
	s_addc_u32 s59, s55, -1
	s_cmp_eq_u32 s86, 28
	s_cselect_b32 s61, s11, s59
	s_cselect_b32 s60, s13, s58
	s_cselect_b32 s59, s34, s49
	s_cselect_b32 s58, s35, s45
	v_lshl_add_u64 v[190:191], v[226:227], 0, s[84:85]
	s_mov_b32 m0, s28
	s_nop 0
	global_load_lds_dwordx4 v[190:191], off
	v_lshl_add_u64 v[190:191], v[228:229], 0, s[84:85]
	s_mov_b32 m0, s77
	s_nop 0
	global_load_lds_dwordx4 v[190:191], off
	s_add_i32 m0, s65, 0xc000
	ds_read_b128 v[164:167], v219
	ds_read_b128 v[168:171], v219 offset:1024
	ds_read_b128 v[172:175], v219 offset:2048
	ds_read_b128 v[176:179], v219 offset:3072
	ds_read_b128 v[204:207], v219 offset:4096
	ds_read_b128 v[208:211], v219 offset:5120
	ds_read_b128 v[212:215], v219 offset:6144
	ds_read_b128 v[220:223], v219 offset:7168
	global_load_lds_dwordx4 v186, s[54:55]
	s_add_i32 m0, s65, 0xe000
	s_nop 0
	global_load_lds_dwordx4 v188, s[54:55]
	s_waitcnt vmcnt(8)
	s_waitcnt lgkmcnt(0)
	s_barrier
	s_setprio 1
	s_waitcnt lgkmcnt(0)
	v_mfma_i32_16x16x64_i8 v[152:155], v[28:31], v[164:167], v[152:155]
	v_mfma_i32_16x16x64_i8 v[152:155], v[32:35], v[168:171], v[152:155]
	v_mfma_i32_16x16x64_i8 v[128:131], v[32:35], v[176:179], v[128:131]
	v_mfma_i32_16x16x64_i8 v[128:131], v[28:31], v[172:175], v[128:131]
	v_mfma_i32_16x16x64_i8 v[112:115], v[28:31], v[204:207], v[112:115]
	v_mfma_i32_16x16x64_i8 v[112:115], v[32:35], v[208:211], v[112:115]
	v_mfma_i32_16x16x64_i8 v[96:99], v[32:35], v[220:223], v[96:99]
	v_mfma_i32_16x16x64_i8 v[96:99], v[28:31], v[212:215], v[96:99]
	v_mfma_i32_16x16x64_i8 v[92:95], v[36:39], v[212:215], v[92:95]
	v_mfma_i32_16x16x64_i8 v[92:95], v[40:43], v[220:223], v[92:95]
	v_mfma_i32_16x16x64_i8 v[108:111], v[40:43], v[208:211], v[108:111]
	v_mfma_i32_16x16x64_i8 v[108:111], v[36:39], v[204:207], v[108:111]
	v_mfma_i32_16x16x64_i8 v[124:127], v[36:39], v[172:175], v[124:127]
	v_mfma_i32_16x16x64_i8 v[124:127], v[40:43], v[176:179], v[124:127]
	v_mfma_i32_16x16x64_i8 v[148:151], v[40:43], v[168:171], v[148:151]
	v_mfma_i32_16x16x64_i8 v[148:151], v[36:39], v[164:167], v[148:151]
	v_mfma_i32_16x16x64_i8 v[136:139], v[140:143], v[164:167], v[136:139]
	v_mfma_i32_16x16x64_i8 v[136:139], v[144:147], v[168:171], v[136:139]
	v_mfma_i32_16x16x64_i8 v[120:123], v[144:147], v[176:179], v[120:123]
	v_mfma_i32_16x16x64_i8 v[120:123], v[140:143], v[172:175], v[120:123]
	v_mfma_i32_16x16x64_i8 v[104:107], v[140:143], v[204:207], v[104:107]
	v_mfma_i32_16x16x64_i8 v[104:107], v[144:147], v[208:211], v[104:107]
	v_mfma_i32_16x16x64_i8 v[88:91], v[144:147], v[220:223], v[88:91]
	v_mfma_i32_16x16x64_i8 v[88:91], v[140:143], v[212:215], v[88:91]
	v_mfma_i32_16x16x64_i8 v[84:87], v[156:159], v[212:215], v[84:87]
	v_mfma_i32_16x16x64_i8 v[84:87], v[160:163], v[220:223], v[84:87]
	v_mfma_i32_16x16x64_i8 v[100:103], v[160:163], v[208:211], v[100:103]
	v_mfma_i32_16x16x64_i8 v[100:103], v[156:159], v[204:207], v[100:103]
	v_mfma_i32_16x16x64_i8 v[116:119], v[156:159], v[172:175], v[116:119]
	v_mfma_i32_16x16x64_i8 v[116:119], v[160:163], v[176:179], v[116:119]
	v_mfma_i32_16x16x64_i8 v[132:135], v[160:163], v[168:171], v[132:135]
	v_mfma_i32_16x16x64_i8 v[132:135], v[156:159], v[164:167], v[132:135]
	s_setprio 0
	s_barrier
	s_add_i32 s87, s87, s46
	s_mov_b32 m0, s87
	ds_read_b128 v[164:167], v219 offset:16384
	ds_read_b128 v[168:171], v219 offset:17408
	ds_read_b128 v[172:175], v219 offset:18432
	ds_read_b128 v[176:179], v219 offset:19456
	ds_read_b128 v[204:207], v219 offset:20480
	ds_read_b128 v[208:211], v219 offset:21504
	ds_read_b128 v[212:215], v219 offset:22528
	ds_read_b128 v[220:223], v219 offset:23552
	global_load_lds_dwordx4 v2, s[58:59]
	s_add_i32 m0, s87, 0x2000
	s_add_u32 s96, s58, 0x80000
	s_addc_u32 s97, s59, 0
	s_add_i32 s87, vcc_lo, s46
	global_load_lds_dwordx4 v184, s[58:59]
	s_mov_b32 m0, s87
	v_lshl_add_u64 v[228:229], s[60:61], 0, v[182:183]
	global_load_lds_dwordx4 v2, s[96:97]
	s_add_i32 m0, s87, 0x2000
	s_nop 0
	global_load_lds_dwordx4 v184, s[96:97]
	v_lshl_add_u64 v[226:227], s[60:61], 0, v[180:181]
	s_waitcnt vmcnt(6)
	s_waitcnt lgkmcnt(0)
	s_barrier
; #define PG8_STAGE(bufoff, gbase, voff) do { _Pragma("unroll") for (int _i = 0; _i < 2; ++_i) \
;         __builtin_amdgcn_global_load_lds((const unsigned*)((const char*)(gbase) + (voff)[_i]), (PG8_LAS unsigned*)(lds + (bufoff) + ldsw + _i * 8192), 16, 0, 0); } while (0)
; #define PG8_LDA(dst, b, h) do { _Pragma("unroll") for (int m = 0; m < 4; ++m) _Pragma("unroll") for (int k = 0; k < 2; ++k) dst[m][k] = *(const PG8_LAS bf16x8*)(lds + PG8_SA(b, h) + aoff + m * 2048 + k * 1024); } while (0)
; #define PG8_WAIT_V(n) asm volatile("s_waitcnt vmcnt(" #n ")" ::: "memory")
; #define PG8_WAIT_L(n) asm volatile("s_waitcnt lgkmcnt(" #n ")" ::: "memory")
; #define PG8_BAR __builtin_amdgcn_s_barrier()
; #define PG8_SCHED __builtin_amdgcn_sched_barrier(0)
; template <class Epi, class Sched, bool ALIGN_EPI = false, bool SP2 = false, bool I8 = false>
; __device__ __forceinline__ void gemm_phase(PG8_LAS unsigned char* lds, const Gemm g, const Sched& S, const Epi& E) {
;     ...
;             PG8_WAIT_V(8); PG8_WAIT_L(0); PG8_BAR; PG8_MMA(0, 0, At, B0); PG8_MMA(0, 1, At, B1); PG8_BAR; PG8_SCHED;
;             PG8_LDA(At, 1, 1); PG8_STAGE(PG8_SB(1, 0), b3, voffB); PG8_STAGE(PG8_SB(1, 1), b3 + hstep, voffB); PG8_STAGE(PG8_SA(1, 0), a3, voffA);
;             PG8_WAIT_V(8); PG8_WAIT_L(0); PG8_BAR; PG8_MMA(1, 0, At, B0); PG8_MMA(1, 1, At, B1); PG8_BAR; PG8_SCHED;
	s_setprio 1
	s_waitcnt lgkmcnt(0)
	v_mfma_i32_16x16x64_i8 v[80:83], v[28:31], v[164:167], v[80:83]
	v_mfma_i32_16x16x64_i8 v[80:83], v[32:35], v[168:171], v[80:83]
	v_mfma_i32_16x16x64_i8 v[64:67], v[32:35], v[176:179], v[64:67]
	v_mfma_i32_16x16x64_i8 v[64:67], v[28:31], v[172:175], v[64:67]
	v_mfma_i32_16x16x64_i8 v[48:51], v[28:31], v[204:207], v[48:51]
	v_mfma_i32_16x16x64_i8 v[48:51], v[32:35], v[208:211], v[48:51]
	v_mfma_i32_16x16x64_i8 v[16:19], v[32:35], v[220:223], v[16:19]
	v_mfma_i32_16x16x64_i8 v[16:19], v[28:31], v[212:215], v[16:19]
	v_mfma_i32_16x16x64_i8 v[12:15], v[36:39], v[212:215], v[12:15]
	v_mfma_i32_16x16x64_i8 v[12:15], v[40:43], v[220:223], v[12:15]
	v_mfma_i32_16x16x64_i8 v[44:47], v[40:43], v[208:211], v[44:47]
	v_mfma_i32_16x16x64_i8 v[44:47], v[36:39], v[204:207], v[44:47]
	v_mfma_i32_16x16x64_i8 v[60:63], v[36:39], v[172:175], v[60:63]
	v_mfma_i32_16x16x64_i8 v[60:63], v[40:43], v[176:179], v[60:63]
	v_mfma_i32_16x16x64_i8 v[76:79], v[40:43], v[168:171], v[76:79]
	v_mfma_i32_16x16x64_i8 v[76:79], v[36:39], v[164:167], v[76:79]
	v_mfma_i32_16x16x64_i8 v[28:31], v[140:143], v[164:167], v[72:75]
	v_mfma_i32_16x16x64_i8 v[28:31], v[144:147], v[168:171], v[28:31]
	v_mfma_i32_16x16x64_i8 v[36:39], v[144:147], v[176:179], v[56:59]
	v_mfma_i32_16x16x64_i8 v[36:39], v[140:143], v[172:175], v[36:39]
	v_mfma_i32_16x16x64_i8 v[24:27], v[140:143], v[204:207], v[24:27]
	v_mfma_i32_16x16x64_i8 v[24:27], v[144:147], v[208:211], v[24:27]
	v_mfma_i32_16x16x64_i8 v[8:11], v[144:147], v[220:223], v[8:11]
	v_mfma_i32_16x16x64_i8 v[8:11], v[140:143], v[212:215], v[8:11]
	v_mfma_i32_16x16x64_i8 v[4:7], v[156:159], v[212:215], v[4:7]
	v_mfma_i32_16x16x64_i8 v[4:7], v[160:163], v[220:223], v[4:7]
	v_mfma_i32_16x16x64_i8 v[20:23], v[160:163], v[208:211], v[20:23]
	v_mfma_i32_16x16x64_i8 v[20:23], v[156:159], v[204:207], v[20:23]
	v_mfma_i32_16x16x64_i8 v[40:43], v[156:159], v[172:175], v[52:55]
	v_mfma_i32_16x16x64_i8 v[40:43], v[160:163], v[176:179], v[40:43]
	v_mfma_i32_16x16x64_i8 v[32:35], v[160:163], v[168:171], v[68:71]
	v_mfma_i32_16x16x64_i8 v[32:35], v[156:159], v[164:167], v[32:35]
	s_setprio 0
	s_barrier
	s_mov_b32 m0, s65
	s_nop 0
	global_load_lds_dwordx4 v[226:227], off
	s_mov_b32 m0, s67
	s_nop 0
	global_load_lds_dwordx4 v[228:229], off
	s_add_i32 s87, 0, 0x18000
	s_add_i32 s96, 0, 0x1c000
	v_add_u32_e32 v72, s87, v217
	v_add_u32_e32 v160, s96, v217
	ds_read_b128 v[52:55], v72
	ds_read_b128 v[56:59], v72 offset:1024
	ds_read_b128 v[68:71], v72 offset:2048
	ds_read_b128 v[72:75], v72 offset:3072
	ds_read_b128 v[140:143], v160
	ds_read_b128 v[144:147], v160 offset:1024
	ds_read_b128 v[156:159], v160 offset:2048
	ds_read_b128 v[160:163], v160 offset:3072
	s_add_u32 s60, s60, 0x80000
	s_addc_u32 s61, s61, 0
	s_mov_b32 m0, s72
	ds_read_b128 v[164:167], v219 offset:32768
	ds_read_b128 v[168:171], v219 offset:33792
	ds_read_b128 v[172:175], v219 offset:34816
	ds_read_b128 v[176:179], v219 offset:35840
	ds_read_b128 v[204:207], v219 offset:36864
	ds_read_b128 v[208:211], v219 offset:37888
	ds_read_b128 v[212:215], v219 offset:38912
	ds_read_b128 v[220:223], v219 offset:39936
	global_load_lds_dwordx4 v180, s[60:61]
	s_mov_b32 m0, s73
	s_nop 0
	global_load_lds_dwordx4 v182, s[60:61]
	s_waitcnt vmcnt(8)
	s_waitcnt lgkmcnt(0)
	s_barrier
	s_setprio 1
	s_waitcnt lgkmcnt(0)
	v_mfma_i32_16x16x64_i8 v[152:155], v[52:55], v[164:167], v[152:155]
	v_mfma_i32_16x16x64_i8 v[152:155], v[56:59], v[168:171], v[152:155]
	v_mfma_i32_16x16x64_i8 v[128:131], v[56:59], v[176:179], v[128:131]
	v_mfma_i32_16x16x64_i8 v[128:131], v[52:55], v[172:175], v[128:131]
	v_mfma_i32_16x16x64_i8 v[112:115], v[52:55], v[204:207], v[112:115]
	v_mfma_i32_16x16x64_i8 v[112:115], v[56:59], v[208:211], v[112:115]
	v_mfma_i32_16x16x64_i8 v[96:99], v[56:59], v[220:223], v[96:99]
	v_mfma_i32_16x16x64_i8 v[96:99], v[52:55], v[212:215], v[96:99]
	v_mfma_i32_16x16x64_i8 v[92:95], v[68:71], v[212:215], v[92:95]
	v_mfma_i32_16x16x64_i8 v[92:95], v[72:75], v[220:223], v[92:95]
	v_mfma_i32_16x16x64_i8 v[108:111], v[72:75], v[208:211], v[108:111]
	v_mfma_i32_16x16x64_i8 v[108:111], v[68:71], v[204:207], v[108:111]
	v_mfma_i32_16x16x64_i8 v[124:127], v[68:71], v[172:175], v[124:127]
	v_mfma_i32_16x16x64_i8 v[124:127], v[72:75], v[176:179], v[124:127]
	v_mfma_i32_16x16x64_i8 v[148:151], v[72:75], v[168:171], v[148:151]
	v_mfma_i32_16x16x64_i8 v[148:151], v[68:71], v[164:167], v[148:151]
	v_mfma_i32_16x16x64_i8 v[136:139], v[140:143], v[164:167], v[136:139]
	v_mfma_i32_16x16x64_i8 v[136:139], v[144:147], v[168:171], v[136:139]
	v_mfma_i32_16x16x64_i8 v[120:123], v[144:147], v[176:179], v[120:123]
	v_mfma_i32_16x16x64_i8 v[120:123], v[140:143], v[172:175], v[120:123]
	v_mfma_i32_16x16x64_i8 v[104:107], v[140:143], v[204:207], v[104:107]
	v_mfma_i32_16x16x64_i8 v[104:107], v[144:147], v[208:211], v[104:107]
	v_mfma_i32_16x16x64_i8 v[88:91], v[144:147], v[220:223], v[88:91]
	v_mfma_i32_16x16x64_i8 v[88:91], v[140:143], v[212:215], v[88:91]
	v_mfma_i32_16x16x64_i8 v[84:87], v[156:159], v[212:215], v[84:87]
	v_mfma_i32_16x16x64_i8 v[84:87], v[160:163], v[220:223], v[84:87]
	v_mfma_i32_16x16x64_i8 v[100:103], v[160:163], v[208:211], v[100:103]
	v_mfma_i32_16x16x64_i8 v[100:103], v[156:159], v[204:207], v[100:103]
	v_mfma_i32_16x16x64_i8 v[116:119], v[156:159], v[172:175], v[116:119]
	v_mfma_i32_16x16x64_i8 v[116:119], v[160:163], v[176:179], v[116:119]
	v_mfma_i32_16x16x64_i8 v[132:135], v[160:163], v[168:171], v[132:135]
	v_mfma_i32_16x16x64_i8 v[132:135], v[156:159], v[164:167], v[132:135]
	s_setprio 0
	s_barrier
	s_add_i32 s60, s87, s46
	s_mov_b32 m0, s60
	ds_read_b128 v[164:167], v219 offset:49152
	ds_read_b128 v[168:171], v219 offset:50176
	ds_read_b128 v[172:175], v219 offset:51200
	ds_read_b128 v[176:179], v219 offset:52224
	ds_read_b128 v[204:207], v219 offset:53248
	ds_read_b128 v[208:211], v219 offset:54272
	ds_read_b128 v[212:215], v219 offset:55296
	ds_read_b128 v[220:223], v219 offset:56320
	s_add_u32 s98, s58, 0x80
	s_addc_u32 s99, s59, 0
	global_load_lds_dwordx4 v2, s[98:99]
	s_add_i32 m0, s60, 0x2000
	s_add_u32 s58, s58, 0x80080
	s_addc_u32 s59, s59, 0
	s_add_i32 s60, s96, s46
	global_load_lds_dwordx4 v184, s[98:99]
	s_mov_b32 m0, s60
	s_nop 0
	global_load_lds_dwordx4 v2, s[58:59]
	s_add_i32 m0, s60, 0x2000
	s_nop 0
	global_load_lds_dwordx4 v184, s[58:59]
	s_cmp_eq_u32 s86, 28
	s_cbranch_scc0 .Ldefer_1843_body
	v_lshl_add_u64 v[190:191], v[226:227], 0, s[84:85]
	s_mov_b32 m0, s28
	s_nop 0
	global_load_lds_dwordx4 v[190:191], off
	v_lshl_add_u64 v[190:191], v[228:229], 0, s[84:85]
	s_mov_b32 m0, s77
	s_nop 0
	global_load_lds_dwordx4 v[190:191], off
